# first K iteration of each GEMM tile peeled: first MFMA of every accumulator takes C=0, accumulator zeroing removed
# speedup vs baseline: 1.0289x; 1.0064x over previous
; #define PG8_STAGE(bufoff, gbase, voff) do { _Pragma("unroll") for (int _i = 0; _i < 2; ++_i) \
;         __builtin_amdgcn_global_load_lds((const unsigned*)((const char*)(gbase) + (voff)[_i]), (PG8_LAS unsigned*)(lds + (bufoff) + ldsw + _i * 8192), 16, 0, 0); } while (0)
; #define PG8_LDA(dst, b, h) do { _Pragma("unroll") for (int m = 0; m < 4; ++m) _Pragma("unroll") for (int k = 0; k < 2; ++k) dst[m][k] = *(const PG8_LAS bf16x8*)(lds + PG8_SA(b, h) + aoff + m * 2048 + k * 1024); } while (0)
; #define PG8_LDB(dst, b, h) do { _Pragma("unroll") for (int n = 0; n < 2; ++n) _Pragma("unroll") for (int k = 0; k < 2; ++k) dst[n][k] = *(const PG8_LAS bf16x8*)(lds + PG8_SB(b, h) + boff + n * 2048 + k * 1024); } while (0)
; #define PG8_MMA(ai, bj, At, Bt) do { __builtin_amdgcn_s_setprio(1); _Pragma("unroll") for (int m = 0; m < 4; ++m) _Pragma("unroll") for (int n = 0; n < 2; ++n) _Pragma("unroll") for (int k = 0; k < 2; ++k) \
;         acc[ai][bj][m][n] = __builtin_amdgcn_mfma_f32_16x16x32_bf16(Bt[n][k], At[m][k], acc[ai][bj][m][n], 0, 0, 0); __builtin_amdgcn_s_setprio(0); } while (0)
; #define PG8_WAIT_V(n) asm volatile("s_waitcnt vmcnt(" #n ")" ::: "memory")
; #define PG8_WAIT_L(n) asm volatile("s_waitcnt lgkmcnt(" #n ")" ::: "memory")
; #define PG8_BAR __builtin_amdgcn_s_barrier()
; #define PG8_SCHED __builtin_amdgcn_sched_barrier(0)
; template <class Epi, class Sched, bool ALIGN_EPI = false, bool SP2 = false>
; __device__ __forceinline__ void gemm_phase(PG8_LAS unsigned char* lds, const Gemm g, const Sched& S, const Epi& E) {
;     ...
;             PG8_LDB(B0, 0, 0); PG8_LDB(B1, 0, 1); PG8_SCHED; PG8_LDA(At, 0, 0); PG8_STAGE(PG8_SA(1, 1), a1 + hstepA, voffA);
;             PG8_WAIT_V(8); PG8_WAIT_L(0); PG8_BAR; PG8_MMA(0, 0, At, B0); PG8_MMA(0, 1, At, B1); PG8_BAR; PG8_SCHED;
;             PG8_LDA(At, 0, 1); PG8_STAGE(PG8_SB(0, 0), b2, voffB); PG8_STAGE(PG8_SB(0, 1), b2 + hstepB, voffB); PG8_STAGE(PG8_SA(0, 0), a2, voffA);
;     ...
; #pragma unroll
;         for (int a = 0; a < 2; ++a)
; #pragma unroll
;             for (int b = 0; b < 2; ++b)
; #pragma unroll
;                 for (int m = 0; m < 4; ++m)
; #pragma unroll
;                     for (int n = 0; n < 2; ++n) acc[a][b][m][n] = (f32x4){0.f, 0.f, 0.f, 0.f};
;         cur = nxt; cA = nA; cB = nB; ++ui;
.LBB0_140:
	s_ashr_i32 s59, s58, 31
	s_lshl_b64 s[60:61], s[58:59], 19
	s_add_u32 s60, s12, s60
	s_addc_u32 s61, s13, s61
	s_and_b64 s[62:63], s[2:3], exec
	s_cselect_b32 s59, s61, s71
	s_cselect_b32 s92, s60, s70
	s_ashr_i32 s57, s56, 31
	s_lshl_b64 s[62:63], s[56:57], 19
	s_add_u32 s62, s80, s62
	s_addc_u32 s63, s81, s63
	s_and_b64 s[94:95], s[2:3], exec
	s_cselect_b32 s57, s63, s73
	s_cselect_b32 s93, s62, s72
	s_add_u32 s70, s70, 0x10000
	s_addc_u32 s71, s71, 0
	s_add_u32 s72, s72, 0x10000
	s_addc_u32 s73, s73, 0
	s_mov_b32 s94, -2
	ds_read_b128 v[150:153], v143
	ds_read_b128 v[154:157], v143 offset:1024
	ds_read_b128 v[158:161], v143 offset:2048
	ds_read_b128 v[162:165], v143 offset:3072
	ds_read_b128 v[166:169], v144
	ds_read_b128 v[170:173], v144 offset:1024
	ds_read_b128 v[174:177], v144 offset:2048
	ds_read_b128 v[178:181], v144 offset:3072
	s_cmp_eq_u32 s94, 12
	s_cselect_b32 s97, s59, s71
	s_cselect_b32 s96, s92, s70
	s_cselect_b32 vcc_hi, s57, s73
	s_cselect_b32 vcc_lo, s93, s72
	s_movk_i32 s8, 0xc000
	v_lshl_add_u64 v[186:187], s[70:71], 0, v[128:129]
	s_mov_b32 s9, -1
	v_lshl_add_u64 v[220:221], v[186:187], 0, s[8:9]
	s_movk_i32 s8, 0xe000
	s_add_i32 m0, s18, 0xc000
	s_mov_b32 s9, -1
	ds_read_b128 v[182:185], v145
	ds_read_b128 v[190:193], v145 offset:1024
	ds_read_b128 v[194:197], v145 offset:2048
	ds_read_b128 v[198:201], v145 offset:3072
	ds_read_b128 v[202:205], v145 offset:4096
	ds_read_b128 v[206:209], v145 offset:5120
	ds_read_b128 v[210:213], v145 offset:6144
	ds_read_b128 v[214:217], v145 offset:7168
	global_load_lds_dwordx4 v[220:221], off
	v_lshl_add_u64 v[186:187], v[186:187], 0, s[8:9]
	s_add_i32 m0, s18, 0xe000
	s_nop 0
	global_load_lds_dwordx4 v[186:187], off
	s_waitcnt vmcnt(8)
	s_waitcnt lgkmcnt(0)
	s_barrier
	s_setprio 1
	s_waitcnt lgkmcnt(0)
	v_mfma_f32_16x16x32_bf16 v[116:119], v[150:153], v[182:185], 0
	v_mfma_f32_16x16x32_bf16 v[112:115], v[158:161], v[182:185], 0
	v_mfma_f32_16x16x32_bf16 v[108:111], v[150:153], v[194:197], 0
	v_mfma_f32_16x16x32_bf16 v[100:103], v[158:161], v[194:197], 0
	v_mfma_f32_16x16x32_bf16 v[92:95], v[150:153], v[202:205], 0
	v_mfma_f32_16x16x32_bf16 v[84:87], v[158:161], v[202:205], 0
	v_mfma_f32_16x16x32_bf16 v[76:79], v[150:153], v[210:213], 0
	v_mfma_f32_16x16x32_bf16 v[68:71], v[158:161], v[210:213], 0
	v_mfma_f32_16x16x32_bf16 v[116:119], v[154:157], v[190:193], v[116:119]
	v_mfma_f32_16x16x32_bf16 v[112:115], v[162:165], v[190:193], v[112:115]
	v_mfma_f32_16x16x32_bf16 v[108:111], v[154:157], v[198:201], v[108:111]
	v_mfma_f32_16x16x32_bf16 v[100:103], v[162:165], v[198:201], v[100:103]
	v_mfma_f32_16x16x32_bf16 v[92:95], v[154:157], v[206:209], v[92:95]
	v_mfma_f32_16x16x32_bf16 v[84:87], v[162:165], v[206:209], v[84:87]
	v_mfma_f32_16x16x32_bf16 v[76:79], v[154:157], v[214:217], v[76:79]
	v_mfma_f32_16x16x32_bf16 v[68:71], v[162:165], v[214:217], v[68:71]
	s_setprio 0
	s_setprio 1
	v_mfma_f32_16x16x32_bf16 v[124:127], v[166:169], v[182:185], 0
	v_mfma_f32_16x16x32_bf16 v[120:123], v[174:177], v[182:185], 0
	v_mfma_f32_16x16x32_bf16 v[104:107], v[166:169], v[194:197], 0
	v_mfma_f32_16x16x32_bf16 v[96:99], v[174:177], v[194:197], 0
	v_mfma_f32_16x16x32_bf16 v[88:91], v[166:169], v[202:205], 0
	v_mfma_f32_16x16x32_bf16 v[80:83], v[174:177], v[202:205], 0
	v_mfma_f32_16x16x32_bf16 v[72:75], v[166:169], v[210:213], 0
	v_mfma_f32_16x16x32_bf16 v[64:67], v[174:177], v[210:213], 0
	v_mfma_f32_16x16x32_bf16 v[124:127], v[170:173], v[190:193], v[124:127]
	v_mfma_f32_16x16x32_bf16 v[120:123], v[178:181], v[190:193], v[120:123]
	v_mfma_f32_16x16x32_bf16 v[104:107], v[170:173], v[198:201], v[104:107]
	v_mfma_f32_16x16x32_bf16 v[96:99], v[178:181], v[198:201], v[96:99]
	v_mfma_f32_16x16x32_bf16 v[88:91], v[170:173], v[206:209], v[88:91]
	v_mfma_f32_16x16x32_bf16 v[80:83], v[178:181], v[206:209], v[80:83]
	v_mfma_f32_16x16x32_bf16 v[72:75], v[170:173], v[214:217], v[72:75]
	v_mfma_f32_16x16x32_bf16 v[64:67], v[178:181], v[214:217], v[64:67]
	s_setprio 0
	s_barrier
	s_add_i32 s8, s86, s14
	v_lshl_add_u64 v[186:187], vcc, 0, v[128:129]
	s_mov_b32 m0, s8
	ds_read_b128 v[182:185], v145 offset:16384
	ds_read_b128 v[190:193], v145 offset:17408
	ds_read_b128 v[194:197], v145 offset:18432
	ds_read_b128 v[198:201], v145 offset:19456
	ds_read_b128 v[202:205], v145 offset:20480
	ds_read_b128 v[206:209], v145 offset:21504
	ds_read_b128 v[210:213], v145 offset:22528
	ds_read_b128 v[214:217], v145 offset:23552
	global_load_lds_dwordx4 v[186:187], off
	v_lshl_add_u64 v[220:221], v[186:187], 0, s[4:5]
	s_add_i32 m0, s8, 0x2000
	s_add_i32 s8, s89, s14
	global_load_lds_dwordx4 v[220:221], off
	v_lshl_add_u64 v[220:221], v[186:187], 0, s[6:7]
	s_mov_b32 m0, s8
	s_nop 0
	global_load_lds_dwordx4 v[220:221], off
	v_lshl_add_u64 v[220:221], v[186:187], 0, s[30:31]
	s_add_i32 m0, s8, 0x2000
	s_nop 0
	global_load_lds_dwordx4 v[220:221], off
	v_lshl_add_u64 v[220:221], s[96:97], 0, v[128:129]
	s_mov_b32 m0, s18
	v_lshl_add_u64 v[222:223], v[220:221], 0, s[4:5]
	global_load_lds_dwordx4 v[220:221], off
	s_mov_b32 m0, s19
	s_nop 0
	global_load_lds_dwordx4 v[222:223], off
	s_waitcnt vmcnt(8)
	s_waitcnt lgkmcnt(0)
	s_barrier
; #define PG8_STAGE(bufoff, gbase, voff) do { _Pragma("unroll") for (int _i = 0; _i < 2; ++_i) \
;         __builtin_amdgcn_global_load_lds((const unsigned*)((const char*)(gbase) + (voff)[_i]), (PG8_LAS unsigned*)(lds + (bufoff) + ldsw + _i * 8192), 16, 0, 0); } while (0)
; #define PG8_LDA(dst, b, h) do { _Pragma("unroll") for (int m = 0; m < 4; ++m) _Pragma("unroll") for (int k = 0; k < 2; ++k) dst[m][k] = *(const PG8_LAS bf16x8*)(lds + PG8_SA(b, h) + aoff + m * 2048 + k * 1024); } while (0)
; #define PG8_LDB(dst, b, h) do { _Pragma("unroll") for (int n = 0; n < 2; ++n) _Pragma("unroll") for (int k = 0; k < 2; ++k) dst[n][k] = *(const PG8_LAS bf16x8*)(lds + PG8_SB(b, h) + boff + n * 2048 + k * 1024); } while (0)
; #define PG8_MMA(ai, bj, At, Bt) do { __builtin_amdgcn_s_setprio(1); _Pragma("unroll") for (int m = 0; m < 4; ++m) _Pragma("unroll") for (int n = 0; n < 2; ++n) _Pragma("unroll") for (int k = 0; k < 2; ++k) \
;         acc[ai][bj][m][n] = __builtin_amdgcn_mfma_f32_16x16x32_bf16(Bt[n][k], At[m][k], acc[ai][bj][m][n], 0, 0, 0); __builtin_amdgcn_s_setprio(0); } while (0)
; #define PG8_WAIT_V(n) asm volatile("s_waitcnt vmcnt(" #n ")" ::: "memory")
; #define PG8_WAIT_L(n) asm volatile("s_waitcnt lgkmcnt(" #n ")" ::: "memory")
; #define PG8_BAR __builtin_amdgcn_s_barrier()
; #define PG8_SCHED __builtin_amdgcn_sched_barrier(0)
; template <class Epi, class Sched, bool ALIGN_EPI = false, bool SP2 = false>
; __device__ __forceinline__ void gemm_phase(PG8_LAS unsigned char* lds, const Gemm g, const Sched& S, const Epi& E) {
;     ...
;             PG8_WAIT_V(8); PG8_WAIT_L(0); PG8_BAR; PG8_MMA(1, 0, At, B0); PG8_MMA(1, 1, At, B1); PG8_BAR; PG8_SCHED;
;             PG8_LDB(B0, 1, 0); PG8_LDB(B1, 1, 1); PG8_SCHED; PG8_LDA(At, 1, 0); PG8_STAGE(PG8_SA(0, 1), a2 + hstepA, voffA);
;             PG8_WAIT_V(8); PG8_WAIT_L(0); PG8_BAR; PG8_MMA(0, 0, At, B0); PG8_MMA(0, 1, At, B1); PG8_BAR; PG8_SCHED;
	s_setprio 1
	s_waitcnt lgkmcnt(0)
	v_mfma_f32_16x16x32_bf16 v[60:63], v[150:153], v[182:185], 0
	v_mfma_f32_16x16x32_bf16 v[52:55], v[158:161], v[182:185], 0
	v_mfma_f32_16x16x32_bf16 v[44:47], v[150:153], v[194:197], 0
	v_mfma_f32_16x16x32_bf16 v[36:39], v[158:161], v[194:197], 0
	v_mfma_f32_16x16x32_bf16 v[28:31], v[150:153], v[202:205], 0
	v_mfma_f32_16x16x32_bf16 v[20:23], v[158:161], v[202:205], 0
	v_mfma_f32_16x16x32_bf16 v[12:15], v[150:153], v[210:213], 0
	v_mfma_f32_16x16x32_bf16 v[4:7], v[158:161], v[210:213], 0
	v_mfma_f32_16x16x32_bf16 v[60:63], v[154:157], v[190:193], v[60:63]
	v_mfma_f32_16x16x32_bf16 v[52:55], v[162:165], v[190:193], v[52:55]
	v_mfma_f32_16x16x32_bf16 v[44:47], v[154:157], v[198:201], v[44:47]
	v_mfma_f32_16x16x32_bf16 v[36:39], v[162:165], v[198:201], v[36:39]
	v_mfma_f32_16x16x32_bf16 v[28:31], v[154:157], v[206:209], v[28:31]
	v_mfma_f32_16x16x32_bf16 v[20:23], v[162:165], v[206:209], v[20:23]
	v_mfma_f32_16x16x32_bf16 v[12:15], v[154:157], v[214:217], v[12:15]
	v_mfma_f32_16x16x32_bf16 v[4:7], v[162:165], v[214:217], v[4:7]
	s_setprio 0
	s_setprio 1
	v_mfma_f32_16x16x32_bf16 v[56:59], v[166:169], v[182:185], 0
	v_mfma_f32_16x16x32_bf16 v[48:51], v[174:177], v[182:185], 0
	v_mfma_f32_16x16x32_bf16 v[40:43], v[166:169], v[194:197], 0
	v_mfma_f32_16x16x32_bf16 v[32:35], v[174:177], v[194:197], 0
	v_mfma_f32_16x16x32_bf16 v[24:27], v[166:169], v[202:205], 0
	v_mfma_f32_16x16x32_bf16 v[16:19], v[174:177], v[202:205], 0
	v_mfma_f32_16x16x32_bf16 v[8:11], v[166:169], v[210:213], 0
	v_mfma_f32_16x16x32_bf16 v[0:3], v[174:177], v[210:213], 0
	v_mfma_f32_16x16x32_bf16 v[56:59], v[170:173], v[190:193], v[56:59]
	v_mfma_f32_16x16x32_bf16 v[48:51], v[178:181], v[190:193], v[48:51]
	v_mfma_f32_16x16x32_bf16 v[40:43], v[170:173], v[198:201], v[40:43]
	v_mfma_f32_16x16x32_bf16 v[32:35], v[178:181], v[198:201], v[32:35]
	v_mfma_f32_16x16x32_bf16 v[24:27], v[170:173], v[206:209], v[24:27]
	v_mfma_f32_16x16x32_bf16 v[16:19], v[178:181], v[206:209], v[16:19]
	v_mfma_f32_16x16x32_bf16 v[8:11], v[170:173], v[214:217], v[8:11]
	v_mfma_f32_16x16x32_bf16 v[0:3], v[178:181], v[214:217], v[0:3]
	s_setprio 0
	s_barrier
	ds_read_b128 v[150:153], v146
	ds_read_b128 v[154:157], v146 offset:1024
	ds_read_b128 v[158:161], v146 offset:2048
	ds_read_b128 v[162:165], v146 offset:3072
	ds_read_b128 v[166:169], v147
	ds_read_b128 v[170:173], v147 offset:1024
	ds_read_b128 v[174:177], v147 offset:2048
	ds_read_b128 v[178:181], v147 offset:3072
	s_mov_b32 m0, s74
	v_lshl_add_u64 v[222:223], v[220:221], 0, s[6:7]
	ds_read_b128 v[182:185], v145 offset:32768
	ds_read_b128 v[190:193], v145 offset:33792
	ds_read_b128 v[194:197], v145 offset:34816
	ds_read_b128 v[198:201], v145 offset:35840
	ds_read_b128 v[202:205], v145 offset:36864
	ds_read_b128 v[206:209], v145 offset:37888
	ds_read_b128 v[210:213], v145 offset:38912
	ds_read_b128 v[214:217], v145 offset:39936
	global_load_lds_dwordx4 v[222:223], off
	v_lshl_add_u64 v[222:223], v[220:221], 0, s[30:31]
	s_mov_b32 m0, s75
	s_nop 0
	global_load_lds_dwordx4 v[222:223], off
	s_waitcnt vmcnt(8)
	s_waitcnt lgkmcnt(0)
	s_barrier
	s_setprio 1
	s_waitcnt lgkmcnt(0)
	v_mfma_f32_16x16x32_bf16 v[116:119], v[150:153], v[182:185], v[116:119]
	v_mfma_f32_16x16x32_bf16 v[112:115], v[158:161], v[182:185], v[112:115]
	v_mfma_f32_16x16x32_bf16 v[108:111], v[150:153], v[194:197], v[108:111]
	v_mfma_f32_16x16x32_bf16 v[100:103], v[158:161], v[194:197], v[100:103]
	v_mfma_f32_16x16x32_bf16 v[92:95], v[150:153], v[202:205], v[92:95]
	v_mfma_f32_16x16x32_bf16 v[84:87], v[158:161], v[202:205], v[84:87]
	v_mfma_f32_16x16x32_bf16 v[76:79], v[150:153], v[210:213], v[76:79]
	v_mfma_f32_16x16x32_bf16 v[68:71], v[158:161], v[210:213], v[68:71]
	v_mfma_f32_16x16x32_bf16 v[116:119], v[154:157], v[190:193], v[116:119]
	v_mfma_f32_16x16x32_bf16 v[112:115], v[162:165], v[190:193], v[112:115]
	v_mfma_f32_16x16x32_bf16 v[108:111], v[154:157], v[198:201], v[108:111]
	v_mfma_f32_16x16x32_bf16 v[100:103], v[162:165], v[198:201], v[100:103]
	v_mfma_f32_16x16x32_bf16 v[92:95], v[154:157], v[206:209], v[92:95]
	v_mfma_f32_16x16x32_bf16 v[84:87], v[162:165], v[206:209], v[84:87]
	v_mfma_f32_16x16x32_bf16 v[76:79], v[154:157], v[214:217], v[76:79]
	v_mfma_f32_16x16x32_bf16 v[68:71], v[162:165], v[214:217], v[68:71]
	s_setprio 0
	s_setprio 1
	v_mfma_f32_16x16x32_bf16 v[124:127], v[166:169], v[182:185], v[124:127]
	v_mfma_f32_16x16x32_bf16 v[120:123], v[174:177], v[182:185], v[120:123]
	v_mfma_f32_16x16x32_bf16 v[104:107], v[166:169], v[194:197], v[104:107]
	v_mfma_f32_16x16x32_bf16 v[96:99], v[174:177], v[194:197], v[96:99]
	v_mfma_f32_16x16x32_bf16 v[88:91], v[166:169], v[202:205], v[88:91]
	v_mfma_f32_16x16x32_bf16 v[80:83], v[174:177], v[202:205], v[80:83]
	v_mfma_f32_16x16x32_bf16 v[72:75], v[166:169], v[210:213], v[72:75]
	v_mfma_f32_16x16x32_bf16 v[64:67], v[174:177], v[210:213], v[64:67]
	v_mfma_f32_16x16x32_bf16 v[124:127], v[170:173], v[190:193], v[124:127]
	v_mfma_f32_16x16x32_bf16 v[120:123], v[178:181], v[190:193], v[120:123]
	v_mfma_f32_16x16x32_bf16 v[104:107], v[170:173], v[198:201], v[104:107]
	v_mfma_f32_16x16x32_bf16 v[96:99], v[178:181], v[198:201], v[96:99]
	v_mfma_f32_16x16x32_bf16 v[88:91], v[170:173], v[206:209], v[88:91]
	v_mfma_f32_16x16x32_bf16 v[80:83], v[178:181], v[206:209], v[80:83]
	v_mfma_f32_16x16x32_bf16 v[72:75], v[170:173], v[214:217], v[72:75]
	v_mfma_f32_16x16x32_bf16 v[64:67], v[178:181], v[214:217], v[64:67]
	s_setprio 0
	s_barrier
; #define PG8_STAGE(bufoff, gbase, voff) do { _Pragma("unroll") for (int _i = 0; _i < 2; ++_i) \
;         __builtin_amdgcn_global_load_lds((const unsigned*)((const char*)(gbase) + (voff)[_i]), (PG8_LAS unsigned*)(lds + (bufoff) + ldsw + _i * 8192), 16, 0, 0); } while (0)
; #define PG8_LDA(dst, b, h) do { _Pragma("unroll") for (int m = 0; m < 4; ++m) _Pragma("unroll") for (int k = 0; k < 2; ++k) dst[m][k] = *(const PG8_LAS bf16x8*)(lds + PG8_SA(b, h) + aoff + m * 2048 + k * 1024); } while (0)
; #define PG8_MMA(ai, bj, At, Bt) do { __builtin_amdgcn_s_setprio(1); _Pragma("unroll") for (int m = 0; m < 4; ++m) _Pragma("unroll") for (int n = 0; n < 2; ++n) _Pragma("unroll") for (int k = 0; k < 2; ++k) \
;         acc[ai][bj][m][n] = __builtin_amdgcn_mfma_f32_16x16x32_bf16(Bt[n][k], At[m][k], acc[ai][bj][m][n], 0, 0, 0); __builtin_amdgcn_s_setprio(0); } while (0)
; #define PG8_WAIT_V(n) asm volatile("s_waitcnt vmcnt(" #n ")" ::: "memory")
; #define PG8_WAIT_L(n) asm volatile("s_waitcnt lgkmcnt(" #n ")" ::: "memory")
; #define PG8_BAR __builtin_amdgcn_s_barrier()
; #define PG8_SCHED __builtin_amdgcn_sched_barrier(0)
; template <class Epi, class Sched, bool ALIGN_EPI = false, bool SP2 = false>
; __device__ __forceinline__ void gemm_phase(PG8_LAS unsigned char* lds, const Gemm g, const Sched& S, const Epi& E) {
;     ...
;             PG8_LDA(At, 1, 1); PG8_STAGE(PG8_SB(1, 0), b3, voffB); PG8_STAGE(PG8_SB(1, 1), b3 + hstepB, voffB); PG8_STAGE(PG8_SA(1, 0), a3, voffA);
;             PG8_WAIT_V(8); PG8_WAIT_L(0); PG8_BAR; PG8_MMA(1, 0, At, B0); PG8_MMA(1, 1, At, B1); PG8_BAR; PG8_SCHED;
	s_add_i32 s8, s90, s14
	v_lshl_add_u64 v[222:223], v[186:187], 0, s[34:35]
	s_mov_b32 m0, s8
	ds_read_b128 v[182:185], v145 offset:49152
	ds_read_b128 v[190:193], v145 offset:50176
	ds_read_b128 v[194:197], v145 offset:51200
	ds_read_b128 v[198:201], v145 offset:52224
	ds_read_b128 v[202:205], v145 offset:53248
	ds_read_b128 v[206:209], v145 offset:54272
	ds_read_b128 v[210:213], v145 offset:55296
	ds_read_b128 v[214:217], v145 offset:56320
	global_load_lds_dwordx4 v[222:223], off
	v_lshl_add_u64 v[222:223], v[186:187], 0, s[36:37]
	s_add_i32 m0, s8, 0x2000
	s_add_i32 s8, s91, s14
	global_load_lds_dwordx4 v[222:223], off
	v_lshl_add_u64 v[222:223], v[186:187], 0, s[38:39]
	s_mov_b32 m0, s8
	v_lshl_add_u64 v[186:187], v[186:187], 0, s[40:41]
	global_load_lds_dwordx4 v[222:223], off
	s_add_i32 m0, s8, 0x2000
	s_nop 0
	global_load_lds_dwordx4 v[186:187], off
	v_lshl_add_u64 v[186:187], v[220:221], 0, s[34:35]
	s_mov_b32 m0, s76
	s_nop 0
	global_load_lds_dwordx4 v[186:187], off
	v_lshl_add_u64 v[186:187], v[220:221], 0, s[36:37]
	s_mov_b32 m0, s77
	s_nop 0
	global_load_lds_dwordx4 v[186:187], off
	s_waitcnt vmcnt(8)
	s_waitcnt lgkmcnt(0)
	s_barrier
	s_setprio 1
	s_waitcnt lgkmcnt(0)
	v_mfma_f32_16x16x32_bf16 v[60:63], v[150:153], v[182:185], v[60:63]
	v_mfma_f32_16x16x32_bf16 v[52:55], v[158:161], v[182:185], v[52:55]
	v_mfma_f32_16x16x32_bf16 v[44:47], v[150:153], v[194:197], v[44:47]
	v_mfma_f32_16x16x32_bf16 v[36:39], v[158:161], v[194:197], v[36:39]
	v_mfma_f32_16x16x32_bf16 v[28:31], v[150:153], v[202:205], v[28:31]
	v_mfma_f32_16x16x32_bf16 v[20:23], v[158:161], v[202:205], v[20:23]
	v_mfma_f32_16x16x32_bf16 v[12:15], v[150:153], v[210:213], v[12:15]
	v_mfma_f32_16x16x32_bf16 v[4:7], v[158:161], v[210:213], v[4:7]
	v_mfma_f32_16x16x32_bf16 v[60:63], v[154:157], v[190:193], v[60:63]
	v_mfma_f32_16x16x32_bf16 v[52:55], v[162:165], v[190:193], v[52:55]
	v_mfma_f32_16x16x32_bf16 v[44:47], v[154:157], v[198:201], v[44:47]
	v_mfma_f32_16x16x32_bf16 v[36:39], v[162:165], v[198:201], v[36:39]
	v_mfma_f32_16x16x32_bf16 v[28:31], v[154:157], v[206:209], v[28:31]
	v_mfma_f32_16x16x32_bf16 v[20:23], v[162:165], v[206:209], v[20:23]
	v_mfma_f32_16x16x32_bf16 v[12:15], v[154:157], v[214:217], v[12:15]
	v_mfma_f32_16x16x32_bf16 v[4:7], v[162:165], v[214:217], v[4:7]
	s_setprio 0
	s_setprio 1
	v_mfma_f32_16x16x32_bf16 v[56:59], v[166:169], v[182:185], v[56:59]
	v_mfma_f32_16x16x32_bf16 v[48:51], v[174:177], v[182:185], v[48:51]
	v_mfma_f32_16x16x32_bf16 v[40:43], v[166:169], v[194:197], v[40:43]
	v_mfma_f32_16x16x32_bf16 v[32:35], v[174:177], v[194:197], v[32:35]
	v_mfma_f32_16x16x32_bf16 v[24:27], v[166:169], v[202:205], v[24:27]
	v_mfma_f32_16x16x32_bf16 v[16:19], v[174:177], v[202:205], v[16:19]
	v_mfma_f32_16x16x32_bf16 v[8:11], v[166:169], v[210:213], v[8:11]
	v_mfma_f32_16x16x32_bf16 v[0:3], v[174:177], v[210:213], v[0:3]
	v_mfma_f32_16x16x32_bf16 v[56:59], v[170:173], v[190:193], v[56:59]
	v_mfma_f32_16x16x32_bf16 v[48:51], v[178:181], v[190:193], v[48:51]
	v_mfma_f32_16x16x32_bf16 v[40:43], v[170:173], v[198:201], v[40:43]
	v_mfma_f32_16x16x32_bf16 v[32:35], v[178:181], v[198:201], v[32:35]
	v_mfma_f32_16x16x32_bf16 v[24:27], v[170:173], v[206:209], v[24:27]
	v_mfma_f32_16x16x32_bf16 v[16:19], v[178:181], v[206:209], v[16:19]
	v_mfma_f32_16x16x32_bf16 v[8:11], v[170:173], v[214:217], v[8:11]
	v_mfma_f32_16x16x32_bf16 v[0:3], v[178:181], v[214:217], v[0:3]
	s_setprio 0
	s_barrier
	s_add_i32 s94, s94, 2
	s_add_u32 s70, s70, 0x10000
	s_addc_u32 s71, s71, 0
	s_add_u32 s72, s72, 0x10000
	s_addc_u32 s73, s73, 0
	s_cmp_gt_u32 s94, 13

; #define PG8_STAGE(bufoff, gbase, voff) do { _Pragma("unroll") for (int _i = 0; _i < 2; ++_i) \
;         __builtin_amdgcn_global_load_lds((const unsigned*)((const char*)(gbase) + (voff)[_i]), (PG8_LAS unsigned*)(lds + (bufoff) + ldsw + _i * 8192), 16, 0, 0); } while (0)
; #define PG8_LDA(dst, b, h) do { _Pragma("unroll") for (int m = 0; m < 4; ++m) _Pragma("unroll") for (int k = 0; k < 2; ++k) dst[m][k] = *(const PG8_LAS bf16x8*)(lds + PG8_SA(b, h) + aoff + m * 2048 + k * 1024); } while (0)
; #define PG8_LDB(dst, b, h) do { _Pragma("unroll") for (int n = 0; n < 2; ++n) _Pragma("unroll") for (int k = 0; k < 2; ++k) dst[n][k] = *(const PG8_LAS bf16x8*)(lds + PG8_SB(b, h) + boff + n * 2048 + k * 1024); } while (0)
; #define PG8_MMA(ai, bj, At, Bt) do { __builtin_amdgcn_s_setprio(1); _Pragma("unroll") for (int m = 0; m < 4; ++m) _Pragma("unroll") for (int n = 0; n < 2; ++n) _Pragma("unroll") for (int k = 0; k < 2; ++k) \
;         acc[ai][bj][m][n] = __builtin_amdgcn_mfma_f32_16x16x32_bf16(Bt[n][k], At[m][k], acc[ai][bj][m][n], 0, 0, 0); __builtin_amdgcn_s_setprio(0); } while (0)
; #define PG8_WAIT_V(n) asm volatile("s_waitcnt vmcnt(" #n ")" ::: "memory")
; #define PG8_WAIT_L(n) asm volatile("s_waitcnt lgkmcnt(" #n ")" ::: "memory")
; #define PG8_BAR __builtin_amdgcn_s_barrier()
; #define PG8_SCHED __builtin_amdgcn_sched_barrier(0)
; template <class Epi, class Sched, bool ALIGN_EPI = false, bool SP2 = false>
; __device__ __forceinline__ void gemm_phase(PG8_LAS unsigned char* lds, const Gemm g, const Sched& S, const Epi& E) {
;     ...
;             PG8_LDB(B0, 0, 0); PG8_LDB(B1, 0, 1); PG8_SCHED; PG8_LDA(At, 0, 0); PG8_STAGE(PG8_SA(1, 1), a1 + hstepA, voffA);
;             PG8_WAIT_V(8); PG8_WAIT_L(0); PG8_BAR; PG8_MMA(0, 0, At, B0); PG8_MMA(0, 1, At, B1); PG8_BAR; PG8_SCHED;
;             PG8_LDA(At, 0, 1); PG8_STAGE(PG8_SB(0, 0), b2, voffB); PG8_STAGE(PG8_SB(0, 1), b2 + hstepB, voffB); PG8_STAGE(PG8_SA(0, 0), a2, voffA);
;     ...
; #pragma unroll
;         for (int a = 0; a < 2; ++a)
; #pragma unroll
;             for (int b = 0; b < 2; ++b)
; #pragma unroll
;                 for (int m = 0; m < 4; ++m)
; #pragma unroll
;                     for (int n = 0; n < 2; ++n) acc[a][b][m][n] = (f32x4){0.f, 0.f, 0.f, 0.f};
;         cur = nxt; cA = nA; cB = nB; ++ui;
.LBB0_225:
	s_add_u32 s68, s68, 0x10000
	s_addc_u32 s69, s69, 0
	s_add_u32 s70, s70, 0x10000
	s_addc_u32 s71, s71, 0
	s_mov_b32 s73, -2
	s_waitcnt lgkmcnt(0)
	ds_read_b128 v[112:115], v210
	ds_read_b128 v[124:127], v210 offset:1024
	ds_read_b128 v[136:139], v210 offset:2048
	ds_read_b128 v[140:143], v210 offset:3072
	ds_read_b128 v[144:147], v211
	ds_read_b128 v[148:151], v211 offset:1024
	ds_read_b128 v[152:155], v211 offset:2048
	ds_read_b128 v[156:159], v211 offset:3072
	s_cmp_eq_u32 s73, 40
	s_cselect_b32 s9, s1, s69
	s_cselect_b32 s8, s0, s68
	s_cselect_b32 s75, s63, s71
	s_cselect_b32 s74, s62, s70
	v_lshl_add_u64 v[208:209], s[68:69], 0, v[184:185]
	v_lshl_add_u64 v[216:217], v[208:209], 0, s[96:97]
	s_add_i32 m0, s15, 0xc000
	ds_read_b128 v[160:163], v212
	ds_read_b128 v[164:167], v212 offset:1024
	ds_read_b128 v[168:171], v212 offset:2048
	ds_read_b128 v[172:175], v212 offset:3072
	ds_read_b128 v[176:179], v212 offset:4096
	ds_read_b128 v[180:183], v212 offset:5120
	ds_read_b128 v[220:223], v212 offset:6144
	ds_read_b128 v[224:227], v212 offset:7168
	global_load_lds_dwordx4 v[216:217], off
	v_lshl_add_u64 v[208:209], v[208:209], 0, s[60:61]
	s_add_i32 m0, s15, 0xe000
	s_nop 0
	global_load_lds_dwordx4 v[208:209], off
	s_waitcnt vmcnt(8)
	s_waitcnt lgkmcnt(0)
	s_barrier
	s_setprio 1
	s_waitcnt lgkmcnt(0)
	v_mfma_f32_16x16x32_bf16 v[132:135], v[112:115], v[160:163], 0
	v_mfma_f32_16x16x32_bf16 v[128:131], v[136:139], v[160:163], 0
	v_mfma_f32_16x16x32_bf16 v[108:111], v[112:115], v[168:171], 0
	v_mfma_f32_16x16x32_bf16 v[104:107], v[136:139], v[168:171], 0
	v_mfma_f32_16x16x32_bf16 v[92:95], v[112:115], v[176:179], 0
	v_mfma_f32_16x16x32_bf16 v[88:91], v[136:139], v[176:179], 0
	v_mfma_f32_16x16x32_bf16 v[76:79], v[112:115], v[220:223], 0
	v_mfma_f32_16x16x32_bf16 v[72:75], v[136:139], v[220:223], 0
	v_mfma_f32_16x16x32_bf16 v[132:135], v[124:127], v[164:167], v[132:135]
	v_mfma_f32_16x16x32_bf16 v[128:131], v[140:143], v[164:167], v[128:131]
	v_mfma_f32_16x16x32_bf16 v[108:111], v[124:127], v[172:175], v[108:111]
	v_mfma_f32_16x16x32_bf16 v[104:107], v[140:143], v[172:175], v[104:107]
	v_mfma_f32_16x16x32_bf16 v[92:95], v[124:127], v[180:183], v[92:95]
	v_mfma_f32_16x16x32_bf16 v[88:91], v[140:143], v[180:183], v[88:91]
	v_mfma_f32_16x16x32_bf16 v[76:79], v[124:127], v[224:227], v[76:79]
	v_mfma_f32_16x16x32_bf16 v[72:75], v[140:143], v[224:227], v[72:75]
	s_setprio 0
	s_setprio 1
	v_mfma_f32_16x16x32_bf16 v[120:123], v[144:147], v[160:163], 0
	v_mfma_f32_16x16x32_bf16 v[116:119], v[152:155], v[160:163], 0
	v_mfma_f32_16x16x32_bf16 v[100:103], v[144:147], v[168:171], 0
	v_mfma_f32_16x16x32_bf16 v[96:99], v[152:155], v[168:171], 0
	v_mfma_f32_16x16x32_bf16 v[84:87], v[144:147], v[176:179], 0
	v_mfma_f32_16x16x32_bf16 v[80:83], v[152:155], v[176:179], 0
	v_mfma_f32_16x16x32_bf16 v[68:71], v[144:147], v[220:223], 0
	v_mfma_f32_16x16x32_bf16 v[64:67], v[152:155], v[220:223], 0
	v_mfma_f32_16x16x32_bf16 v[120:123], v[148:151], v[164:167], v[120:123]
	v_mfma_f32_16x16x32_bf16 v[116:119], v[156:159], v[164:167], v[116:119]
	v_mfma_f32_16x16x32_bf16 v[100:103], v[148:151], v[172:175], v[100:103]
	v_mfma_f32_16x16x32_bf16 v[96:99], v[156:159], v[172:175], v[96:99]
	v_mfma_f32_16x16x32_bf16 v[84:87], v[148:151], v[180:183], v[84:87]
	v_mfma_f32_16x16x32_bf16 v[80:83], v[156:159], v[180:183], v[80:83]
	v_mfma_f32_16x16x32_bf16 v[68:71], v[148:151], v[224:227], v[68:71]
	v_mfma_f32_16x16x32_bf16 v[64:67], v[156:159], v[224:227], v[64:67]
	s_setprio 0
	s_barrier
	s_add_i32 s33, s89, s14
	v_lshl_add_u64 v[208:209], s[74:75], 0, v[184:185]
	s_mov_b32 m0, s33
	ds_read_b128 v[160:163], v212 offset:16384
	ds_read_b128 v[164:167], v212 offset:17408
	ds_read_b128 v[168:171], v212 offset:18432
	ds_read_b128 v[172:175], v212 offset:19456
	ds_read_b128 v[176:179], v212 offset:20480
	ds_read_b128 v[180:183], v212 offset:21504
	ds_read_b128 v[220:223], v212 offset:22528
	ds_read_b128 v[224:227], v212 offset:23552
	global_load_lds_dwordx4 v[208:209], off
	v_lshl_add_u64 v[216:217], v[208:209], 0, s[30:31]
	s_add_i32 m0, s33, 0x2000
	s_add_i32 s33, s90, s14
	global_load_lds_dwordx4 v[216:217], off
	v_lshl_add_u64 v[216:217], v[208:209], 0, s[34:35]
	s_mov_b32 m0, s33
	s_nop 0
	global_load_lds_dwordx4 v[216:217], off
	v_lshl_add_u64 v[216:217], v[208:209], 0, s[36:37]
	s_add_i32 m0, s33, 0x2000
	s_nop 0
	global_load_lds_dwordx4 v[216:217], off
	v_lshl_add_u64 v[216:217], s[8:9], 0, v[184:185]
	s_mov_b32 m0, s15
	v_lshl_add_u64 v[228:229], v[216:217], 0, s[30:31]
	global_load_lds_dwordx4 v[216:217], off
	s_mov_b32 m0, s17
	s_nop 0
	global_load_lds_dwordx4 v[228:229], off
	s_waitcnt vmcnt(8)
	s_waitcnt lgkmcnt(0)
	s_barrier
; #define PG8_STAGE(bufoff, gbase, voff) do { _Pragma("unroll") for (int _i = 0; _i < 2; ++_i) \
;         __builtin_amdgcn_global_load_lds((const unsigned*)((const char*)(gbase) + (voff)[_i]), (PG8_LAS unsigned*)(lds + (bufoff) + ldsw + _i * 8192), 16, 0, 0); } while (0)
; #define PG8_LDA(dst, b, h) do { _Pragma("unroll") for (int m = 0; m < 4; ++m) _Pragma("unroll") for (int k = 0; k < 2; ++k) dst[m][k] = *(const PG8_LAS bf16x8*)(lds + PG8_SA(b, h) + aoff + m * 2048 + k * 1024); } while (0)
; #define PG8_LDB(dst, b, h) do { _Pragma("unroll") for (int n = 0; n < 2; ++n) _Pragma("unroll") for (int k = 0; k < 2; ++k) dst[n][k] = *(const PG8_LAS bf16x8*)(lds + PG8_SB(b, h) + boff + n * 2048 + k * 1024); } while (0)
; #define PG8_MMA(ai, bj, At, Bt) do { __builtin_amdgcn_s_setprio(1); _Pragma("unroll") for (int m = 0; m < 4; ++m) _Pragma("unroll") for (int n = 0; n < 2; ++n) _Pragma("unroll") for (int k = 0; k < 2; ++k) \
;         acc[ai][bj][m][n] = __builtin_amdgcn_mfma_f32_16x16x32_bf16(Bt[n][k], At[m][k], acc[ai][bj][m][n], 0, 0, 0); __builtin_amdgcn_s_setprio(0); } while (0)
; #define PG8_WAIT_V(n) asm volatile("s_waitcnt vmcnt(" #n ")" ::: "memory")
; #define PG8_WAIT_L(n) asm volatile("s_waitcnt lgkmcnt(" #n ")" ::: "memory")
; #define PG8_BAR __builtin_amdgcn_s_barrier()
; #define PG8_SCHED __builtin_amdgcn_sched_barrier(0)
; template <class Epi, class Sched, bool ALIGN_EPI = false, bool SP2 = false>
; __device__ __forceinline__ void gemm_phase(PG8_LAS unsigned char* lds, const Gemm g, const Sched& S, const Epi& E) {
;     ...
;             PG8_WAIT_V(8); PG8_WAIT_L(0); PG8_BAR; PG8_MMA(1, 0, At, B0); PG8_MMA(1, 1, At, B1); PG8_BAR; PG8_SCHED;
;             PG8_LDB(B0, 1, 0); PG8_LDB(B1, 1, 1); PG8_SCHED; PG8_LDA(At, 1, 0); PG8_STAGE(PG8_SA(0, 1), a2 + hstepA, voffA);
;             PG8_WAIT_V(8); PG8_WAIT_L(0); PG8_BAR; PG8_MMA(0, 0, At, B0); PG8_MMA(0, 1, At, B1); PG8_BAR; PG8_SCHED;
	s_setprio 1
	s_waitcnt lgkmcnt(0)
	v_mfma_f32_16x16x32_bf16 v[60:63], v[112:115], v[160:163], 0
	v_mfma_f32_16x16x32_bf16 v[56:59], v[136:139], v[160:163], 0
	v_mfma_f32_16x16x32_bf16 v[44:47], v[112:115], v[168:171], 0
	v_mfma_f32_16x16x32_bf16 v[40:43], v[136:139], v[168:171], 0
	v_mfma_f32_16x16x32_bf16 v[28:31], v[112:115], v[176:179], 0
	v_mfma_f32_16x16x32_bf16 v[24:27], v[136:139], v[176:179], 0
	v_mfma_f32_16x16x32_bf16 v[12:15], v[112:115], v[220:223], 0
	v_mfma_f32_16x16x32_bf16 v[8:11], v[136:139], v[220:223], 0
	v_mfma_f32_16x16x32_bf16 v[60:63], v[124:127], v[164:167], v[60:63]
	v_mfma_f32_16x16x32_bf16 v[56:59], v[140:143], v[164:167], v[56:59]
	v_mfma_f32_16x16x32_bf16 v[44:47], v[124:127], v[172:175], v[44:47]
	v_mfma_f32_16x16x32_bf16 v[40:43], v[140:143], v[172:175], v[40:43]
	v_mfma_f32_16x16x32_bf16 v[28:31], v[124:127], v[180:183], v[28:31]
	v_mfma_f32_16x16x32_bf16 v[24:27], v[140:143], v[180:183], v[24:27]
	v_mfma_f32_16x16x32_bf16 v[12:15], v[124:127], v[224:227], v[12:15]
	v_mfma_f32_16x16x32_bf16 v[8:11], v[140:143], v[224:227], v[8:11]
	s_setprio 0
	s_setprio 1
	v_mfma_f32_16x16x32_bf16 v[52:55], v[144:147], v[160:163], 0
	v_mfma_f32_16x16x32_bf16 v[48:51], v[152:155], v[160:163], 0
	v_mfma_f32_16x16x32_bf16 v[36:39], v[144:147], v[168:171], 0
	v_mfma_f32_16x16x32_bf16 v[32:35], v[152:155], v[168:171], 0
	v_mfma_f32_16x16x32_bf16 v[20:23], v[144:147], v[176:179], 0
	v_mfma_f32_16x16x32_bf16 v[16:19], v[152:155], v[176:179], 0
	v_mfma_f32_16x16x32_bf16 v[4:7], v[144:147], v[220:223], 0
	v_mfma_f32_16x16x32_bf16 v[0:3], v[152:155], v[220:223], 0
	v_mfma_f32_16x16x32_bf16 v[52:55], v[148:151], v[164:167], v[52:55]
	v_mfma_f32_16x16x32_bf16 v[48:51], v[156:159], v[164:167], v[48:51]
	v_mfma_f32_16x16x32_bf16 v[36:39], v[148:151], v[172:175], v[36:39]
	v_mfma_f32_16x16x32_bf16 v[32:35], v[156:159], v[172:175], v[32:35]
	v_mfma_f32_16x16x32_bf16 v[20:23], v[148:151], v[180:183], v[20:23]
	v_mfma_f32_16x16x32_bf16 v[16:19], v[156:159], v[180:183], v[16:19]
	v_mfma_f32_16x16x32_bf16 v[4:7], v[148:151], v[224:227], v[4:7]
	v_mfma_f32_16x16x32_bf16 v[0:3], v[156:159], v[224:227], v[0:3]
	s_setprio 0
	s_barrier
	ds_read_b128 v[112:115], v213
	ds_read_b128 v[124:127], v213 offset:1024
	ds_read_b128 v[136:139], v213 offset:2048
	ds_read_b128 v[140:143], v213 offset:3072
	ds_read_b128 v[144:147], v214
	ds_read_b128 v[148:151], v214 offset:1024
	ds_read_b128 v[152:155], v214 offset:2048
	ds_read_b128 v[156:159], v214 offset:3072
	s_mov_b32 m0, s18
	v_lshl_add_u64 v[228:229], v[216:217], 0, s[34:35]
	ds_read_b128 v[160:163], v212 offset:32768
	ds_read_b128 v[164:167], v212 offset:33792
	ds_read_b128 v[168:171], v212 offset:34816
	ds_read_b128 v[172:175], v212 offset:35840
	ds_read_b128 v[176:179], v212 offset:36864
	ds_read_b128 v[180:183], v212 offset:37888
	ds_read_b128 v[220:223], v212 offset:38912
	ds_read_b128 v[224:227], v212 offset:39936
	global_load_lds_dwordx4 v[228:229], off
	v_lshl_add_u64 v[228:229], v[216:217], 0, s[36:37]
	s_mov_b32 m0, s19
	s_nop 0
	global_load_lds_dwordx4 v[228:229], off
	s_waitcnt vmcnt(8)
	s_waitcnt lgkmcnt(0)
	s_barrier
	s_setprio 1
	s_waitcnt lgkmcnt(0)
	v_mfma_f32_16x16x32_bf16 v[132:135], v[112:115], v[160:163], v[132:135]
	v_mfma_f32_16x16x32_bf16 v[128:131], v[136:139], v[160:163], v[128:131]
	v_mfma_f32_16x16x32_bf16 v[108:111], v[112:115], v[168:171], v[108:111]
	v_mfma_f32_16x16x32_bf16 v[104:107], v[136:139], v[168:171], v[104:107]
	v_mfma_f32_16x16x32_bf16 v[92:95], v[112:115], v[176:179], v[92:95]
	v_mfma_f32_16x16x32_bf16 v[88:91], v[136:139], v[176:179], v[88:91]
	v_mfma_f32_16x16x32_bf16 v[76:79], v[112:115], v[220:223], v[76:79]
	v_mfma_f32_16x16x32_bf16 v[72:75], v[136:139], v[220:223], v[72:75]
	v_mfma_f32_16x16x32_bf16 v[132:135], v[124:127], v[164:167], v[132:135]
	v_mfma_f32_16x16x32_bf16 v[128:131], v[140:143], v[164:167], v[128:131]
	v_mfma_f32_16x16x32_bf16 v[108:111], v[124:127], v[172:175], v[108:111]
	v_mfma_f32_16x16x32_bf16 v[104:107], v[140:143], v[172:175], v[104:107]
	v_mfma_f32_16x16x32_bf16 v[92:95], v[124:127], v[180:183], v[92:95]
	v_mfma_f32_16x16x32_bf16 v[88:91], v[140:143], v[180:183], v[88:91]
	v_mfma_f32_16x16x32_bf16 v[76:79], v[124:127], v[224:227], v[76:79]
	v_mfma_f32_16x16x32_bf16 v[72:75], v[140:143], v[224:227], v[72:75]
	s_setprio 0
	s_setprio 1
	v_mfma_f32_16x16x32_bf16 v[120:123], v[144:147], v[160:163], v[120:123]
	v_mfma_f32_16x16x32_bf16 v[116:119], v[152:155], v[160:163], v[116:119]
	v_mfma_f32_16x16x32_bf16 v[100:103], v[144:147], v[168:171], v[100:103]
	v_mfma_f32_16x16x32_bf16 v[96:99], v[152:155], v[168:171], v[96:99]
	v_mfma_f32_16x16x32_bf16 v[84:87], v[144:147], v[176:179], v[84:87]
	v_mfma_f32_16x16x32_bf16 v[80:83], v[152:155], v[176:179], v[80:83]
	v_mfma_f32_16x16x32_bf16 v[68:71], v[144:147], v[220:223], v[68:71]
	v_mfma_f32_16x16x32_bf16 v[64:67], v[152:155], v[220:223], v[64:67]
	v_mfma_f32_16x16x32_bf16 v[120:123], v[148:151], v[164:167], v[120:123]
	v_mfma_f32_16x16x32_bf16 v[116:119], v[156:159], v[164:167], v[116:119]
	v_mfma_f32_16x16x32_bf16 v[100:103], v[148:151], v[172:175], v[100:103]
	v_mfma_f32_16x16x32_bf16 v[96:99], v[156:159], v[172:175], v[96:99]
	v_mfma_f32_16x16x32_bf16 v[84:87], v[148:151], v[180:183], v[84:87]
	v_mfma_f32_16x16x32_bf16 v[80:83], v[156:159], v[180:183], v[80:83]
	v_mfma_f32_16x16x32_bf16 v[68:71], v[148:151], v[224:227], v[68:71]
	v_mfma_f32_16x16x32_bf16 v[64:67], v[156:159], v[224:227], v[64:67]
	s_setprio 0
	s_barrier
; #define PG8_STAGE(bufoff, gbase, voff) do { _Pragma("unroll") for (int _i = 0; _i < 2; ++_i) \
;         __builtin_amdgcn_global_load_lds((const unsigned*)((const char*)(gbase) + (voff)[_i]), (PG8_LAS unsigned*)(lds + (bufoff) + ldsw + _i * 8192), 16, 0, 0); } while (0)
; #define PG8_LDA(dst, b, h) do { _Pragma("unroll") for (int m = 0; m < 4; ++m) _Pragma("unroll") for (int k = 0; k < 2; ++k) dst[m][k] = *(const PG8_LAS bf16x8*)(lds + PG8_SA(b, h) + aoff + m * 2048 + k * 1024); } while (0)
; #define PG8_MMA(ai, bj, At, Bt) do { __builtin_amdgcn_s_setprio(1); _Pragma("unroll") for (int m = 0; m < 4; ++m) _Pragma("unroll") for (int n = 0; n < 2; ++n) _Pragma("unroll") for (int k = 0; k < 2; ++k) \
;         acc[ai][bj][m][n] = __builtin_amdgcn_mfma_f32_16x16x32_bf16(Bt[n][k], At[m][k], acc[ai][bj][m][n], 0, 0, 0); __builtin_amdgcn_s_setprio(0); } while (0)
; #define PG8_WAIT_V(n) asm volatile("s_waitcnt vmcnt(" #n ")" ::: "memory")
; #define PG8_WAIT_L(n) asm volatile("s_waitcnt lgkmcnt(" #n ")" ::: "memory")
; #define PG8_BAR __builtin_amdgcn_s_barrier()
; #define PG8_SCHED __builtin_amdgcn_sched_barrier(0)
; template <class Epi, class Sched, bool ALIGN_EPI = false, bool SP2 = false>
; __device__ __forceinline__ void gemm_phase(PG8_LAS unsigned char* lds, const Gemm g, const Sched& S, const Epi& E) {
;     ...
;             PG8_LDA(At, 1, 1); PG8_STAGE(PG8_SB(1, 0), b3, voffB); PG8_STAGE(PG8_SB(1, 1), b3 + hstepB, voffB); PG8_STAGE(PG8_SA(1, 0), a3, voffA);
;             PG8_WAIT_V(8); PG8_WAIT_L(0); PG8_BAR; PG8_MMA(1, 0, At, B0); PG8_MMA(1, 1, At, B1); PG8_BAR; PG8_SCHED;
	s_add_i32 s8, s91, s14
	v_lshl_add_u64 v[228:229], v[208:209], 0, s[38:39]
	s_mov_b32 m0, s8
	ds_read_b128 v[160:163], v212 offset:49152
	ds_read_b128 v[164:167], v212 offset:50176
	ds_read_b128 v[168:171], v212 offset:51200
	ds_read_b128 v[172:175], v212 offset:52224
	ds_read_b128 v[176:179], v212 offset:53248
	ds_read_b128 v[180:183], v212 offset:54272
	ds_read_b128 v[220:223], v212 offset:55296
	ds_read_b128 v[224:227], v212 offset:56320
	global_load_lds_dwordx4 v[228:229], off
	v_lshl_add_u64 v[228:229], v[208:209], 0, s[40:41]
	s_add_i32 m0, s8, 0x2000
	s_add_i32 s8, s92, s14
	global_load_lds_dwordx4 v[228:229], off
	v_lshl_add_u64 v[228:229], v[208:209], 0, s[52:53]
	s_mov_b32 m0, s8
	v_lshl_add_u64 v[208:209], v[208:209], 0, s[54:55]
	global_load_lds_dwordx4 v[228:229], off
	s_add_i32 m0, s8, 0x2000
	s_nop 0
	global_load_lds_dwordx4 v[208:209], off
	v_lshl_add_u64 v[208:209], v[216:217], 0, s[38:39]
	s_mov_b32 m0, s78
	s_nop 0
	global_load_lds_dwordx4 v[208:209], off
	v_lshl_add_u64 v[208:209], v[216:217], 0, s[40:41]
	s_mov_b32 m0, s79
	s_nop 0
	global_load_lds_dwordx4 v[208:209], off
	s_waitcnt vmcnt(8)
	s_waitcnt lgkmcnt(0)
	s_barrier
	s_setprio 1
	s_waitcnt lgkmcnt(0)
	v_mfma_f32_16x16x32_bf16 v[60:63], v[112:115], v[160:163], v[60:63]
	v_mfma_f32_16x16x32_bf16 v[56:59], v[136:139], v[160:163], v[56:59]
	v_mfma_f32_16x16x32_bf16 v[44:47], v[112:115], v[168:171], v[44:47]
	v_mfma_f32_16x16x32_bf16 v[40:43], v[136:139], v[168:171], v[40:43]
	v_mfma_f32_16x16x32_bf16 v[28:31], v[112:115], v[176:179], v[28:31]
	v_mfma_f32_16x16x32_bf16 v[24:27], v[136:139], v[176:179], v[24:27]
	v_mfma_f32_16x16x32_bf16 v[12:15], v[112:115], v[220:223], v[12:15]
	v_mfma_f32_16x16x32_bf16 v[8:11], v[136:139], v[220:223], v[8:11]
	v_mfma_f32_16x16x32_bf16 v[60:63], v[124:127], v[164:167], v[60:63]
	v_mfma_f32_16x16x32_bf16 v[56:59], v[140:143], v[164:167], v[56:59]
	v_mfma_f32_16x16x32_bf16 v[44:47], v[124:127], v[172:175], v[44:47]
	v_mfma_f32_16x16x32_bf16 v[40:43], v[140:143], v[172:175], v[40:43]
	v_mfma_f32_16x16x32_bf16 v[28:31], v[124:127], v[180:183], v[28:31]
	v_mfma_f32_16x16x32_bf16 v[24:27], v[140:143], v[180:183], v[24:27]
	v_mfma_f32_16x16x32_bf16 v[12:15], v[124:127], v[224:227], v[12:15]
	v_mfma_f32_16x16x32_bf16 v[8:11], v[140:143], v[224:227], v[8:11]
	s_setprio 0
	s_setprio 1
	v_mfma_f32_16x16x32_bf16 v[52:55], v[144:147], v[160:163], v[52:55]
	v_mfma_f32_16x16x32_bf16 v[48:51], v[152:155], v[160:163], v[48:51]
	v_mfma_f32_16x16x32_bf16 v[36:39], v[144:147], v[168:171], v[36:39]
	v_mfma_f32_16x16x32_bf16 v[32:35], v[152:155], v[168:171], v[32:35]
	v_mfma_f32_16x16x32_bf16 v[20:23], v[144:147], v[176:179], v[20:23]
	v_mfma_f32_16x16x32_bf16 v[16:19], v[152:155], v[176:179], v[16:19]
	v_mfma_f32_16x16x32_bf16 v[4:7], v[144:147], v[220:223], v[4:7]
	v_mfma_f32_16x16x32_bf16 v[0:3], v[152:155], v[220:223], v[0:3]
	v_mfma_f32_16x16x32_bf16 v[52:55], v[148:151], v[164:167], v[52:55]
	v_mfma_f32_16x16x32_bf16 v[48:51], v[156:159], v[164:167], v[48:51]
	v_mfma_f32_16x16x32_bf16 v[36:39], v[148:151], v[172:175], v[36:39]
	v_mfma_f32_16x16x32_bf16 v[32:35], v[156:159], v[172:175], v[32:35]
	v_mfma_f32_16x16x32_bf16 v[20:23], v[148:151], v[180:183], v[20:23]
	v_mfma_f32_16x16x32_bf16 v[16:19], v[156:159], v[180:183], v[16:19]
	v_mfma_f32_16x16x32_bf16 v[4:7], v[148:151], v[224:227], v[4:7]
	v_mfma_f32_16x16x32_bf16 v[0:3], v[156:159], v[224:227], v[0:3]
	s_setprio 0
	s_barrier
	s_add_i32 s73, s73, 2
	s_add_u32 s68, s68, 0x10000
	s_addc_u32 s69, s69, 0
	s_add_u32 s70, s70, 0x10000
	s_addc_u32 s71, s71, 0
	s_cmp_gt_u32 s73, 41

; #define PG8_STAGE(bufoff, gbase, voff) do { _Pragma("unroll") for (int _i = 0; _i < 2; ++_i) \
;         __builtin_amdgcn_global_load_lds((const unsigned*)((const char*)(gbase) + (voff)[_i]), (PG8_LAS unsigned*)(lds + (bufoff) + ldsw + _i * 8192), 16, 0, 0); } while (0)
; #define PG8_LDA(dst, b, h) do { _Pragma("unroll") for (int m = 0; m < 4; ++m) _Pragma("unroll") for (int k = 0; k < 2; ++k) dst[m][k] = *(const PG8_LAS bf16x8*)(lds + PG8_SA(b, h) + aoff + m * 2048 + k * 1024); } while (0)
; #define PG8_LDB(dst, b, h) do { _Pragma("unroll") for (int n = 0; n < 2; ++n) _Pragma("unroll") for (int k = 0; k < 2; ++k) dst[n][k] = *(const PG8_LAS bf16x8*)(lds + PG8_SB(b, h) + boff + n * 2048 + k * 1024); } while (0)
; #define PG8_MMA(ai, bj, At, Bt) do { __builtin_amdgcn_s_setprio(1); _Pragma("unroll") for (int m = 0; m < 4; ++m) _Pragma("unroll") for (int n = 0; n < 2; ++n) _Pragma("unroll") for (int k = 0; k < 2; ++k) \
;         acc[ai][bj][m][n] = __builtin_amdgcn_mfma_f32_16x16x32_bf16(Bt[n][k], At[m][k], acc[ai][bj][m][n], 0, 0, 0); __builtin_amdgcn_s_setprio(0); } while (0)
; #define PG8_WAIT_V(n) asm volatile("s_waitcnt vmcnt(" #n ")" ::: "memory")
; #define PG8_WAIT_L(n) asm volatile("s_waitcnt lgkmcnt(" #n ")" ::: "memory")
; #define PG8_BAR __builtin_amdgcn_s_barrier()
; #define PG8_SCHED __builtin_amdgcn_sched_barrier(0)
; template <class Epi, class Sched, bool ALIGN_EPI = false, bool SP2 = false>
; __device__ __forceinline__ void gemm_phase(PG8_LAS unsigned char* lds, const Gemm g, const Sched& S, const Epi& E) {
;     ...
;             PG8_LDB(B0, 0, 0); PG8_LDB(B1, 0, 1); PG8_SCHED; PG8_LDA(At, 0, 0); PG8_STAGE(PG8_SA(1, 1), a1 + hstepA, voffA);
;             PG8_WAIT_V(8); PG8_WAIT_L(0); PG8_BAR; PG8_MMA(0, 0, At, B0); PG8_MMA(0, 1, At, B1); PG8_BAR; PG8_SCHED;
;             PG8_LDA(At, 0, 1); PG8_STAGE(PG8_SB(0, 0), b2, voffB); PG8_STAGE(PG8_SB(0, 1), b2 + hstepB, voffB); PG8_STAGE(PG8_SA(0, 0), a2, voffA);
;     ...
; #pragma unroll
;         for (int a = 0; a < 2; ++a)
; #pragma unroll
;             for (int b = 0; b < 2; ++b)
; #pragma unroll
;                 for (int m = 0; m < 4; ++m)
; #pragma unroll
;                     for (int n = 0; n < 2; ++n) acc[a][b][m][n] = (f32x4){0.f, 0.f, 0.f, 0.f};
;         cur = nxt; cA = nA; cB = nB; ++ui;
.LBB0_314:
	s_ashr_i32 s63, s62, 31
	s_lshl_b64 s[8:9], s[62:63], 19
	s_add_u32 s68, s12, s8
	s_addc_u32 s69, s13, s9
	s_and_b64 s[8:9], s[2:3], exec
	s_cselect_b32 s7, s69, s5
	s_cselect_b32 s63, s68, s4
	s_ashr_i32 s61, s60, 31
	s_lshl_b64 s[8:9], s[60:61], 19
	s_add_u32 s70, s87, s8
	s_addc_u32 s71, s88, s9
	s_and_b64 s[8:9], s[2:3], exec
	s_cselect_b32 s61, s71, s75
	s_cselect_b32 s73, s70, s74
	s_add_u32 s4, s4, 0x10000
	s_addc_u32 s5, s5, 0
	s_add_u32 s74, s74, 0x10000
	s_addc_u32 s75, s75, 0
	s_mov_b32 s76, -2
	ds_read_b128 v[140:143], v159
	ds_read_b128 v[144:147], v159 offset:1024
	ds_read_b128 v[148:151], v159 offset:2048
	ds_read_b128 v[166:169], v159 offset:3072
	ds_read_b128 v[170:173], v160
	ds_read_b128 v[174:177], v160 offset:1024
	ds_read_b128 v[178:181], v160 offset:2048
	ds_read_b128 v[182:185], v160 offset:3072
	s_cmp_eq_u32 s76, 12
	s_cselect_b32 s9, s7, s5
	s_cselect_b32 s8, s63, s4
	s_cselect_b32 vcc_hi, s61, s75
	s_cselect_b32 vcc_lo, s73, s74
	s_movk_i32 s78, 0xc000
	v_lshl_add_u64 v[2:3], s[4:5], 0, v[132:133]
	s_mov_b32 s79, -1
	v_lshl_add_u64 v[152:153], v[2:3], 0, s[78:79]
	s_movk_i32 s78, 0xe000
	s_add_i32 m0, s90, 0xc000
	s_mov_b32 s79, -1
	ds_read_b128 v[190:193], v161
	ds_read_b128 v[194:197], v161 offset:1024
	ds_read_b128 v[198:201], v161 offset:2048
	ds_read_b128 v[202:205], v161 offset:3072
	ds_read_b128 v[206:209], v161 offset:4096
	ds_read_b128 v[210:213], v161 offset:5120
	ds_read_b128 v[214:217], v161 offset:6144
	ds_read_b128 v[220:223], v161 offset:7168
	global_load_lds_dwordx4 v[152:153], off
	v_lshl_add_u64 v[2:3], v[2:3], 0, s[78:79]
	s_add_i32 m0, s90, 0xe000
	s_nop 0
	global_load_lds_dwordx4 v[2:3], off
	s_waitcnt vmcnt(8)
	s_waitcnt lgkmcnt(0)
	s_barrier
	s_setprio 1
	s_waitcnt lgkmcnt(0)
	v_mfma_f32_16x16x32_bf16 v[128:131], v[140:143], v[190:193], 0
	v_mfma_f32_16x16x32_bf16 v[124:127], v[148:151], v[190:193], 0
	v_mfma_f32_16x16x32_bf16 v[112:115], v[140:143], v[198:201], 0
	v_mfma_f32_16x16x32_bf16 v[108:111], v[148:151], v[198:201], 0
	v_mfma_f32_16x16x32_bf16 v[96:99], v[140:143], v[206:209], 0
	v_mfma_f32_16x16x32_bf16 v[92:95], v[148:151], v[206:209], 0
	v_mfma_f32_16x16x32_bf16 v[80:83], v[140:143], v[214:217], 0
	v_mfma_f32_16x16x32_bf16 v[76:79], v[148:151], v[214:217], 0
	v_mfma_f32_16x16x32_bf16 v[128:131], v[144:147], v[194:197], v[128:131]
	v_mfma_f32_16x16x32_bf16 v[124:127], v[166:169], v[194:197], v[124:127]
	v_mfma_f32_16x16x32_bf16 v[112:115], v[144:147], v[202:205], v[112:115]
	v_mfma_f32_16x16x32_bf16 v[108:111], v[166:169], v[202:205], v[108:111]
	v_mfma_f32_16x16x32_bf16 v[96:99], v[144:147], v[210:213], v[96:99]
	v_mfma_f32_16x16x32_bf16 v[92:95], v[166:169], v[210:213], v[92:95]
	v_mfma_f32_16x16x32_bf16 v[80:83], v[144:147], v[220:223], v[80:83]
	v_mfma_f32_16x16x32_bf16 v[76:79], v[166:169], v[220:223], v[76:79]
	s_setprio 0
	s_setprio 1
	v_mfma_f32_16x16x32_bf16 v[120:123], v[170:173], v[190:193], 0
	v_mfma_f32_16x16x32_bf16 v[116:119], v[178:181], v[190:193], 0
	v_mfma_f32_16x16x32_bf16 v[104:107], v[170:173], v[198:201], 0
	v_mfma_f32_16x16x32_bf16 v[100:103], v[178:181], v[198:201], 0
	v_mfma_f32_16x16x32_bf16 v[88:91], v[170:173], v[206:209], 0
	v_mfma_f32_16x16x32_bf16 v[84:87], v[178:181], v[206:209], 0
	v_mfma_f32_16x16x32_bf16 v[72:75], v[170:173], v[214:217], 0
	v_mfma_f32_16x16x32_bf16 v[68:71], v[178:181], v[214:217], 0
	v_mfma_f32_16x16x32_bf16 v[120:123], v[174:177], v[194:197], v[120:123]
	v_mfma_f32_16x16x32_bf16 v[116:119], v[182:185], v[194:197], v[116:119]
	v_mfma_f32_16x16x32_bf16 v[104:107], v[174:177], v[202:205], v[104:107]
	v_mfma_f32_16x16x32_bf16 v[100:103], v[182:185], v[202:205], v[100:103]
	v_mfma_f32_16x16x32_bf16 v[88:91], v[174:177], v[210:213], v[88:91]
	v_mfma_f32_16x16x32_bf16 v[84:87], v[182:185], v[210:213], v[84:87]
	v_mfma_f32_16x16x32_bf16 v[72:75], v[174:177], v[220:223], v[72:75]
	v_mfma_f32_16x16x32_bf16 v[68:71], v[182:185], v[220:223], v[68:71]
	s_setprio 0
	s_barrier
	s_add_i32 s77, s15, s89
	v_lshl_add_u64 v[152:153], vcc, 0, v[132:133]
	s_mov_b32 m0, s77
	ds_read_b128 v[190:193], v161 offset:16384
	ds_read_b128 v[194:197], v161 offset:17408
	ds_read_b128 v[198:201], v161 offset:18432
	ds_read_b128 v[202:205], v161 offset:19456
	ds_read_b128 v[206:209], v161 offset:20480
	ds_read_b128 v[210:213], v161 offset:21504
	ds_read_b128 v[214:217], v161 offset:22528
	ds_read_b128 v[220:223], v161 offset:23552
	global_load_lds_dwordx4 v[152:153], off
	v_lshl_add_u64 v[2:3], v[152:153], 0, s[30:31]
	s_add_i32 m0, s77, 0x2000
	s_add_i32 s77, s18, s89
	global_load_lds_dwordx4 v[2:3], off
	v_lshl_add_u64 v[2:3], v[152:153], 0, s[34:35]
	s_mov_b32 m0, s77
	v_lshl_add_u64 v[186:187], s[8:9], 0, v[132:133]
	global_load_lds_dwordx4 v[2:3], off
	v_lshl_add_u64 v[2:3], v[152:153], 0, s[36:37]
	s_add_i32 m0, s77, 0x2000
	s_nop 0
	global_load_lds_dwordx4 v[2:3], off
	s_mov_b32 m0, s90
	v_lshl_add_u64 v[2:3], v[186:187], 0, s[30:31]
	global_load_lds_dwordx4 v[186:187], off
	s_mov_b32 m0, s91
	s_nop 0
	global_load_lds_dwordx4 v[2:3], off
	s_waitcnt vmcnt(8)
	s_waitcnt lgkmcnt(0)
	s_barrier
; #define PG8_STAGE(bufoff, gbase, voff) do { _Pragma("unroll") for (int _i = 0; _i < 2; ++_i) \
;         __builtin_amdgcn_global_load_lds((const unsigned*)((const char*)(gbase) + (voff)[_i]), (PG8_LAS unsigned*)(lds + (bufoff) + ldsw + _i * 8192), 16, 0, 0); } while (0)
; #define PG8_LDA(dst, b, h) do { _Pragma("unroll") for (int m = 0; m < 4; ++m) _Pragma("unroll") for (int k = 0; k < 2; ++k) dst[m][k] = *(const PG8_LAS bf16x8*)(lds + PG8_SA(b, h) + aoff + m * 2048 + k * 1024); } while (0)
; #define PG8_LDB(dst, b, h) do { _Pragma("unroll") for (int n = 0; n < 2; ++n) _Pragma("unroll") for (int k = 0; k < 2; ++k) dst[n][k] = *(const PG8_LAS bf16x8*)(lds + PG8_SB(b, h) + boff + n * 2048 + k * 1024); } while (0)
; #define PG8_MMA(ai, bj, At, Bt) do { __builtin_amdgcn_s_setprio(1); _Pragma("unroll") for (int m = 0; m < 4; ++m) _Pragma("unroll") for (int n = 0; n < 2; ++n) _Pragma("unroll") for (int k = 0; k < 2; ++k) \
;         acc[ai][bj][m][n] = __builtin_amdgcn_mfma_f32_16x16x32_bf16(Bt[n][k], At[m][k], acc[ai][bj][m][n], 0, 0, 0); __builtin_amdgcn_s_setprio(0); } while (0)
; #define PG8_WAIT_V(n) asm volatile("s_waitcnt vmcnt(" #n ")" ::: "memory")
; #define PG8_WAIT_L(n) asm volatile("s_waitcnt lgkmcnt(" #n ")" ::: "memory")
; #define PG8_BAR __builtin_amdgcn_s_barrier()
; #define PG8_SCHED __builtin_amdgcn_sched_barrier(0)
; template <class Epi, class Sched, bool ALIGN_EPI = false, bool SP2 = false>
; __device__ __forceinline__ void gemm_phase(PG8_LAS unsigned char* lds, const Gemm g, const Sched& S, const Epi& E) {
;     ...
;             PG8_WAIT_V(8); PG8_WAIT_L(0); PG8_BAR; PG8_MMA(1, 0, At, B0); PG8_MMA(1, 1, At, B1); PG8_BAR; PG8_SCHED;
;             PG8_LDB(B0, 1, 0); PG8_LDB(B1, 1, 1); PG8_SCHED; PG8_LDA(At, 1, 0); PG8_STAGE(PG8_SA(0, 1), a2 + hstepA, voffA);
;             PG8_WAIT_V(8); PG8_WAIT_L(0); PG8_BAR; PG8_MMA(0, 0, At, B0); PG8_MMA(0, 1, At, B1); PG8_BAR; PG8_SCHED;
	s_setprio 1
	s_waitcnt lgkmcnt(0)
	v_mfma_f32_16x16x32_bf16 v[64:67], v[140:143], v[190:193], 0
	v_mfma_f32_16x16x32_bf16 v[60:63], v[148:151], v[190:193], 0
	v_mfma_f32_16x16x32_bf16 v[48:51], v[140:143], v[198:201], 0
	v_mfma_f32_16x16x32_bf16 v[44:47], v[148:151], v[198:201], 0
	v_mfma_f32_16x16x32_bf16 v[32:35], v[140:143], v[206:209], 0
	v_mfma_f32_16x16x32_bf16 v[28:31], v[148:151], v[206:209], 0
	v_mfma_f32_16x16x32_bf16 v[16:19], v[140:143], v[214:217], 0
	v_mfma_f32_16x16x32_bf16 v[12:15], v[148:151], v[214:217], 0
	v_mfma_f32_16x16x32_bf16 v[64:67], v[144:147], v[194:197], v[64:67]
	v_mfma_f32_16x16x32_bf16 v[60:63], v[166:169], v[194:197], v[60:63]
	v_mfma_f32_16x16x32_bf16 v[48:51], v[144:147], v[202:205], v[48:51]
	v_mfma_f32_16x16x32_bf16 v[44:47], v[166:169], v[202:205], v[44:47]
	v_mfma_f32_16x16x32_bf16 v[32:35], v[144:147], v[210:213], v[32:35]
	v_mfma_f32_16x16x32_bf16 v[28:31], v[166:169], v[210:213], v[28:31]
	v_mfma_f32_16x16x32_bf16 v[16:19], v[144:147], v[220:223], v[16:19]
	v_mfma_f32_16x16x32_bf16 v[12:15], v[166:169], v[220:223], v[12:15]
	s_setprio 0
	s_setprio 1
	v_mfma_f32_16x16x32_bf16 v[56:59], v[170:173], v[190:193], 0
	v_mfma_f32_16x16x32_bf16 v[52:55], v[178:181], v[190:193], 0
	v_mfma_f32_16x16x32_bf16 v[40:43], v[170:173], v[198:201], 0
	v_mfma_f32_16x16x32_bf16 v[36:39], v[178:181], v[198:201], 0
	v_mfma_f32_16x16x32_bf16 v[24:27], v[170:173], v[206:209], 0
	v_mfma_f32_16x16x32_bf16 v[20:23], v[178:181], v[206:209], 0
	v_mfma_f32_16x16x32_bf16 v[8:11], v[170:173], v[214:217], 0
	v_mfma_f32_16x16x32_bf16 v[2:5], v[178:181], v[214:217], 0
	v_mfma_f32_16x16x32_bf16 v[56:59], v[174:177], v[194:197], v[56:59]
	v_mfma_f32_16x16x32_bf16 v[52:55], v[182:185], v[194:197], v[52:55]
	v_mfma_f32_16x16x32_bf16 v[40:43], v[174:177], v[202:205], v[40:43]
	v_mfma_f32_16x16x32_bf16 v[36:39], v[182:185], v[202:205], v[36:39]
	v_mfma_f32_16x16x32_bf16 v[24:27], v[174:177], v[210:213], v[24:27]
	v_mfma_f32_16x16x32_bf16 v[20:23], v[182:185], v[210:213], v[20:23]
	v_mfma_f32_16x16x32_bf16 v[8:11], v[174:177], v[220:223], v[8:11]
	v_mfma_f32_16x16x32_bf16 v[2:5], v[182:185], v[220:223], v[2:5]
	s_setprio 0
	s_barrier
	ds_read_b128 v[140:143], v162
	ds_read_b128 v[144:147], v162 offset:1024
	ds_read_b128 v[148:151], v162 offset:2048
	ds_read_b128 v[166:169], v162 offset:3072
	ds_read_b128 v[170:173], v163
	ds_read_b128 v[174:177], v163 offset:1024
	ds_read_b128 v[178:181], v163 offset:2048
	ds_read_b128 v[182:185], v163 offset:3072
	s_mov_b32 m0, s92
	v_lshl_add_u64 v[6:7], v[186:187], 0, s[34:35]
	ds_read_b128 v[190:193], v161 offset:32768
	ds_read_b128 v[194:197], v161 offset:33792
	ds_read_b128 v[198:201], v161 offset:34816
	ds_read_b128 v[202:205], v161 offset:35840
	ds_read_b128 v[206:209], v161 offset:36864
	ds_read_b128 v[210:213], v161 offset:37888
	ds_read_b128 v[214:217], v161 offset:38912
	ds_read_b128 v[220:223], v161 offset:39936
	global_load_lds_dwordx4 v[6:7], off
	v_lshl_add_u64 v[6:7], v[186:187], 0, s[36:37]
	s_mov_b32 m0, s93
	s_nop 0
	global_load_lds_dwordx4 v[6:7], off
	s_waitcnt vmcnt(8)
	s_waitcnt lgkmcnt(0)
	s_barrier
	s_setprio 1
	s_waitcnt lgkmcnt(0)
	v_mfma_f32_16x16x32_bf16 v[128:131], v[140:143], v[190:193], v[128:131]
	v_mfma_f32_16x16x32_bf16 v[124:127], v[148:151], v[190:193], v[124:127]
	v_mfma_f32_16x16x32_bf16 v[112:115], v[140:143], v[198:201], v[112:115]
	v_mfma_f32_16x16x32_bf16 v[108:111], v[148:151], v[198:201], v[108:111]
	v_mfma_f32_16x16x32_bf16 v[96:99], v[140:143], v[206:209], v[96:99]
	v_mfma_f32_16x16x32_bf16 v[92:95], v[148:151], v[206:209], v[92:95]
	v_mfma_f32_16x16x32_bf16 v[80:83], v[140:143], v[214:217], v[80:83]
	v_mfma_f32_16x16x32_bf16 v[76:79], v[148:151], v[214:217], v[76:79]
	v_mfma_f32_16x16x32_bf16 v[128:131], v[144:147], v[194:197], v[128:131]
	v_mfma_f32_16x16x32_bf16 v[124:127], v[166:169], v[194:197], v[124:127]
	v_mfma_f32_16x16x32_bf16 v[112:115], v[144:147], v[202:205], v[112:115]
	v_mfma_f32_16x16x32_bf16 v[108:111], v[166:169], v[202:205], v[108:111]
	v_mfma_f32_16x16x32_bf16 v[96:99], v[144:147], v[210:213], v[96:99]
	v_mfma_f32_16x16x32_bf16 v[92:95], v[166:169], v[210:213], v[92:95]
	v_mfma_f32_16x16x32_bf16 v[80:83], v[144:147], v[220:223], v[80:83]
	v_mfma_f32_16x16x32_bf16 v[76:79], v[166:169], v[220:223], v[76:79]
	s_setprio 0
	s_setprio 1
	v_mfma_f32_16x16x32_bf16 v[120:123], v[170:173], v[190:193], v[120:123]
	v_mfma_f32_16x16x32_bf16 v[116:119], v[178:181], v[190:193], v[116:119]
	v_mfma_f32_16x16x32_bf16 v[104:107], v[170:173], v[198:201], v[104:107]
	v_mfma_f32_16x16x32_bf16 v[100:103], v[178:181], v[198:201], v[100:103]
	v_mfma_f32_16x16x32_bf16 v[88:91], v[170:173], v[206:209], v[88:91]
	v_mfma_f32_16x16x32_bf16 v[84:87], v[178:181], v[206:209], v[84:87]
	v_mfma_f32_16x16x32_bf16 v[72:75], v[170:173], v[214:217], v[72:75]
	v_mfma_f32_16x16x32_bf16 v[68:71], v[178:181], v[214:217], v[68:71]
	v_mfma_f32_16x16x32_bf16 v[120:123], v[174:177], v[194:197], v[120:123]
	v_mfma_f32_16x16x32_bf16 v[116:119], v[182:185], v[194:197], v[116:119]
	v_mfma_f32_16x16x32_bf16 v[104:107], v[174:177], v[202:205], v[104:107]
	v_mfma_f32_16x16x32_bf16 v[100:103], v[182:185], v[202:205], v[100:103]
	v_mfma_f32_16x16x32_bf16 v[88:91], v[174:177], v[210:213], v[88:91]
	v_mfma_f32_16x16x32_bf16 v[84:87], v[182:185], v[210:213], v[84:87]
	v_mfma_f32_16x16x32_bf16 v[72:75], v[174:177], v[220:223], v[72:75]
	v_mfma_f32_16x16x32_bf16 v[68:71], v[182:185], v[220:223], v[68:71]
	s_setprio 0
	s_barrier
; #define PG8_STAGE(bufoff, gbase, voff) do { _Pragma("unroll") for (int _i = 0; _i < 2; ++_i) \
;         __builtin_amdgcn_global_load_lds((const unsigned*)((const char*)(gbase) + (voff)[_i]), (PG8_LAS unsigned*)(lds + (bufoff) + ldsw + _i * 8192), 16, 0, 0); } while (0)
; #define PG8_LDA(dst, b, h) do { _Pragma("unroll") for (int m = 0; m < 4; ++m) _Pragma("unroll") for (int k = 0; k < 2; ++k) dst[m][k] = *(const PG8_LAS bf16x8*)(lds + PG8_SA(b, h) + aoff + m * 2048 + k * 1024); } while (0)
; #define PG8_MMA(ai, bj, At, Bt) do { __builtin_amdgcn_s_setprio(1); _Pragma("unroll") for (int m = 0; m < 4; ++m) _Pragma("unroll") for (int n = 0; n < 2; ++n) _Pragma("unroll") for (int k = 0; k < 2; ++k) \
;         acc[ai][bj][m][n] = __builtin_amdgcn_mfma_f32_16x16x32_bf16(Bt[n][k], At[m][k], acc[ai][bj][m][n], 0, 0, 0); __builtin_amdgcn_s_setprio(0); } while (0)
; #define PG8_WAIT_V(n) asm volatile("s_waitcnt vmcnt(" #n ")" ::: "memory")
; #define PG8_WAIT_L(n) asm volatile("s_waitcnt lgkmcnt(" #n ")" ::: "memory")
; #define PG8_BAR __builtin_amdgcn_s_barrier()
; #define PG8_SCHED __builtin_amdgcn_sched_barrier(0)
; template <class Epi, class Sched, bool ALIGN_EPI = false, bool SP2 = false>
; __device__ __forceinline__ void gemm_phase(PG8_LAS unsigned char* lds, const Gemm g, const Sched& S, const Epi& E) {
;     ...
;             PG8_LDA(At, 1, 1); PG8_STAGE(PG8_SB(1, 0), b3, voffB); PG8_STAGE(PG8_SB(1, 1), b3 + hstepB, voffB); PG8_STAGE(PG8_SA(1, 0), a3, voffA);
;             PG8_WAIT_V(8); PG8_WAIT_L(0); PG8_BAR; PG8_MMA(1, 0, At, B0); PG8_MMA(1, 1, At, B1); PG8_BAR; PG8_SCHED;
	s_add_i32 s8, s19, s89
	v_lshl_add_u64 v[6:7], v[152:153], 0, s[38:39]
	s_mov_b32 m0, s8
	ds_read_b128 v[190:193], v161 offset:49152
	ds_read_b128 v[194:197], v161 offset:50176
	ds_read_b128 v[198:201], v161 offset:51200
	ds_read_b128 v[202:205], v161 offset:52224
	ds_read_b128 v[206:209], v161 offset:53248
	ds_read_b128 v[210:213], v161 offset:54272
	ds_read_b128 v[214:217], v161 offset:55296
	ds_read_b128 v[220:223], v161 offset:56320
	global_load_lds_dwordx4 v[6:7], off
	v_lshl_add_u64 v[6:7], v[152:153], 0, s[40:41]
	s_add_i32 m0, s8, 0x2000
	s_add_i32 s8, s80, s89
	global_load_lds_dwordx4 v[6:7], off
	v_lshl_add_u64 v[6:7], v[152:153], 0, s[52:53]
	s_mov_b32 m0, s8
	s_nop 0
	global_load_lds_dwordx4 v[6:7], off
	v_lshl_add_u64 v[6:7], v[152:153], 0, s[54:55]
	s_add_i32 m0, s8, 0x2000
	s_nop 0
	global_load_lds_dwordx4 v[6:7], off
	v_lshl_add_u64 v[6:7], v[186:187], 0, s[38:39]
	s_mov_b32 m0, s94
	s_nop 0
	global_load_lds_dwordx4 v[6:7], off
	v_lshl_add_u64 v[6:7], v[186:187], 0, s[40:41]
	s_mov_b32 m0, s95
	s_nop 0
	global_load_lds_dwordx4 v[6:7], off
	s_waitcnt vmcnt(8)
	s_waitcnt lgkmcnt(0)
	s_barrier
	s_setprio 1
	s_waitcnt lgkmcnt(0)
	v_mfma_f32_16x16x32_bf16 v[64:67], v[140:143], v[190:193], v[64:67]
	v_mfma_f32_16x16x32_bf16 v[60:63], v[148:151], v[190:193], v[60:63]
	v_mfma_f32_16x16x32_bf16 v[48:51], v[140:143], v[198:201], v[48:51]
	v_mfma_f32_16x16x32_bf16 v[44:47], v[148:151], v[198:201], v[44:47]
	v_mfma_f32_16x16x32_bf16 v[32:35], v[140:143], v[206:209], v[32:35]
	v_mfma_f32_16x16x32_bf16 v[28:31], v[148:151], v[206:209], v[28:31]
	v_mfma_f32_16x16x32_bf16 v[16:19], v[140:143], v[214:217], v[16:19]
	v_mfma_f32_16x16x32_bf16 v[12:15], v[148:151], v[214:217], v[12:15]
	v_mfma_f32_16x16x32_bf16 v[64:67], v[144:147], v[194:197], v[64:67]
	v_mfma_f32_16x16x32_bf16 v[60:63], v[166:169], v[194:197], v[60:63]
	v_mfma_f32_16x16x32_bf16 v[48:51], v[144:147], v[202:205], v[48:51]
	v_mfma_f32_16x16x32_bf16 v[44:47], v[166:169], v[202:205], v[44:47]
	v_mfma_f32_16x16x32_bf16 v[32:35], v[144:147], v[210:213], v[32:35]
	v_mfma_f32_16x16x32_bf16 v[28:31], v[166:169], v[210:213], v[28:31]
	v_mfma_f32_16x16x32_bf16 v[16:19], v[144:147], v[220:223], v[16:19]
	v_mfma_f32_16x16x32_bf16 v[12:15], v[166:169], v[220:223], v[12:15]
	s_setprio 0
	s_setprio 1
	v_mfma_f32_16x16x32_bf16 v[56:59], v[170:173], v[190:193], v[56:59]
	v_mfma_f32_16x16x32_bf16 v[52:55], v[178:181], v[190:193], v[52:55]
	v_mfma_f32_16x16x32_bf16 v[40:43], v[170:173], v[198:201], v[40:43]
	v_mfma_f32_16x16x32_bf16 v[36:39], v[178:181], v[198:201], v[36:39]
	v_mfma_f32_16x16x32_bf16 v[24:27], v[170:173], v[206:209], v[24:27]
	v_mfma_f32_16x16x32_bf16 v[20:23], v[178:181], v[206:209], v[20:23]
	v_mfma_f32_16x16x32_bf16 v[6:9], v[170:173], v[214:217], v[8:11]
	v_mfma_f32_16x16x32_bf16 v[2:5], v[178:181], v[214:217], v[2:5]
	v_mfma_f32_16x16x32_bf16 v[56:59], v[174:177], v[194:197], v[56:59]
	v_mfma_f32_16x16x32_bf16 v[52:55], v[182:185], v[194:197], v[52:55]
	v_mfma_f32_16x16x32_bf16 v[40:43], v[174:177], v[202:205], v[40:43]
	v_mfma_f32_16x16x32_bf16 v[36:39], v[182:185], v[202:205], v[36:39]
	v_mfma_f32_16x16x32_bf16 v[24:27], v[174:177], v[210:213], v[24:27]
	v_mfma_f32_16x16x32_bf16 v[20:23], v[182:185], v[210:213], v[20:23]
	v_mfma_f32_16x16x32_bf16 v[8:11], v[174:177], v[220:223], v[6:9]
	v_mfma_f32_16x16x32_bf16 v[4:7], v[182:185], v[220:223], v[2:5]
	s_setprio 0
	s_barrier
	s_add_i32 s76, s76, 2
	s_add_u32 s4, s4, 0x10000
	s_addc_u32 s5, s5, 0
	s_add_u32 s74, s74, 0x10000
	s_addc_u32 s75, s75, 0
	s_cmp_gt_u32 s76, 13

; #define PG8_STAGE(bufoff, gbase, voff) do { _Pragma("unroll") for (int _i = 0; _i < 2; ++_i) \
;         __builtin_amdgcn_global_load_lds((const unsigned*)((const char*)(gbase) + (voff)[_i]), (PG8_LAS unsigned*)(lds + (bufoff) + ldsw + _i * 8192), 16, 0, 0); } while (0)
; #define PG8_LDA(dst, b, h) do { _Pragma("unroll") for (int m = 0; m < 4; ++m) _Pragma("unroll") for (int k = 0; k < 2; ++k) dst[m][k] = *(const PG8_LAS bf16x8*)(lds + PG8_SA(b, h) + aoff + m * 2048 + k * 1024); } while (0)
; #define PG8_LDB(dst, b, h) do { _Pragma("unroll") for (int n = 0; n < 2; ++n) _Pragma("unroll") for (int k = 0; k < 2; ++k) dst[n][k] = *(const PG8_LAS bf16x8*)(lds + PG8_SB(b, h) + boff + n * 2048 + k * 1024); } while (0)
; #define PG8_MMA(ai, bj, At, Bt) do { __builtin_amdgcn_s_setprio(1); _Pragma("unroll") for (int m = 0; m < 4; ++m) _Pragma("unroll") for (int n = 0; n < 2; ++n) _Pragma("unroll") for (int k = 0; k < 2; ++k) \
;         acc[ai][bj][m][n] = __builtin_amdgcn_mfma_f32_16x16x32_bf16(Bt[n][k], At[m][k], acc[ai][bj][m][n], 0, 0, 0); __builtin_amdgcn_s_setprio(0); } while (0)
; #define PG8_WAIT_V(n) asm volatile("s_waitcnt vmcnt(" #n ")" ::: "memory")
; #define PG8_WAIT_L(n) asm volatile("s_waitcnt lgkmcnt(" #n ")" ::: "memory")
; #define PG8_BAR __builtin_amdgcn_s_barrier()
; #define PG8_SCHED __builtin_amdgcn_sched_barrier(0)
; template <class Epi, class Sched, bool ALIGN_EPI = false, bool SP2 = false>
; __device__ __forceinline__ void gemm_phase(PG8_LAS unsigned char* lds, const Gemm g, const Sched& S, const Epi& E) {
;     ...
;             PG8_LDB(B0, 0, 0); PG8_LDB(B1, 0, 1); PG8_SCHED; PG8_LDA(At, 0, 0); PG8_STAGE(PG8_SA(1, 1), a1 + hstepA, voffA);
;             PG8_WAIT_V(8); PG8_WAIT_L(0); PG8_BAR; PG8_MMA(0, 0, At, B0); PG8_MMA(0, 1, At, B1); PG8_BAR; PG8_SCHED;
;             PG8_LDA(At, 0, 1); PG8_STAGE(PG8_SB(0, 0), b2, voffB); PG8_STAGE(PG8_SB(0, 1), b2 + hstepB, voffB); PG8_STAGE(PG8_SA(0, 0), a2, voffA);
;     ...
; #pragma unroll
;         for (int a = 0; a < 2; ++a)
; #pragma unroll
;             for (int b = 0; b < 2; ++b)
; #pragma unroll
;                 for (int m = 0; m < 4; ++m)
; #pragma unroll
;                     for (int n = 0; n < 2; ++n) acc[a][b][m][n] = (f32x4){0.f, 0.f, 0.f, 0.f};
;         cur = nxt; cA = nA; cB = nB; ++ui;
.LBB0_645:
	s_ashr_i32 s61, s60, 31
	s_lshl_b64 s[8:9], s[60:61], 19
	s_add_u32 s64, s85, s8
	s_addc_u32 s65, s86, s9
	s_and_b64 s[0:1], s[0:1], exec
	s_cselect_b32 s61, s65, s67
	s_cselect_b32 s90, s64, s66
	s_add_u32 s91, s66, 0x10000
	s_addc_u32 s92, s67, 0
	s_add_u32 s0, s68, 0xf0080
	s_addc_u32 s1, s69, 0
	s_mov_b32 s68, -2
	ds_read_b128 v[128:131], v197
	ds_read_b128 v[132:135], v197 offset:1024
	ds_read_b128 v[136:139], v197 offset:2048
	ds_read_b128 v[140:143], v197 offset:3072
	ds_read_b128 v[144:147], v198
	ds_read_b128 v[148:151], v198 offset:1024
	ds_read_b128 v[152:155], v198 offset:2048
	ds_read_b128 v[156:159], v198 offset:3072
	s_add_u32 s8, s0, 0xfff10080
	s_addc_u32 s9, s1, -1
	s_cmp_eq_u32 s68, 12
	s_cselect_b32 s67, s63, s9
	s_cselect_b32 s66, s62, s8
	s_cselect_b32 s9, s61, s92
	s_cselect_b32 s8, s90, s91
	v_lshl_add_u64 v[236:237], s[0:1], 0, v[174:175]
	s_add_i32 m0, s17, 0xc000
	ds_read_b128 v[202:205], v199
	ds_read_b128 v[206:209], v199 offset:1024
	ds_read_b128 v[210:213], v199 offset:2048
	ds_read_b128 v[214:217], v199 offset:3072
	ds_read_b128 v[220:223], v199 offset:4096
	ds_read_b128 v[224:227], v199 offset:5120
	ds_read_b128 v[228:231], v199 offset:6144
	ds_read_b128 v[232:235], v199 offset:7168
	global_load_lds_dwordx4 v[236:237], off
	v_lshl_add_u64 v[236:237], s[0:1], 0, v[176:177]
	s_add_i32 m0, s17, 0xe000
	s_nop 0
	global_load_lds_dwordx4 v[236:237], off
	s_waitcnt vmcnt(8)
	s_waitcnt lgkmcnt(0)
	s_barrier
	s_setprio 1
	s_waitcnt lgkmcnt(0)
	v_mfma_f32_16x16x32_bf16 v[124:127], v[128:131], v[202:205], 0
	v_mfma_f32_16x16x32_bf16 v[120:123], v[136:139], v[202:205], 0
	v_mfma_f32_16x16x32_bf16 v[108:111], v[128:131], v[210:213], 0
	v_mfma_f32_16x16x32_bf16 v[104:107], v[136:139], v[210:213], 0
	v_mfma_f32_16x16x32_bf16 v[96:99], v[128:131], v[220:223], 0
	v_mfma_f32_16x16x32_bf16 v[88:91], v[136:139], v[220:223], 0
	v_mfma_f32_16x16x32_bf16 v[80:83], v[128:131], v[228:231], 0
	v_mfma_f32_16x16x32_bf16 v[72:75], v[136:139], v[228:231], 0
	v_mfma_f32_16x16x32_bf16 v[124:127], v[132:135], v[206:209], v[124:127]
	v_mfma_f32_16x16x32_bf16 v[120:123], v[140:143], v[206:209], v[120:123]
	v_mfma_f32_16x16x32_bf16 v[108:111], v[132:135], v[214:217], v[108:111]
	v_mfma_f32_16x16x32_bf16 v[104:107], v[140:143], v[214:217], v[104:107]
	v_mfma_f32_16x16x32_bf16 v[96:99], v[132:135], v[224:227], v[96:99]
	v_mfma_f32_16x16x32_bf16 v[88:91], v[140:143], v[224:227], v[88:91]
	v_mfma_f32_16x16x32_bf16 v[80:83], v[132:135], v[232:235], v[80:83]
	v_mfma_f32_16x16x32_bf16 v[72:75], v[140:143], v[232:235], v[72:75]
	s_setprio 0
	s_setprio 1
	v_mfma_f32_16x16x32_bf16 v[116:119], v[144:147], v[202:205], 0
	v_mfma_f32_16x16x32_bf16 v[112:115], v[152:155], v[202:205], 0
	v_mfma_f32_16x16x32_bf16 v[100:103], v[144:147], v[210:213], 0
	v_mfma_f32_16x16x32_bf16 v[92:95], v[152:155], v[210:213], 0
	v_mfma_f32_16x16x32_bf16 v[84:87], v[144:147], v[220:223], 0
	v_mfma_f32_16x16x32_bf16 v[76:79], v[152:155], v[220:223], 0
	v_mfma_f32_16x16x32_bf16 v[68:71], v[144:147], v[228:231], 0
	v_mfma_f32_16x16x32_bf16 v[64:67], v[152:155], v[228:231], 0
	v_mfma_f32_16x16x32_bf16 v[116:119], v[148:151], v[206:209], v[116:119]
	v_mfma_f32_16x16x32_bf16 v[112:115], v[156:159], v[206:209], v[112:115]
	v_mfma_f32_16x16x32_bf16 v[100:103], v[148:151], v[214:217], v[100:103]
	v_mfma_f32_16x16x32_bf16 v[92:95], v[156:159], v[214:217], v[92:95]
	v_mfma_f32_16x16x32_bf16 v[84:87], v[148:151], v[224:227], v[84:87]
	v_mfma_f32_16x16x32_bf16 v[76:79], v[156:159], v[224:227], v[76:79]
	v_mfma_f32_16x16x32_bf16 v[68:71], v[148:151], v[232:235], v[68:71]
	v_mfma_f32_16x16x32_bf16 v[64:67], v[156:159], v[232:235], v[64:67]
	s_setprio 0
	s_barrier
	v_lshl_add_u64 v[236:237], s[8:9], 0, v[190:191]
	s_add_i32 s8, s77, s15
	s_mov_b32 m0, s8
	ds_read_b128 v[202:205], v199 offset:16384
	ds_read_b128 v[206:209], v199 offset:17408
	ds_read_b128 v[210:213], v199 offset:18432
	ds_read_b128 v[214:217], v199 offset:19456
	ds_read_b128 v[220:223], v199 offset:20480
	ds_read_b128 v[224:227], v199 offset:21504
	ds_read_b128 v[228:231], v199 offset:22528
	ds_read_b128 v[232:235], v199 offset:23552
	global_load_lds_dwordx4 v[236:237], off
	v_lshl_add_u64 v[238:239], v[236:237], 0, s[36:37]
	s_add_i32 m0, s8, 0x2000
	s_add_i32 s8, s80, s15
	global_load_lds_dwordx4 v[238:239], off
	v_lshl_add_u64 v[238:239], v[236:237], 0, s[38:39]
	s_mov_b32 m0, s8
	v_lshl_add_u64 v[240:241], s[66:67], 0, v[162:163]
	global_load_lds_dwordx4 v[238:239], off
	v_lshl_add_u64 v[238:239], v[236:237], 0, s[40:41]
	s_add_i32 m0, s8, 0x2000
	s_nop 0
	global_load_lds_dwordx4 v[238:239], off
	v_lshl_add_u64 v[238:239], s[66:67], 0, v[160:161]
	s_mov_b32 m0, s17
	s_nop 0
	global_load_lds_dwordx4 v[238:239], off
	s_mov_b32 m0, s18
	s_nop 0
	global_load_lds_dwordx4 v[240:241], off
	s_waitcnt vmcnt(8)
	s_waitcnt lgkmcnt(0)
	s_barrier
; #define PG8_STAGE(bufoff, gbase, voff) do { _Pragma("unroll") for (int _i = 0; _i < 2; ++_i) \
;         __builtin_amdgcn_global_load_lds((const unsigned*)((const char*)(gbase) + (voff)[_i]), (PG8_LAS unsigned*)(lds + (bufoff) + ldsw + _i * 8192), 16, 0, 0); } while (0)
; #define PG8_LDA(dst, b, h) do { _Pragma("unroll") for (int m = 0; m < 4; ++m) _Pragma("unroll") for (int k = 0; k < 2; ++k) dst[m][k] = *(const PG8_LAS bf16x8*)(lds + PG8_SA(b, h) + aoff + m * 2048 + k * 1024); } while (0)
; #define PG8_LDB(dst, b, h) do { _Pragma("unroll") for (int n = 0; n < 2; ++n) _Pragma("unroll") for (int k = 0; k < 2; ++k) dst[n][k] = *(const PG8_LAS bf16x8*)(lds + PG8_SB(b, h) + boff + n * 2048 + k * 1024); } while (0)
; #define PG8_MMA(ai, bj, At, Bt) do { __builtin_amdgcn_s_setprio(1); _Pragma("unroll") for (int m = 0; m < 4; ++m) _Pragma("unroll") for (int n = 0; n < 2; ++n) _Pragma("unroll") for (int k = 0; k < 2; ++k) \
;         acc[ai][bj][m][n] = __builtin_amdgcn_mfma_f32_16x16x32_bf16(Bt[n][k], At[m][k], acc[ai][bj][m][n], 0, 0, 0); __builtin_amdgcn_s_setprio(0); } while (0)
; #define PG8_WAIT_V(n) asm volatile("s_waitcnt vmcnt(" #n ")" ::: "memory")
; #define PG8_WAIT_L(n) asm volatile("s_waitcnt lgkmcnt(" #n ")" ::: "memory")
; #define PG8_BAR __builtin_amdgcn_s_barrier()
; #define PG8_SCHED __builtin_amdgcn_sched_barrier(0)
; template <class Epi, class Sched, bool ALIGN_EPI = false, bool SP2 = false>
; __device__ __forceinline__ void gemm_phase(PG8_LAS unsigned char* lds, const Gemm g, const Sched& S, const Epi& E) {
;     ...
;             PG8_WAIT_V(8); PG8_WAIT_L(0); PG8_BAR; PG8_MMA(1, 0, At, B0); PG8_MMA(1, 1, At, B1); PG8_BAR; PG8_SCHED;
;             PG8_LDB(B0, 1, 0); PG8_LDB(B1, 1, 1); PG8_SCHED; PG8_LDA(At, 1, 0); PG8_STAGE(PG8_SA(0, 1), a2 + hstepA, voffA);
;             PG8_WAIT_V(8); PG8_WAIT_L(0); PG8_BAR; PG8_MMA(0, 0, At, B0); PG8_MMA(0, 1, At, B1); PG8_BAR; PG8_SCHED;
	s_setprio 1
	s_waitcnt lgkmcnt(0)
	v_mfma_f32_16x16x32_bf16 v[60:63], v[128:131], v[202:205], 0
	v_mfma_f32_16x16x32_bf16 v[56:59], v[136:139], v[202:205], 0
	v_mfma_f32_16x16x32_bf16 v[48:51], v[128:131], v[210:213], 0
	v_mfma_f32_16x16x32_bf16 v[40:43], v[136:139], v[210:213], 0
	v_mfma_f32_16x16x32_bf16 v[32:35], v[128:131], v[220:223], 0
	v_mfma_f32_16x16x32_bf16 v[24:27], v[136:139], v[220:223], 0
	v_mfma_f32_16x16x32_bf16 v[16:19], v[128:131], v[228:231], 0
	v_mfma_f32_16x16x32_bf16 v[8:11], v[136:139], v[228:231], 0
	v_mfma_f32_16x16x32_bf16 v[60:63], v[132:135], v[206:209], v[60:63]
	v_mfma_f32_16x16x32_bf16 v[56:59], v[140:143], v[206:209], v[56:59]
	v_mfma_f32_16x16x32_bf16 v[48:51], v[132:135], v[214:217], v[48:51]
	v_mfma_f32_16x16x32_bf16 v[40:43], v[140:143], v[214:217], v[40:43]
	v_mfma_f32_16x16x32_bf16 v[32:35], v[132:135], v[224:227], v[32:35]
	v_mfma_f32_16x16x32_bf16 v[24:27], v[140:143], v[224:227], v[24:27]
	v_mfma_f32_16x16x32_bf16 v[16:19], v[132:135], v[232:235], v[16:19]
	v_mfma_f32_16x16x32_bf16 v[8:11], v[140:143], v[232:235], v[8:11]
	s_setprio 0
	s_setprio 1
	v_mfma_f32_16x16x32_bf16 v[52:55], v[144:147], v[202:205], 0
	v_mfma_f32_16x16x32_bf16 v[44:47], v[152:155], v[202:205], 0
	v_mfma_f32_16x16x32_bf16 v[36:39], v[144:147], v[210:213], 0
	v_mfma_f32_16x16x32_bf16 v[28:31], v[152:155], v[210:213], 0
	v_mfma_f32_16x16x32_bf16 v[20:23], v[144:147], v[220:223], 0
	v_mfma_f32_16x16x32_bf16 v[12:15], v[152:155], v[220:223], 0
	v_mfma_f32_16x16x32_bf16 v[4:7], v[144:147], v[228:231], 0
	v_mfma_f32_16x16x32_bf16 v[0:3], v[152:155], v[228:231], 0
	v_mfma_f32_16x16x32_bf16 v[52:55], v[148:151], v[206:209], v[52:55]
	v_mfma_f32_16x16x32_bf16 v[44:47], v[156:159], v[206:209], v[44:47]
	v_mfma_f32_16x16x32_bf16 v[36:39], v[148:151], v[214:217], v[36:39]
	v_mfma_f32_16x16x32_bf16 v[28:31], v[156:159], v[214:217], v[28:31]
	v_mfma_f32_16x16x32_bf16 v[20:23], v[148:151], v[224:227], v[20:23]
	v_mfma_f32_16x16x32_bf16 v[12:15], v[156:159], v[224:227], v[12:15]
	v_mfma_f32_16x16x32_bf16 v[4:7], v[148:151], v[232:235], v[4:7]
	v_mfma_f32_16x16x32_bf16 v[0:3], v[156:159], v[232:235], v[0:3]
	s_setprio 0
	s_barrier
	ds_read_b128 v[128:131], v200
	ds_read_b128 v[132:135], v200 offset:1024
	ds_read_b128 v[136:139], v200 offset:2048
	ds_read_b128 v[140:143], v200 offset:3072
	ds_read_b128 v[144:147], v201
	ds_read_b128 v[148:151], v201 offset:1024
	ds_read_b128 v[152:155], v201 offset:2048
	ds_read_b128 v[156:159], v201 offset:3072
	s_add_u32 s8, s66, 0xf0000
	s_addc_u32 s9, s67, 0
	s_mov_b32 m0, s19
	v_lshl_add_u64 v[242:243], s[8:9], 0, v[160:161]
	ds_read_b128 v[202:205], v199 offset:32768
	ds_read_b128 v[206:209], v199 offset:33792
	ds_read_b128 v[210:213], v199 offset:34816
	ds_read_b128 v[214:217], v199 offset:35840
	ds_read_b128 v[220:223], v199 offset:36864
	ds_read_b128 v[224:227], v199 offset:37888
	ds_read_b128 v[228:231], v199 offset:38912
	ds_read_b128 v[232:235], v199 offset:39936
	global_load_lds_dwordx4 v[242:243], off
	v_lshl_add_u64 v[242:243], s[8:9], 0, v[162:163]
	s_mov_b32 m0, s59
	s_nop 0
	global_load_lds_dwordx4 v[242:243], off
	s_waitcnt vmcnt(8)
	s_waitcnt lgkmcnt(0)
	s_barrier
	s_setprio 1
	s_waitcnt lgkmcnt(0)
	v_mfma_f32_16x16x32_bf16 v[124:127], v[128:131], v[202:205], v[124:127]
	v_mfma_f32_16x16x32_bf16 v[120:123], v[136:139], v[202:205], v[120:123]
	v_mfma_f32_16x16x32_bf16 v[108:111], v[128:131], v[210:213], v[108:111]
	v_mfma_f32_16x16x32_bf16 v[104:107], v[136:139], v[210:213], v[104:107]
	v_mfma_f32_16x16x32_bf16 v[96:99], v[128:131], v[220:223], v[96:99]
	v_mfma_f32_16x16x32_bf16 v[88:91], v[136:139], v[220:223], v[88:91]
	v_mfma_f32_16x16x32_bf16 v[80:83], v[128:131], v[228:231], v[80:83]
	v_mfma_f32_16x16x32_bf16 v[72:75], v[136:139], v[228:231], v[72:75]
	v_mfma_f32_16x16x32_bf16 v[124:127], v[132:135], v[206:209], v[124:127]
	v_mfma_f32_16x16x32_bf16 v[120:123], v[140:143], v[206:209], v[120:123]
	v_mfma_f32_16x16x32_bf16 v[108:111], v[132:135], v[214:217], v[108:111]
	v_mfma_f32_16x16x32_bf16 v[104:107], v[140:143], v[214:217], v[104:107]
	v_mfma_f32_16x16x32_bf16 v[96:99], v[132:135], v[224:227], v[96:99]
	v_mfma_f32_16x16x32_bf16 v[88:91], v[140:143], v[224:227], v[88:91]
	v_mfma_f32_16x16x32_bf16 v[80:83], v[132:135], v[232:235], v[80:83]
	v_mfma_f32_16x16x32_bf16 v[72:75], v[140:143], v[232:235], v[72:75]
	s_setprio 0
	s_setprio 1
	v_mfma_f32_16x16x32_bf16 v[116:119], v[144:147], v[202:205], v[116:119]
	v_mfma_f32_16x16x32_bf16 v[112:115], v[152:155], v[202:205], v[112:115]
	v_mfma_f32_16x16x32_bf16 v[100:103], v[144:147], v[210:213], v[100:103]
	v_mfma_f32_16x16x32_bf16 v[92:95], v[152:155], v[210:213], v[92:95]
	v_mfma_f32_16x16x32_bf16 v[84:87], v[144:147], v[220:223], v[84:87]
	v_mfma_f32_16x16x32_bf16 v[76:79], v[152:155], v[220:223], v[76:79]
	v_mfma_f32_16x16x32_bf16 v[68:71], v[144:147], v[228:231], v[68:71]
	v_mfma_f32_16x16x32_bf16 v[64:67], v[152:155], v[228:231], v[64:67]
	v_mfma_f32_16x16x32_bf16 v[116:119], v[148:151], v[206:209], v[116:119]
	v_mfma_f32_16x16x32_bf16 v[112:115], v[156:159], v[206:209], v[112:115]
	v_mfma_f32_16x16x32_bf16 v[100:103], v[148:151], v[214:217], v[100:103]
	v_mfma_f32_16x16x32_bf16 v[92:95], v[156:159], v[214:217], v[92:95]
	v_mfma_f32_16x16x32_bf16 v[84:87], v[148:151], v[224:227], v[84:87]
	v_mfma_f32_16x16x32_bf16 v[76:79], v[156:159], v[224:227], v[76:79]
	v_mfma_f32_16x16x32_bf16 v[68:71], v[148:151], v[232:235], v[68:71]
	v_mfma_f32_16x16x32_bf16 v[64:67], v[156:159], v[232:235], v[64:67]
	s_setprio 0
	s_barrier
; #define PG8_STAGE(bufoff, gbase, voff) do { _Pragma("unroll") for (int _i = 0; _i < 2; ++_i) \
;         __builtin_amdgcn_global_load_lds((const unsigned*)((const char*)(gbase) + (voff)[_i]), (PG8_LAS unsigned*)(lds + (bufoff) + ldsw + _i * 8192), 16, 0, 0); } while (0)
; #define PG8_LDA(dst, b, h) do { _Pragma("unroll") for (int m = 0; m < 4; ++m) _Pragma("unroll") for (int k = 0; k < 2; ++k) dst[m][k] = *(const PG8_LAS bf16x8*)(lds + PG8_SA(b, h) + aoff + m * 2048 + k * 1024); } while (0)
; #define PG8_MMA(ai, bj, At, Bt) do { __builtin_amdgcn_s_setprio(1); _Pragma("unroll") for (int m = 0; m < 4; ++m) _Pragma("unroll") for (int n = 0; n < 2; ++n) _Pragma("unroll") for (int k = 0; k < 2; ++k) \
;         acc[ai][bj][m][n] = __builtin_amdgcn_mfma_f32_16x16x32_bf16(Bt[n][k], At[m][k], acc[ai][bj][m][n], 0, 0, 0); __builtin_amdgcn_s_setprio(0); } while (0)
; #define PG8_WAIT_V(n) asm volatile("s_waitcnt vmcnt(" #n ")" ::: "memory")
; #define PG8_WAIT_L(n) asm volatile("s_waitcnt lgkmcnt(" #n ")" ::: "memory")
; #define PG8_BAR __builtin_amdgcn_s_barrier()
; #define PG8_SCHED __builtin_amdgcn_sched_barrier(0)
; template <class Epi, class Sched, bool ALIGN_EPI = false, bool SP2 = false>
; __device__ __forceinline__ void gemm_phase(PG8_LAS unsigned char* lds, const Gemm g, const Sched& S, const Epi& E) {
;     ...
;             PG8_LDA(At, 1, 1); PG8_STAGE(PG8_SB(1, 0), b3, voffB); PG8_STAGE(PG8_SB(1, 1), b3 + hstepB, voffB); PG8_STAGE(PG8_SA(1, 0), a3, voffA);
;             PG8_WAIT_V(8); PG8_WAIT_L(0); PG8_BAR; PG8_MMA(1, 0, At, B0); PG8_MMA(1, 1, At, B1); PG8_BAR; PG8_SCHED;
	s_add_i32 s8, s81, s15
	v_lshl_add_u64 v[242:243], v[236:237], 0, s[42:43]
	s_mov_b32 m0, s8
	ds_read_b128 v[202:205], v199 offset:49152
	ds_read_b128 v[206:209], v199 offset:50176
	ds_read_b128 v[210:213], v199 offset:51200
	ds_read_b128 v[214:217], v199 offset:52224
	ds_read_b128 v[220:223], v199 offset:53248
	ds_read_b128 v[224:227], v199 offset:54272
	ds_read_b128 v[228:231], v199 offset:55296
	ds_read_b128 v[232:235], v199 offset:56320
	global_load_lds_dwordx4 v[242:243], off
	v_lshl_add_u64 v[242:243], v[236:237], 0, s[44:45]
	s_add_i32 m0, s8, 0x2000
	s_add_i32 s8, s82, s15
	global_load_lds_dwordx4 v[242:243], off
	v_lshl_add_u64 v[242:243], v[236:237], 0, s[48:49]
	s_mov_b32 m0, s8
	v_lshl_add_u64 v[236:237], v[236:237], 0, s[52:53]
	global_load_lds_dwordx4 v[242:243], off
	s_add_i32 m0, s8, 0x2000
	s_nop 0
	global_load_lds_dwordx4 v[236:237], off
	v_lshl_add_u64 v[236:237], v[238:239], 0, s[46:47]
	s_mov_b32 m0, s70
	s_nop 0
	global_load_lds_dwordx4 v[236:237], off
	v_lshl_add_u64 v[236:237], v[240:241], 0, s[46:47]
	s_mov_b32 m0, s71
	s_nop 0
	global_load_lds_dwordx4 v[236:237], off
	s_waitcnt vmcnt(8)
	s_waitcnt lgkmcnt(0)
	s_barrier
	s_setprio 1
	s_waitcnt lgkmcnt(0)
	v_mfma_f32_16x16x32_bf16 v[60:63], v[128:131], v[202:205], v[60:63]
	v_mfma_f32_16x16x32_bf16 v[56:59], v[136:139], v[202:205], v[56:59]
	v_mfma_f32_16x16x32_bf16 v[48:51], v[128:131], v[210:213], v[48:51]
	v_mfma_f32_16x16x32_bf16 v[40:43], v[136:139], v[210:213], v[40:43]
	v_mfma_f32_16x16x32_bf16 v[32:35], v[128:131], v[220:223], v[32:35]
	v_mfma_f32_16x16x32_bf16 v[24:27], v[136:139], v[220:223], v[24:27]
	v_mfma_f32_16x16x32_bf16 v[16:19], v[128:131], v[228:231], v[16:19]
	v_mfma_f32_16x16x32_bf16 v[8:11], v[136:139], v[228:231], v[8:11]
	v_mfma_f32_16x16x32_bf16 v[60:63], v[132:135], v[206:209], v[60:63]
	v_mfma_f32_16x16x32_bf16 v[56:59], v[140:143], v[206:209], v[56:59]
	v_mfma_f32_16x16x32_bf16 v[48:51], v[132:135], v[214:217], v[48:51]
	v_mfma_f32_16x16x32_bf16 v[40:43], v[140:143], v[214:217], v[40:43]
	v_mfma_f32_16x16x32_bf16 v[32:35], v[132:135], v[224:227], v[32:35]
	v_mfma_f32_16x16x32_bf16 v[24:27], v[140:143], v[224:227], v[24:27]
	v_mfma_f32_16x16x32_bf16 v[16:19], v[132:135], v[232:235], v[16:19]
	v_mfma_f32_16x16x32_bf16 v[8:11], v[140:143], v[232:235], v[8:11]
	s_setprio 0
	s_setprio 1
	v_mfma_f32_16x16x32_bf16 v[52:55], v[144:147], v[202:205], v[52:55]
	v_mfma_f32_16x16x32_bf16 v[44:47], v[152:155], v[202:205], v[44:47]
	v_mfma_f32_16x16x32_bf16 v[36:39], v[144:147], v[210:213], v[36:39]
	v_mfma_f32_16x16x32_bf16 v[28:31], v[152:155], v[210:213], v[28:31]
	v_mfma_f32_16x16x32_bf16 v[20:23], v[144:147], v[220:223], v[20:23]
	v_mfma_f32_16x16x32_bf16 v[12:15], v[152:155], v[220:223], v[12:15]
	v_mfma_f32_16x16x32_bf16 v[4:7], v[144:147], v[228:231], v[4:7]
	v_mfma_f32_16x16x32_bf16 v[0:3], v[152:155], v[228:231], v[0:3]
	v_mfma_f32_16x16x32_bf16 v[52:55], v[148:151], v[206:209], v[52:55]
	v_mfma_f32_16x16x32_bf16 v[44:47], v[156:159], v[206:209], v[44:47]
	v_mfma_f32_16x16x32_bf16 v[36:39], v[148:151], v[214:217], v[36:39]
	v_mfma_f32_16x16x32_bf16 v[28:31], v[156:159], v[214:217], v[28:31]
	v_mfma_f32_16x16x32_bf16 v[20:23], v[148:151], v[224:227], v[20:23]
	v_mfma_f32_16x16x32_bf16 v[12:15], v[156:159], v[224:227], v[12:15]
	v_mfma_f32_16x16x32_bf16 v[4:7], v[148:151], v[232:235], v[4:7]
	v_mfma_f32_16x16x32_bf16 v[0:3], v[156:159], v[232:235], v[0:3]
	s_setprio 0
	s_barrier
	s_add_i32 s68, s68, 2
	s_add_u32 s91, s91, 0x10000
	s_addc_u32 s92, s92, 0
	s_add_u32 s0, s0, 0x100
	s_addc_u32 s1, s1, 0
	s_cmp_gt_u32 s68, 13

; #define PG8_STAGE(bufoff, gbase, voff) do { _Pragma("unroll") for (int _i = 0; _i < 2; ++_i) \
;         __builtin_amdgcn_global_load_lds((const unsigned*)((const char*)(gbase) + (voff)[_i]), (PG8_LAS unsigned*)(lds + (bufoff) + ldsw + _i * 8192), 16, 0, 0); } while (0)
; #define PG8_LDA(dst, b, h) do { _Pragma("unroll") for (int m = 0; m < 4; ++m) _Pragma("unroll") for (int k = 0; k < 2; ++k) dst[m][k] = *(const PG8_LAS bf16x8*)(lds + PG8_SA(b, h) + aoff + m * 2048 + k * 1024); } while (0)
; #define PG8_LDB(dst, b, h) do { _Pragma("unroll") for (int n = 0; n < 2; ++n) _Pragma("unroll") for (int k = 0; k < 2; ++k) dst[n][k] = *(const PG8_LAS bf16x8*)(lds + PG8_SB(b, h) + boff + n * 2048 + k * 1024); } while (0)
; #define PG8_MMA(ai, bj, At, Bt) do { __builtin_amdgcn_s_setprio(1); _Pragma("unroll") for (int m = 0; m < 4; ++m) _Pragma("unroll") for (int n = 0; n < 2; ++n) _Pragma("unroll") for (int k = 0; k < 2; ++k) \
;         acc[ai][bj][m][n] = __builtin_amdgcn_mfma_f32_16x16x32_bf16(Bt[n][k], At[m][k], acc[ai][bj][m][n], 0, 0, 0); __builtin_amdgcn_s_setprio(0); } while (0)
; #define PG8_WAIT_V(n) asm volatile("s_waitcnt vmcnt(" #n ")" ::: "memory")
; #define PG8_WAIT_L(n) asm volatile("s_waitcnt lgkmcnt(" #n ")" ::: "memory")
; #define PG8_BAR __builtin_amdgcn_s_barrier()
; #define PG8_SCHED __builtin_amdgcn_sched_barrier(0)
; template <class Epi, class Sched, bool ALIGN_EPI = false, bool SP2 = false>
; __device__ __forceinline__ void gemm_phase(PG8_LAS unsigned char* lds, const Gemm g, const Sched& S, const Epi& E) {
;     ...
;             PG8_LDB(B0, 0, 0); PG8_LDB(B1, 0, 1); PG8_SCHED; PG8_LDA(At, 0, 0); PG8_STAGE(PG8_SA(1, 1), a1 + hstepA, voffA);
;             PG8_WAIT_V(8); PG8_WAIT_L(0); PG8_BAR; PG8_MMA(0, 0, At, B0); PG8_MMA(0, 1, At, B1); PG8_BAR; PG8_SCHED;
;             PG8_LDA(At, 0, 1); PG8_STAGE(PG8_SB(0, 0), b2, voffB); PG8_STAGE(PG8_SB(0, 1), b2 + hstepB, voffB); PG8_STAGE(PG8_SA(0, 0), a2, voffA);
;     ...
; #pragma unroll
;         for (int a = 0; a < 2; ++a)
; #pragma unroll
;             for (int b = 0; b < 2; ++b)
; #pragma unroll
;                 for (int m = 0; m < 4; ++m)
; #pragma unroll
;                     for (int n = 0; n < 2; ++n) acc[a][b][m][n] = (f32x4){0.f, 0.f, 0.f, 0.f};
;         cur = nxt; cA = nA; cB = nB; ++ui;
.LBB0_669:
	s_ashr_i32 s57, s56, 31
	s_lshl_b64 s[8:9], s[56:57], 18
	s_add_u32 s58, s30, s8
	s_addc_u32 s59, s31, s9
	s_and_b64 s[8:9], s[2:3], exec
	s_cselect_b32 s57, s59, s67
	s_cselect_b32 s68, s58, s66
	s_ashr_i32 s55, s54, 31
	s_lshl_b64 s[8:9], s[54:55], 18
	v_readlane_b32 s60, v246, 7
	v_readlane_b32 s61, v246, 8
	s_add_u32 s60, s60, s8
	s_addc_u32 s61, s61, s9
	s_and_b64 s[8:9], s[2:3], exec
	s_cselect_b32 s55, s61, s65
	s_cselect_b32 s69, s60, s64
	s_add_u32 s82, s64, 0x10000
	s_addc_u32 s85, s65, 0
	s_add_u32 s64, s66, 0x20080
	s_addc_u32 s65, s67, 0
	s_mov_b32 s86, -2
	ds_read_b128 v[108:111], v200
	ds_read_b128 v[132:135], v200 offset:1024
	ds_read_b128 v[136:139], v200 offset:2048
	ds_read_b128 v[140:143], v200 offset:3072
	ds_read_b128 v[144:147], v201
	ds_read_b128 v[148:151], v201 offset:1024
	ds_read_b128 v[152:155], v201 offset:2048
	ds_read_b128 v[156:159], v201 offset:3072
	s_add_u32 s8, s64, 0xfffe0080
	s_addc_u32 s9, s65, -1
	s_cmp_eq_u32 s86, 4
	s_cselect_b32 s67, s57, s9
	s_cselect_b32 s66, s68, s8
	s_cselect_b32 s9, s55, s85
	s_cselect_b32 s8, s69, s82
	v_lshl_add_u64 v[216:217], s[64:65], 0, v[186:187]
	s_add_i32 m0, s17, 0xc000
	ds_read_b128 v[160:163], v202
	ds_read_b128 v[164:167], v202 offset:1024
	ds_read_b128 v[168:171], v202 offset:2048
	ds_read_b128 v[204:207], v202 offset:3072
	ds_read_b128 v[208:211], v202 offset:4096
	ds_read_b128 v[212:215], v202 offset:5120
	ds_read_b128 v[220:223], v202 offset:6144
	ds_read_b128 v[224:227], v202 offset:7168
	global_load_lds_dwordx4 v[216:217], off
	v_lshl_add_u64 v[216:217], s[64:65], 0, v[192:193]
	s_add_i32 m0, s17, 0xe000
	s_nop 0
	global_load_lds_dwordx4 v[216:217], off
	s_waitcnt vmcnt(8)
	s_waitcnt lgkmcnt(0)
	s_barrier
	s_setprio 1
	s_waitcnt lgkmcnt(0)
	v_mfma_f32_16x16x32_bf16 v[128:131], v[108:111], v[160:163], 0
	v_mfma_f32_16x16x32_bf16 v[124:127], v[136:139], v[160:163], 0
	v_mfma_f32_16x16x32_bf16 v[112:115], v[108:111], v[168:171], 0
	v_mfma_f32_16x16x32_bf16 v[104:107], v[136:139], v[168:171], 0
	v_mfma_f32_16x16x32_bf16 v[92:95], v[108:111], v[208:211], 0
	v_mfma_f32_16x16x32_bf16 v[88:91], v[136:139], v[208:211], 0
	v_mfma_f32_16x16x32_bf16 v[76:79], v[108:111], v[220:223], 0
	v_mfma_f32_16x16x32_bf16 v[72:75], v[136:139], v[220:223], 0
	v_mfma_f32_16x16x32_bf16 v[128:131], v[132:135], v[164:167], v[128:131]
	v_mfma_f32_16x16x32_bf16 v[124:127], v[140:143], v[164:167], v[124:127]
	v_mfma_f32_16x16x32_bf16 v[112:115], v[132:135], v[204:207], v[112:115]
	v_mfma_f32_16x16x32_bf16 v[104:107], v[140:143], v[204:207], v[104:107]
	v_mfma_f32_16x16x32_bf16 v[92:95], v[132:135], v[212:215], v[92:95]
	v_mfma_f32_16x16x32_bf16 v[88:91], v[140:143], v[212:215], v[88:91]
	v_mfma_f32_16x16x32_bf16 v[76:79], v[132:135], v[224:227], v[76:79]
	v_mfma_f32_16x16x32_bf16 v[72:75], v[140:143], v[224:227], v[72:75]
	s_setprio 0
	s_setprio 1
	v_mfma_f32_16x16x32_bf16 v[120:123], v[144:147], v[160:163], 0
	v_mfma_f32_16x16x32_bf16 v[116:119], v[152:155], v[160:163], 0
	v_mfma_f32_16x16x32_bf16 v[100:103], v[144:147], v[168:171], 0
	v_mfma_f32_16x16x32_bf16 v[96:99], v[152:155], v[168:171], 0
	v_mfma_f32_16x16x32_bf16 v[84:87], v[144:147], v[208:211], 0
	v_mfma_f32_16x16x32_bf16 v[80:83], v[152:155], v[208:211], 0
	v_mfma_f32_16x16x32_bf16 v[68:71], v[144:147], v[220:223], 0
	v_mfma_f32_16x16x32_bf16 v[64:67], v[152:155], v[220:223], 0
	v_mfma_f32_16x16x32_bf16 v[120:123], v[148:151], v[164:167], v[120:123]
	v_mfma_f32_16x16x32_bf16 v[116:119], v[156:159], v[164:167], v[116:119]
	v_mfma_f32_16x16x32_bf16 v[100:103], v[148:151], v[204:207], v[100:103]
	v_mfma_f32_16x16x32_bf16 v[96:99], v[156:159], v[204:207], v[96:99]
	v_mfma_f32_16x16x32_bf16 v[84:87], v[148:151], v[212:215], v[84:87]
	v_mfma_f32_16x16x32_bf16 v[80:83], v[156:159], v[212:215], v[80:83]
	v_mfma_f32_16x16x32_bf16 v[68:71], v[148:151], v[224:227], v[68:71]
	v_mfma_f32_16x16x32_bf16 v[64:67], v[156:159], v[224:227], v[64:67]
	s_setprio 0
	s_barrier
	v_lshl_add_u64 v[216:217], s[8:9], 0, v[190:191]
	s_add_i32 s8, s11, s15
	s_mov_b32 m0, s8
	ds_read_b128 v[160:163], v202 offset:16384
	ds_read_b128 v[164:167], v202 offset:17408
	ds_read_b128 v[168:171], v202 offset:18432
	ds_read_b128 v[204:207], v202 offset:19456
	ds_read_b128 v[208:211], v202 offset:20480
	ds_read_b128 v[212:215], v202 offset:21504
	ds_read_b128 v[220:223], v202 offset:22528
	ds_read_b128 v[224:227], v202 offset:23552
	global_load_lds_dwordx4 v[216:217], off
	v_lshl_add_u64 v[228:229], v[216:217], 0, s[0:1]
	s_add_i32 m0, s8, 0x2000
	s_add_i32 s8, s80, s15
	global_load_lds_dwordx4 v[228:229], off
	v_lshl_add_u64 v[228:229], v[216:217], 0, s[34:35]
	s_mov_b32 m0, s8
	v_lshl_add_u64 v[230:231], s[66:67], 0, v[174:175]
	global_load_lds_dwordx4 v[228:229], off
	v_lshl_add_u64 v[228:229], v[216:217], 0, s[36:37]
	s_add_i32 m0, s8, 0x2000
	s_nop 0
	global_load_lds_dwordx4 v[228:229], off
	v_lshl_add_u64 v[228:229], s[66:67], 0, v[172:173]
	s_mov_b32 m0, s17
	s_nop 0
	global_load_lds_dwordx4 v[228:229], off
	s_mov_b32 m0, s18
	s_nop 0
	global_load_lds_dwordx4 v[230:231], off
	s_waitcnt vmcnt(8)
	s_waitcnt lgkmcnt(0)
	s_barrier
; #define PG8_STAGE(bufoff, gbase, voff) do { _Pragma("unroll") for (int _i = 0; _i < 2; ++_i) \
;         __builtin_amdgcn_global_load_lds((const unsigned*)((const char*)(gbase) + (voff)[_i]), (PG8_LAS unsigned*)(lds + (bufoff) + ldsw + _i * 8192), 16, 0, 0); } while (0)
; #define PG8_LDA(dst, b, h) do { _Pragma("unroll") for (int m = 0; m < 4; ++m) _Pragma("unroll") for (int k = 0; k < 2; ++k) dst[m][k] = *(const PG8_LAS bf16x8*)(lds + PG8_SA(b, h) + aoff + m * 2048 + k * 1024); } while (0)
; #define PG8_LDB(dst, b, h) do { _Pragma("unroll") for (int n = 0; n < 2; ++n) _Pragma("unroll") for (int k = 0; k < 2; ++k) dst[n][k] = *(const PG8_LAS bf16x8*)(lds + PG8_SB(b, h) + boff + n * 2048 + k * 1024); } while (0)
; #define PG8_MMA(ai, bj, At, Bt) do { __builtin_amdgcn_s_setprio(1); _Pragma("unroll") for (int m = 0; m < 4; ++m) _Pragma("unroll") for (int n = 0; n < 2; ++n) _Pragma("unroll") for (int k = 0; k < 2; ++k) \
;         acc[ai][bj][m][n] = __builtin_amdgcn_mfma_f32_16x16x32_bf16(Bt[n][k], At[m][k], acc[ai][bj][m][n], 0, 0, 0); __builtin_amdgcn_s_setprio(0); } while (0)
; #define PG8_WAIT_V(n) asm volatile("s_waitcnt vmcnt(" #n ")" ::: "memory")
; #define PG8_WAIT_L(n) asm volatile("s_waitcnt lgkmcnt(" #n ")" ::: "memory")
; #define PG8_BAR __builtin_amdgcn_s_barrier()
; #define PG8_SCHED __builtin_amdgcn_sched_barrier(0)
; template <class Epi, class Sched, bool ALIGN_EPI = false, bool SP2 = false>
; __device__ __forceinline__ void gemm_phase(PG8_LAS unsigned char* lds, const Gemm g, const Sched& S, const Epi& E) {
;     ...
;             PG8_WAIT_V(8); PG8_WAIT_L(0); PG8_BAR; PG8_MMA(1, 0, At, B0); PG8_MMA(1, 1, At, B1); PG8_BAR; PG8_SCHED;
;             PG8_LDB(B0, 1, 0); PG8_LDB(B1, 1, 1); PG8_SCHED; PG8_LDA(At, 1, 0); PG8_STAGE(PG8_SA(0, 1), a2 + hstepA, voffA);
;             PG8_WAIT_V(8); PG8_WAIT_L(0); PG8_BAR; PG8_MMA(0, 0, At, B0); PG8_MMA(0, 1, At, B1); PG8_BAR; PG8_SCHED;
	s_setprio 1
	s_waitcnt lgkmcnt(0)
	v_mfma_f32_16x16x32_bf16 v[60:63], v[108:111], v[160:163], 0
	v_mfma_f32_16x16x32_bf16 v[56:59], v[136:139], v[160:163], 0
	v_mfma_f32_16x16x32_bf16 v[44:47], v[108:111], v[168:171], 0
	v_mfma_f32_16x16x32_bf16 v[40:43], v[136:139], v[168:171], 0
	v_mfma_f32_16x16x32_bf16 v[28:31], v[108:111], v[208:211], 0
	v_mfma_f32_16x16x32_bf16 v[24:27], v[136:139], v[208:211], 0
	v_mfma_f32_16x16x32_bf16 v[12:15], v[108:111], v[220:223], 0
	v_mfma_f32_16x16x32_bf16 v[8:11], v[136:139], v[220:223], 0
	v_mfma_f32_16x16x32_bf16 v[60:63], v[132:135], v[164:167], v[60:63]
	v_mfma_f32_16x16x32_bf16 v[56:59], v[140:143], v[164:167], v[56:59]
	v_mfma_f32_16x16x32_bf16 v[44:47], v[132:135], v[204:207], v[44:47]
	v_mfma_f32_16x16x32_bf16 v[40:43], v[140:143], v[204:207], v[40:43]
	v_mfma_f32_16x16x32_bf16 v[28:31], v[132:135], v[212:215], v[28:31]
	v_mfma_f32_16x16x32_bf16 v[24:27], v[140:143], v[212:215], v[24:27]
	v_mfma_f32_16x16x32_bf16 v[12:15], v[132:135], v[224:227], v[12:15]
	v_mfma_f32_16x16x32_bf16 v[8:11], v[140:143], v[224:227], v[8:11]
	s_setprio 0
	s_setprio 1
	v_mfma_f32_16x16x32_bf16 v[52:55], v[144:147], v[160:163], 0
	v_mfma_f32_16x16x32_bf16 v[48:51], v[152:155], v[160:163], 0
	v_mfma_f32_16x16x32_bf16 v[36:39], v[144:147], v[168:171], 0
	v_mfma_f32_16x16x32_bf16 v[32:35], v[152:155], v[168:171], 0
	v_mfma_f32_16x16x32_bf16 v[20:23], v[144:147], v[208:211], 0
	v_mfma_f32_16x16x32_bf16 v[16:19], v[152:155], v[208:211], 0
	v_mfma_f32_16x16x32_bf16 v[4:7], v[144:147], v[220:223], 0
	v_mfma_f32_16x16x32_bf16 v[0:3], v[152:155], v[220:223], 0
	v_mfma_f32_16x16x32_bf16 v[52:55], v[148:151], v[164:167], v[52:55]
	v_mfma_f32_16x16x32_bf16 v[48:51], v[156:159], v[164:167], v[48:51]
	v_mfma_f32_16x16x32_bf16 v[36:39], v[148:151], v[204:207], v[36:39]
	v_mfma_f32_16x16x32_bf16 v[32:35], v[156:159], v[204:207], v[32:35]
	v_mfma_f32_16x16x32_bf16 v[20:23], v[148:151], v[212:215], v[20:23]
	v_mfma_f32_16x16x32_bf16 v[16:19], v[156:159], v[212:215], v[16:19]
	v_mfma_f32_16x16x32_bf16 v[4:7], v[148:151], v[224:227], v[4:7]
	v_mfma_f32_16x16x32_bf16 v[0:3], v[156:159], v[224:227], v[0:3]
	s_setprio 0
	s_barrier
	s_add_i32 s78, 0, 0x1c000
	v_add_u32_e32 v156, s78, v199
	ds_read_b128 v[108:111], v203
	ds_read_b128 v[132:135], v203 offset:1024
	ds_read_b128 v[136:139], v203 offset:2048
	ds_read_b128 v[140:143], v203 offset:3072
	ds_read_b128 v[144:147], v156
	ds_read_b128 v[148:151], v156 offset:1024
	ds_read_b128 v[152:155], v156 offset:2048
	ds_read_b128 v[156:159], v156 offset:3072
	s_add_u32 s8, s66, 0x20000
	s_addc_u32 s9, s67, 0
	s_mov_b32 m0, s19
	v_lshl_add_u64 v[232:233], s[8:9], 0, v[172:173]
	ds_read_b128 v[160:163], v202 offset:32768
	ds_read_b128 v[164:167], v202 offset:33792
	ds_read_b128 v[168:171], v202 offset:34816
	ds_read_b128 v[204:207], v202 offset:35840
	ds_read_b128 v[208:211], v202 offset:36864
	ds_read_b128 v[212:215], v202 offset:37888
	ds_read_b128 v[220:223], v202 offset:38912
	ds_read_b128 v[224:227], v202 offset:39936
	global_load_lds_dwordx4 v[232:233], off
	v_lshl_add_u64 v[232:233], s[8:9], 0, v[174:175]
	s_mov_b32 m0, s70
	s_nop 0
	global_load_lds_dwordx4 v[232:233], off
	s_waitcnt vmcnt(8)
	s_waitcnt lgkmcnt(0)
	s_barrier
	s_setprio 1
	s_waitcnt lgkmcnt(0)
	v_mfma_f32_16x16x32_bf16 v[128:131], v[108:111], v[160:163], v[128:131]
	v_mfma_f32_16x16x32_bf16 v[124:127], v[136:139], v[160:163], v[124:127]
	v_mfma_f32_16x16x32_bf16 v[112:115], v[108:111], v[168:171], v[112:115]
	v_mfma_f32_16x16x32_bf16 v[104:107], v[136:139], v[168:171], v[104:107]
	v_mfma_f32_16x16x32_bf16 v[92:95], v[108:111], v[208:211], v[92:95]
	v_mfma_f32_16x16x32_bf16 v[88:91], v[136:139], v[208:211], v[88:91]
	v_mfma_f32_16x16x32_bf16 v[76:79], v[108:111], v[220:223], v[76:79]
	v_mfma_f32_16x16x32_bf16 v[72:75], v[136:139], v[220:223], v[72:75]
	v_mfma_f32_16x16x32_bf16 v[128:131], v[132:135], v[164:167], v[128:131]
	v_mfma_f32_16x16x32_bf16 v[124:127], v[140:143], v[164:167], v[124:127]
	v_mfma_f32_16x16x32_bf16 v[112:115], v[132:135], v[204:207], v[112:115]
	v_mfma_f32_16x16x32_bf16 v[104:107], v[140:143], v[204:207], v[104:107]
	v_mfma_f32_16x16x32_bf16 v[92:95], v[132:135], v[212:215], v[92:95]
	v_mfma_f32_16x16x32_bf16 v[88:91], v[140:143], v[212:215], v[88:91]
	v_mfma_f32_16x16x32_bf16 v[76:79], v[132:135], v[224:227], v[76:79]
	v_mfma_f32_16x16x32_bf16 v[72:75], v[140:143], v[224:227], v[72:75]
	s_setprio 0
	s_setprio 1
	v_mfma_f32_16x16x32_bf16 v[120:123], v[144:147], v[160:163], v[120:123]
	v_mfma_f32_16x16x32_bf16 v[116:119], v[152:155], v[160:163], v[116:119]
	v_mfma_f32_16x16x32_bf16 v[100:103], v[144:147], v[168:171], v[100:103]
	v_mfma_f32_16x16x32_bf16 v[96:99], v[152:155], v[168:171], v[96:99]
	v_mfma_f32_16x16x32_bf16 v[84:87], v[144:147], v[208:211], v[84:87]
	v_mfma_f32_16x16x32_bf16 v[80:83], v[152:155], v[208:211], v[80:83]
	v_mfma_f32_16x16x32_bf16 v[68:71], v[144:147], v[220:223], v[68:71]
	v_mfma_f32_16x16x32_bf16 v[64:67], v[152:155], v[220:223], v[64:67]
	v_mfma_f32_16x16x32_bf16 v[120:123], v[148:151], v[164:167], v[120:123]
	v_mfma_f32_16x16x32_bf16 v[116:119], v[156:159], v[164:167], v[116:119]
	v_mfma_f32_16x16x32_bf16 v[100:103], v[148:151], v[204:207], v[100:103]
	v_mfma_f32_16x16x32_bf16 v[96:99], v[156:159], v[204:207], v[96:99]
	v_mfma_f32_16x16x32_bf16 v[84:87], v[148:151], v[212:215], v[84:87]
	v_mfma_f32_16x16x32_bf16 v[80:83], v[156:159], v[212:215], v[80:83]
	v_mfma_f32_16x16x32_bf16 v[68:71], v[148:151], v[224:227], v[68:71]
	v_mfma_f32_16x16x32_bf16 v[64:67], v[156:159], v[224:227], v[64:67]
	s_setprio 0
	s_barrier
; #define PG8_STAGE(bufoff, gbase, voff) do { _Pragma("unroll") for (int _i = 0; _i < 2; ++_i) \
;         __builtin_amdgcn_global_load_lds((const unsigned*)((const char*)(gbase) + (voff)[_i]), (PG8_LAS unsigned*)(lds + (bufoff) + ldsw + _i * 8192), 16, 0, 0); } while (0)
; #define PG8_LDA(dst, b, h) do { _Pragma("unroll") for (int m = 0; m < 4; ++m) _Pragma("unroll") for (int k = 0; k < 2; ++k) dst[m][k] = *(const PG8_LAS bf16x8*)(lds + PG8_SA(b, h) + aoff + m * 2048 + k * 1024); } while (0)
; #define PG8_MMA(ai, bj, At, Bt) do { __builtin_amdgcn_s_setprio(1); _Pragma("unroll") for (int m = 0; m < 4; ++m) _Pragma("unroll") for (int n = 0; n < 2; ++n) _Pragma("unroll") for (int k = 0; k < 2; ++k) \
;         acc[ai][bj][m][n] = __builtin_amdgcn_mfma_f32_16x16x32_bf16(Bt[n][k], At[m][k], acc[ai][bj][m][n], 0, 0, 0); __builtin_amdgcn_s_setprio(0); } while (0)
; #define PG8_WAIT_V(n) asm volatile("s_waitcnt vmcnt(" #n ")" ::: "memory")
; #define PG8_WAIT_L(n) asm volatile("s_waitcnt lgkmcnt(" #n ")" ::: "memory")
; #define PG8_BAR __builtin_amdgcn_s_barrier()
; #define PG8_SCHED __builtin_amdgcn_sched_barrier(0)
; template <class Epi, class Sched, bool ALIGN_EPI = false, bool SP2 = false>
; __device__ __forceinline__ void gemm_phase(PG8_LAS unsigned char* lds, const Gemm g, const Sched& S, const Epi& E) {
;     ...
;             PG8_LDA(At, 1, 1); PG8_STAGE(PG8_SB(1, 0), b3, voffB); PG8_STAGE(PG8_SB(1, 1), b3 + hstepB, voffB); PG8_STAGE(PG8_SA(1, 0), a3, voffA);
;             PG8_WAIT_V(8); PG8_WAIT_L(0); PG8_BAR; PG8_MMA(1, 0, At, B0); PG8_MMA(1, 1, At, B1); PG8_BAR; PG8_SCHED;
	s_add_i32 s8, s81, s15
	v_lshl_add_u64 v[232:233], v[216:217], 0, s[38:39]
	s_mov_b32 m0, s8
	ds_read_b128 v[160:163], v202 offset:49152
	ds_read_b128 v[164:167], v202 offset:50176
	ds_read_b128 v[168:171], v202 offset:51200
	ds_read_b128 v[204:207], v202 offset:52224
	ds_read_b128 v[208:211], v202 offset:53248
	ds_read_b128 v[212:215], v202 offset:54272
	ds_read_b128 v[220:223], v202 offset:55296
	ds_read_b128 v[224:227], v202 offset:56320
	global_load_lds_dwordx4 v[232:233], off
	v_lshl_add_u64 v[232:233], v[216:217], 0, s[40:41]
	s_add_i32 m0, s8, 0x2000
	s_add_i32 s8, s78, s15
	global_load_lds_dwordx4 v[232:233], off
	v_lshl_add_u64 v[232:233], v[216:217], 0, s[44:45]
	s_mov_b32 m0, s8
	v_lshl_add_u64 v[216:217], v[216:217], 0, s[46:47]
	global_load_lds_dwordx4 v[232:233], off
	s_add_i32 m0, s8, 0x2000
	s_nop 0
	global_load_lds_dwordx4 v[216:217], off
	v_lshl_add_u64 v[216:217], v[228:229], 0, s[42:43]
	s_mov_b32 m0, s71
	s_nop 0
	global_load_lds_dwordx4 v[216:217], off
	v_lshl_add_u64 v[216:217], v[230:231], 0, s[42:43]
	s_mov_b32 m0, s72
	s_nop 0
	global_load_lds_dwordx4 v[216:217], off
	s_waitcnt vmcnt(8)
	s_waitcnt lgkmcnt(0)
	s_barrier
	s_setprio 1
	s_waitcnt lgkmcnt(0)
	v_mfma_f32_16x16x32_bf16 v[60:63], v[108:111], v[160:163], v[60:63]
	v_mfma_f32_16x16x32_bf16 v[56:59], v[136:139], v[160:163], v[56:59]
	v_mfma_f32_16x16x32_bf16 v[44:47], v[108:111], v[168:171], v[44:47]
	v_mfma_f32_16x16x32_bf16 v[40:43], v[136:139], v[168:171], v[40:43]
	v_mfma_f32_16x16x32_bf16 v[28:31], v[108:111], v[208:211], v[28:31]
	v_mfma_f32_16x16x32_bf16 v[24:27], v[136:139], v[208:211], v[24:27]
	v_mfma_f32_16x16x32_bf16 v[12:15], v[108:111], v[220:223], v[12:15]
	v_mfma_f32_16x16x32_bf16 v[8:11], v[136:139], v[220:223], v[8:11]
	v_mfma_f32_16x16x32_bf16 v[60:63], v[132:135], v[164:167], v[60:63]
	v_mfma_f32_16x16x32_bf16 v[56:59], v[140:143], v[164:167], v[56:59]
	v_mfma_f32_16x16x32_bf16 v[44:47], v[132:135], v[204:207], v[44:47]
	v_mfma_f32_16x16x32_bf16 v[40:43], v[140:143], v[204:207], v[40:43]
	v_mfma_f32_16x16x32_bf16 v[28:31], v[132:135], v[212:215], v[28:31]
	v_mfma_f32_16x16x32_bf16 v[24:27], v[140:143], v[212:215], v[24:27]
	v_mfma_f32_16x16x32_bf16 v[12:15], v[132:135], v[224:227], v[12:15]
	v_mfma_f32_16x16x32_bf16 v[8:11], v[140:143], v[224:227], v[8:11]
	s_setprio 0
	s_setprio 1
	v_mfma_f32_16x16x32_bf16 v[52:55], v[144:147], v[160:163], v[52:55]
	v_mfma_f32_16x16x32_bf16 v[48:51], v[152:155], v[160:163], v[48:51]
	v_mfma_f32_16x16x32_bf16 v[36:39], v[144:147], v[168:171], v[36:39]
	v_mfma_f32_16x16x32_bf16 v[32:35], v[152:155], v[168:171], v[32:35]
	v_mfma_f32_16x16x32_bf16 v[20:23], v[144:147], v[208:211], v[20:23]
	v_mfma_f32_16x16x32_bf16 v[16:19], v[152:155], v[208:211], v[16:19]
	v_mfma_f32_16x16x32_bf16 v[4:7], v[144:147], v[220:223], v[4:7]
	v_mfma_f32_16x16x32_bf16 v[0:3], v[152:155], v[220:223], v[0:3]
	v_mfma_f32_16x16x32_bf16 v[52:55], v[148:151], v[164:167], v[52:55]
	v_mfma_f32_16x16x32_bf16 v[48:51], v[156:159], v[164:167], v[48:51]
	v_mfma_f32_16x16x32_bf16 v[36:39], v[148:151], v[204:207], v[36:39]
	v_mfma_f32_16x16x32_bf16 v[32:35], v[156:159], v[204:207], v[32:35]
	v_mfma_f32_16x16x32_bf16 v[20:23], v[148:151], v[212:215], v[20:23]
	v_mfma_f32_16x16x32_bf16 v[16:19], v[156:159], v[212:215], v[16:19]
	v_mfma_f32_16x16x32_bf16 v[4:7], v[148:151], v[224:227], v[4:7]
	v_mfma_f32_16x16x32_bf16 v[0:3], v[156:159], v[224:227], v[0:3]
	s_setprio 0
	s_barrier
	s_add_i32 s86, s86, 2
	s_add_u32 s82, s82, 0x10000
	s_addc_u32 s85, s85, 0
	s_add_u32 s64, s64, 0x100
	s_addc_u32 s65, s65, 0
	s_cmp_gt_u32 s86, 5

; #define PG8_STAGE(bufoff, gbase, voff) do { _Pragma("unroll") for (int _i = 0; _i < 2; ++_i) \
;         __builtin_amdgcn_global_load_lds((const unsigned*)((const char*)(gbase) + (voff)[_i]), (PG8_LAS unsigned*)(lds + (bufoff) + ldsw + _i * 8192), 16, 0, 0); } while (0)
; #define PG8_LDA(dst, b, h) do { _Pragma("unroll") for (int m = 0; m < 4; ++m) _Pragma("unroll") for (int k = 0; k < 2; ++k) dst[m][k] = *(const PG8_LAS bf16x8*)(lds + PG8_SA(b, h) + aoff + m * 2048 + k * 1024); } while (0)
; #define PG8_LDB(dst, b, h) do { _Pragma("unroll") for (int n = 0; n < 2; ++n) _Pragma("unroll") for (int k = 0; k < 2; ++k) dst[n][k] = *(const PG8_LAS bf16x8*)(lds + PG8_SB(b, h) + boff + n * 2048 + k * 1024); } while (0)
; #define PG8_MMA(ai, bj, At, Bt) do { __builtin_amdgcn_s_setprio(1); _Pragma("unroll") for (int m = 0; m < 4; ++m) _Pragma("unroll") for (int n = 0; n < 2; ++n) _Pragma("unroll") for (int k = 0; k < 2; ++k) \
;         acc[ai][bj][m][n] = __builtin_amdgcn_mfma_f32_16x16x32_bf16(Bt[n][k], At[m][k], acc[ai][bj][m][n], 0, 0, 0); __builtin_amdgcn_s_setprio(0); } while (0)
; #define PG8_WAIT_V(n) asm volatile("s_waitcnt vmcnt(" #n ")" ::: "memory")
; #define PG8_WAIT_L(n) asm volatile("s_waitcnt lgkmcnt(" #n ")" ::: "memory")
; #define PG8_BAR __builtin_amdgcn_s_barrier()
; #define PG8_SCHED __builtin_amdgcn_sched_barrier(0)
; template <class Epi, class Sched, bool ALIGN_EPI = false, bool SP2 = false>
; __device__ __forceinline__ void gemm_phase(PG8_LAS unsigned char* lds, const Gemm g, const Sched& S, const Epi& E) {
;     ...
;             PG8_LDB(B0, 0, 0); PG8_LDB(B1, 0, 1); PG8_SCHED; PG8_LDA(At, 0, 0); PG8_STAGE(PG8_SA(1, 1), a1 + hstepA, voffA);
;             PG8_WAIT_V(8); PG8_WAIT_L(0); PG8_BAR; PG8_MMA(0, 0, At, B0); PG8_MMA(0, 1, At, B1); PG8_BAR; PG8_SCHED;
;             PG8_LDA(At, 0, 1); PG8_STAGE(PG8_SB(0, 0), b2, voffB); PG8_STAGE(PG8_SB(0, 1), b2 + hstepB, voffB); PG8_STAGE(PG8_SA(0, 0), a2, voffA);
;     ...
; #pragma unroll
;         for (int a = 0; a < 2; ++a)
; #pragma unroll
;             for (int b = 0; b < 2; ++b)
; #pragma unroll
;                 for (int m = 0; m < 4; ++m)
; #pragma unroll
;                     for (int n = 0; n < 2; ++n) acc[a][b][m][n] = (f32x4){0.f, 0.f, 0.f, 0.f};
;         cur = nxt; cA = nA; cB = nB; ++ui;
.LBB0_750:
	s_ashr_i32 s59, s58, 31
	s_lshl_b64 s[60:61], s[58:59], 19
	s_add_u32 s60, s6, s60
	s_addc_u32 s61, s7, s61
	s_and_b64 s[62:63], s[4:5], exec
	s_cselect_b32 s59, s61, s69
	s_cselect_b32 s65, s60, s68
	s_ashr_i32 s57, s56, 31
	s_lshl_b64 s[62:63], s[56:57], 19
	s_add_u32 s62, s93, s62
	s_addc_u32 s63, s84, s63
	s_and_b64 s[72:73], s[4:5], exec
	s_cselect_b32 s57, s63, s71
	s_cselect_b32 s67, s62, s70
	s_add_u32 s68, s68, 0x10000
	s_addc_u32 s69, s69, 0
	s_add_u32 s70, s70, 0x10000
	s_addc_u32 s71, s71, 0
	s_mov_b32 s72, -2
	s_waitcnt lgkmcnt(0)
	ds_read_b128 v[128:131], v211
	ds_read_b128 v[132:135], v211 offset:1024
	ds_read_b128 v[136:139], v211 offset:2048
	ds_read_b128 v[140:143], v211 offset:3072
	ds_read_b128 v[144:147], v212
	ds_read_b128 v[148:151], v212 offset:1024
	ds_read_b128 v[152:155], v212 offset:2048
	ds_read_b128 v[156:159], v212 offset:3072
	s_cmp_eq_u32 s72, 12
	s_cselect_b32 s79, s59, s69
	s_cselect_b32 s78, s65, s68
	s_cselect_b32 s91, s57, s71
	s_cselect_b32 s90, s67, s70
	v_lshl_add_u64 v[208:209], s[68:69], 0, v[190:191]
	v_lshl_add_u64 v[228:229], v[208:209], 0, s[52:53]
	s_add_i32 m0, s15, 0xc000
	ds_read_b128 v[160:163], v213
	ds_read_b128 v[164:167], v213 offset:1024
	ds_read_b128 v[168:171], v213 offset:2048
	ds_read_b128 v[172:175], v213 offset:3072
	ds_read_b128 v[176:179], v213 offset:4096
	ds_read_b128 v[180:183], v213 offset:5120
	ds_read_b128 v[220:223], v213 offset:6144
	ds_read_b128 v[224:227], v213 offset:7168
	global_load_lds_dwordx4 v[228:229], off
	v_lshl_add_u64 v[208:209], v[208:209], 0, s[54:55]
	s_add_i32 m0, s15, 0xe000
	s_nop 0
	global_load_lds_dwordx4 v[208:209], off
	s_waitcnt vmcnt(8)
	s_waitcnt lgkmcnt(0)
	s_barrier
	s_setprio 1
	s_waitcnt lgkmcnt(0)
	v_mfma_f32_16x16x32_bf16 v[124:127], v[128:131], v[160:163], 0
	v_mfma_f32_16x16x32_bf16 v[120:123], v[136:139], v[160:163], 0
	v_mfma_f32_16x16x32_bf16 v[108:111], v[128:131], v[168:171], 0
	v_mfma_f32_16x16x32_bf16 v[104:107], v[136:139], v[168:171], 0
	v_mfma_f32_16x16x32_bf16 v[92:95], v[128:131], v[176:179], 0
	v_mfma_f32_16x16x32_bf16 v[88:91], v[136:139], v[176:179], 0
	v_mfma_f32_16x16x32_bf16 v[76:79], v[128:131], v[220:223], 0
	v_mfma_f32_16x16x32_bf16 v[72:75], v[136:139], v[220:223], 0
	v_mfma_f32_16x16x32_bf16 v[124:127], v[132:135], v[164:167], v[124:127]
	v_mfma_f32_16x16x32_bf16 v[120:123], v[140:143], v[164:167], v[120:123]
	v_mfma_f32_16x16x32_bf16 v[108:111], v[132:135], v[172:175], v[108:111]
	v_mfma_f32_16x16x32_bf16 v[104:107], v[140:143], v[172:175], v[104:107]
	v_mfma_f32_16x16x32_bf16 v[92:95], v[132:135], v[180:183], v[92:95]
	v_mfma_f32_16x16x32_bf16 v[88:91], v[140:143], v[180:183], v[88:91]
	v_mfma_f32_16x16x32_bf16 v[76:79], v[132:135], v[224:227], v[76:79]
	v_mfma_f32_16x16x32_bf16 v[72:75], v[140:143], v[224:227], v[72:75]
	s_setprio 0
	s_setprio 1
	v_mfma_f32_16x16x32_bf16 v[116:119], v[144:147], v[160:163], 0
	v_mfma_f32_16x16x32_bf16 v[112:115], v[152:155], v[160:163], 0
	v_mfma_f32_16x16x32_bf16 v[100:103], v[144:147], v[168:171], 0
	v_mfma_f32_16x16x32_bf16 v[96:99], v[152:155], v[168:171], 0
	v_mfma_f32_16x16x32_bf16 v[84:87], v[144:147], v[176:179], 0
	v_mfma_f32_16x16x32_bf16 v[80:83], v[152:155], v[176:179], 0
	v_mfma_f32_16x16x32_bf16 v[68:71], v[144:147], v[220:223], 0
	v_mfma_f32_16x16x32_bf16 v[64:67], v[152:155], v[220:223], 0
	v_mfma_f32_16x16x32_bf16 v[116:119], v[148:151], v[164:167], v[116:119]
	v_mfma_f32_16x16x32_bf16 v[112:115], v[156:159], v[164:167], v[112:115]
	v_mfma_f32_16x16x32_bf16 v[100:103], v[148:151], v[172:175], v[100:103]
	v_mfma_f32_16x16x32_bf16 v[96:99], v[156:159], v[172:175], v[96:99]
	v_mfma_f32_16x16x32_bf16 v[84:87], v[148:151], v[180:183], v[84:87]
	v_mfma_f32_16x16x32_bf16 v[80:83], v[156:159], v[180:183], v[80:83]
	v_mfma_f32_16x16x32_bf16 v[68:71], v[148:151], v[224:227], v[68:71]
	v_mfma_f32_16x16x32_bf16 v[64:67], v[156:159], v[224:227], v[64:67]
	s_setprio 0
	s_barrier
	s_add_i32 s73, s85, s14
	v_lshl_add_u64 v[208:209], s[90:91], 0, v[190:191]
	s_mov_b32 m0, s73
	ds_read_b128 v[160:163], v213 offset:16384
	ds_read_b128 v[164:167], v213 offset:17408
	ds_read_b128 v[168:171], v213 offset:18432
	ds_read_b128 v[172:175], v213 offset:19456
	ds_read_b128 v[176:179], v213 offset:20480
	ds_read_b128 v[180:183], v213 offset:21504
	ds_read_b128 v[220:223], v213 offset:22528
	ds_read_b128 v[224:227], v213 offset:23552
	global_load_lds_dwordx4 v[208:209], off
	v_lshl_add_u64 v[228:229], v[208:209], 0, s[10:11]
	s_add_i32 m0, s73, 0x2000
	s_add_i32 s73, s86, s14
	global_load_lds_dwordx4 v[228:229], off
	v_lshl_add_u64 v[228:229], v[208:209], 0, s[34:35]
	s_mov_b32 m0, s73
	s_nop 0
	global_load_lds_dwordx4 v[228:229], off
	v_lshl_add_u64 v[228:229], v[208:209], 0, s[36:37]
	s_add_i32 m0, s73, 0x2000
	s_nop 0
	global_load_lds_dwordx4 v[228:229], off
	v_lshl_add_u64 v[228:229], s[78:79], 0, v[190:191]
	s_mov_b32 m0, s15
	v_lshl_add_u64 v[230:231], v[228:229], 0, s[10:11]
	global_load_lds_dwordx4 v[228:229], off
	s_mov_b32 m0, s17
	s_nop 0
	global_load_lds_dwordx4 v[230:231], off
	s_waitcnt vmcnt(8)
	s_waitcnt lgkmcnt(0)
	s_barrier
; #define PG8_STAGE(bufoff, gbase, voff) do { _Pragma("unroll") for (int _i = 0; _i < 2; ++_i) \
;         __builtin_amdgcn_global_load_lds((const unsigned*)((const char*)(gbase) + (voff)[_i]), (PG8_LAS unsigned*)(lds + (bufoff) + ldsw + _i * 8192), 16, 0, 0); } while (0)
; #define PG8_LDA(dst, b, h) do { _Pragma("unroll") for (int m = 0; m < 4; ++m) _Pragma("unroll") for (int k = 0; k < 2; ++k) dst[m][k] = *(const PG8_LAS bf16x8*)(lds + PG8_SA(b, h) + aoff + m * 2048 + k * 1024); } while (0)
; #define PG8_LDB(dst, b, h) do { _Pragma("unroll") for (int n = 0; n < 2; ++n) _Pragma("unroll") for (int k = 0; k < 2; ++k) dst[n][k] = *(const PG8_LAS bf16x8*)(lds + PG8_SB(b, h) + boff + n * 2048 + k * 1024); } while (0)
; #define PG8_MMA(ai, bj, At, Bt) do { __builtin_amdgcn_s_setprio(1); _Pragma("unroll") for (int m = 0; m < 4; ++m) _Pragma("unroll") for (int n = 0; n < 2; ++n) _Pragma("unroll") for (int k = 0; k < 2; ++k) \
;         acc[ai][bj][m][n] = __builtin_amdgcn_mfma_f32_16x16x32_bf16(Bt[n][k], At[m][k], acc[ai][bj][m][n], 0, 0, 0); __builtin_amdgcn_s_setprio(0); } while (0)
; #define PG8_WAIT_V(n) asm volatile("s_waitcnt vmcnt(" #n ")" ::: "memory")
; #define PG8_WAIT_L(n) asm volatile("s_waitcnt lgkmcnt(" #n ")" ::: "memory")
; #define PG8_BAR __builtin_amdgcn_s_barrier()
; #define PG8_SCHED __builtin_amdgcn_sched_barrier(0)
; template <class Epi, class Sched, bool ALIGN_EPI = false, bool SP2 = false>
; __device__ __forceinline__ void gemm_phase(PG8_LAS unsigned char* lds, const Gemm g, const Sched& S, const Epi& E) {
;     ...
;             PG8_WAIT_V(8); PG8_WAIT_L(0); PG8_BAR; PG8_MMA(1, 0, At, B0); PG8_MMA(1, 1, At, B1); PG8_BAR; PG8_SCHED;
;             PG8_LDB(B0, 1, 0); PG8_LDB(B1, 1, 1); PG8_SCHED; PG8_LDA(At, 1, 0); PG8_STAGE(PG8_SA(0, 1), a2 + hstepA, voffA);
;             PG8_WAIT_V(8); PG8_WAIT_L(0); PG8_BAR; PG8_MMA(0, 0, At, B0); PG8_MMA(0, 1, At, B1); PG8_BAR; PG8_SCHED;
	s_setprio 1
	s_waitcnt lgkmcnt(0)
	v_mfma_f32_16x16x32_bf16 v[60:63], v[128:131], v[160:163], 0
	v_mfma_f32_16x16x32_bf16 v[56:59], v[136:139], v[160:163], 0
	v_mfma_f32_16x16x32_bf16 v[44:47], v[128:131], v[168:171], 0
	v_mfma_f32_16x16x32_bf16 v[40:43], v[136:139], v[168:171], 0
	v_mfma_f32_16x16x32_bf16 v[28:31], v[128:131], v[176:179], 0
	v_mfma_f32_16x16x32_bf16 v[24:27], v[136:139], v[176:179], 0
	v_mfma_f32_16x16x32_bf16 v[12:15], v[128:131], v[220:223], 0
	v_mfma_f32_16x16x32_bf16 v[8:11], v[136:139], v[220:223], 0
	v_mfma_f32_16x16x32_bf16 v[60:63], v[132:135], v[164:167], v[60:63]
	v_mfma_f32_16x16x32_bf16 v[56:59], v[140:143], v[164:167], v[56:59]
	v_mfma_f32_16x16x32_bf16 v[44:47], v[132:135], v[172:175], v[44:47]
	v_mfma_f32_16x16x32_bf16 v[40:43], v[140:143], v[172:175], v[40:43]
	v_mfma_f32_16x16x32_bf16 v[28:31], v[132:135], v[180:183], v[28:31]
	v_mfma_f32_16x16x32_bf16 v[24:27], v[140:143], v[180:183], v[24:27]
	v_mfma_f32_16x16x32_bf16 v[12:15], v[132:135], v[224:227], v[12:15]
	v_mfma_f32_16x16x32_bf16 v[8:11], v[140:143], v[224:227], v[8:11]
	s_setprio 0
	s_setprio 1
	v_mfma_f32_16x16x32_bf16 v[52:55], v[144:147], v[160:163], 0
	v_mfma_f32_16x16x32_bf16 v[48:51], v[152:155], v[160:163], 0
	v_mfma_f32_16x16x32_bf16 v[36:39], v[144:147], v[168:171], 0
	v_mfma_f32_16x16x32_bf16 v[32:35], v[152:155], v[168:171], 0
	v_mfma_f32_16x16x32_bf16 v[20:23], v[144:147], v[176:179], 0
	v_mfma_f32_16x16x32_bf16 v[16:19], v[152:155], v[176:179], 0
	v_mfma_f32_16x16x32_bf16 v[4:7], v[144:147], v[220:223], 0
	v_mfma_f32_16x16x32_bf16 v[0:3], v[152:155], v[220:223], 0
	v_mfma_f32_16x16x32_bf16 v[52:55], v[148:151], v[164:167], v[52:55]
	v_mfma_f32_16x16x32_bf16 v[48:51], v[156:159], v[164:167], v[48:51]
	v_mfma_f32_16x16x32_bf16 v[36:39], v[148:151], v[172:175], v[36:39]
	v_mfma_f32_16x16x32_bf16 v[32:35], v[156:159], v[172:175], v[32:35]
	v_mfma_f32_16x16x32_bf16 v[20:23], v[148:151], v[180:183], v[20:23]
	v_mfma_f32_16x16x32_bf16 v[16:19], v[156:159], v[180:183], v[16:19]
	v_mfma_f32_16x16x32_bf16 v[4:7], v[148:151], v[224:227], v[4:7]
	v_mfma_f32_16x16x32_bf16 v[0:3], v[156:159], v[224:227], v[0:3]
	s_setprio 0
	s_barrier
	ds_read_b128 v[128:131], v214
	ds_read_b128 v[132:135], v214 offset:1024
	ds_read_b128 v[136:139], v214 offset:2048
	ds_read_b128 v[140:143], v214 offset:3072
	ds_read_b128 v[144:147], v215
	ds_read_b128 v[148:151], v215 offset:1024
	ds_read_b128 v[152:155], v215 offset:2048
	ds_read_b128 v[156:159], v215 offset:3072
	s_mov_b32 m0, s18
	v_lshl_add_u64 v[230:231], v[228:229], 0, s[34:35]
	ds_read_b128 v[160:163], v213 offset:32768
	ds_read_b128 v[164:167], v213 offset:33792
	ds_read_b128 v[168:171], v213 offset:34816
	ds_read_b128 v[172:175], v213 offset:35840
	ds_read_b128 v[176:179], v213 offset:36864
	ds_read_b128 v[180:183], v213 offset:37888
	ds_read_b128 v[220:223], v213 offset:38912
	ds_read_b128 v[224:227], v213 offset:39936
	global_load_lds_dwordx4 v[230:231], off
	v_lshl_add_u64 v[230:231], v[228:229], 0, s[36:37]
	s_mov_b32 m0, s19
	s_nop 0
	global_load_lds_dwordx4 v[230:231], off
	s_waitcnt vmcnt(8)
	s_waitcnt lgkmcnt(0)
	s_barrier
	s_setprio 1
	s_waitcnt lgkmcnt(0)
	v_mfma_f32_16x16x32_bf16 v[124:127], v[128:131], v[160:163], v[124:127]
	v_mfma_f32_16x16x32_bf16 v[120:123], v[136:139], v[160:163], v[120:123]
	v_mfma_f32_16x16x32_bf16 v[108:111], v[128:131], v[168:171], v[108:111]
	v_mfma_f32_16x16x32_bf16 v[104:107], v[136:139], v[168:171], v[104:107]
	v_mfma_f32_16x16x32_bf16 v[92:95], v[128:131], v[176:179], v[92:95]
	v_mfma_f32_16x16x32_bf16 v[88:91], v[136:139], v[176:179], v[88:91]
	v_mfma_f32_16x16x32_bf16 v[76:79], v[128:131], v[220:223], v[76:79]
	v_mfma_f32_16x16x32_bf16 v[72:75], v[136:139], v[220:223], v[72:75]
	v_mfma_f32_16x16x32_bf16 v[124:127], v[132:135], v[164:167], v[124:127]
	v_mfma_f32_16x16x32_bf16 v[120:123], v[140:143], v[164:167], v[120:123]
	v_mfma_f32_16x16x32_bf16 v[108:111], v[132:135], v[172:175], v[108:111]
	v_mfma_f32_16x16x32_bf16 v[104:107], v[140:143], v[172:175], v[104:107]
	v_mfma_f32_16x16x32_bf16 v[92:95], v[132:135], v[180:183], v[92:95]
	v_mfma_f32_16x16x32_bf16 v[88:91], v[140:143], v[180:183], v[88:91]
	v_mfma_f32_16x16x32_bf16 v[76:79], v[132:135], v[224:227], v[76:79]
	v_mfma_f32_16x16x32_bf16 v[72:75], v[140:143], v[224:227], v[72:75]
	s_setprio 0
	s_setprio 1
	v_mfma_f32_16x16x32_bf16 v[116:119], v[144:147], v[160:163], v[116:119]
	v_mfma_f32_16x16x32_bf16 v[112:115], v[152:155], v[160:163], v[112:115]
	v_mfma_f32_16x16x32_bf16 v[100:103], v[144:147], v[168:171], v[100:103]
	v_mfma_f32_16x16x32_bf16 v[96:99], v[152:155], v[168:171], v[96:99]
	v_mfma_f32_16x16x32_bf16 v[84:87], v[144:147], v[176:179], v[84:87]
	v_mfma_f32_16x16x32_bf16 v[80:83], v[152:155], v[176:179], v[80:83]
	v_mfma_f32_16x16x32_bf16 v[68:71], v[144:147], v[220:223], v[68:71]
	v_mfma_f32_16x16x32_bf16 v[64:67], v[152:155], v[220:223], v[64:67]
	v_mfma_f32_16x16x32_bf16 v[116:119], v[148:151], v[164:167], v[116:119]
	v_mfma_f32_16x16x32_bf16 v[112:115], v[156:159], v[164:167], v[112:115]
	v_mfma_f32_16x16x32_bf16 v[100:103], v[148:151], v[172:175], v[100:103]
	v_mfma_f32_16x16x32_bf16 v[96:99], v[156:159], v[172:175], v[96:99]
	v_mfma_f32_16x16x32_bf16 v[84:87], v[148:151], v[180:183], v[84:87]
	v_mfma_f32_16x16x32_bf16 v[80:83], v[156:159], v[180:183], v[80:83]
	v_mfma_f32_16x16x32_bf16 v[68:71], v[148:151], v[224:227], v[68:71]
	v_mfma_f32_16x16x32_bf16 v[64:67], v[156:159], v[224:227], v[64:67]
	s_setprio 0
	s_barrier
; #define PG8_STAGE(bufoff, gbase, voff) do { _Pragma("unroll") for (int _i = 0; _i < 2; ++_i) \
;         __builtin_amdgcn_global_load_lds((const unsigned*)((const char*)(gbase) + (voff)[_i]), (PG8_LAS unsigned*)(lds + (bufoff) + ldsw + _i * 8192), 16, 0, 0); } while (0)
; #define PG8_LDA(dst, b, h) do { _Pragma("unroll") for (int m = 0; m < 4; ++m) _Pragma("unroll") for (int k = 0; k < 2; ++k) dst[m][k] = *(const PG8_LAS bf16x8*)(lds + PG8_SA(b, h) + aoff + m * 2048 + k * 1024); } while (0)
; #define PG8_MMA(ai, bj, At, Bt) do { __builtin_amdgcn_s_setprio(1); _Pragma("unroll") for (int m = 0; m < 4; ++m) _Pragma("unroll") for (int n = 0; n < 2; ++n) _Pragma("unroll") for (int k = 0; k < 2; ++k) \
;         acc[ai][bj][m][n] = __builtin_amdgcn_mfma_f32_16x16x32_bf16(Bt[n][k], At[m][k], acc[ai][bj][m][n], 0, 0, 0); __builtin_amdgcn_s_setprio(0); } while (0)
; #define PG8_WAIT_V(n) asm volatile("s_waitcnt vmcnt(" #n ")" ::: "memory")
; #define PG8_WAIT_L(n) asm volatile("s_waitcnt lgkmcnt(" #n ")" ::: "memory")
; #define PG8_BAR __builtin_amdgcn_s_barrier()
; #define PG8_SCHED __builtin_amdgcn_sched_barrier(0)
; template <class Epi, class Sched, bool ALIGN_EPI = false, bool SP2 = false>
; __device__ __forceinline__ void gemm_phase(PG8_LAS unsigned char* lds, const Gemm g, const Sched& S, const Epi& E) {
;     ...
;         for (int t = 0; t < nt; t += 2) {
;             const bool last = (t == nt - 2);
;             const char* a1 = cA + (size_t)(t + 1) * kstepA;
;             const char* a2 = last ? nA : cA + (size_t)(t + 2) * kstepA; const char* b2 = last ? nB : cB + (size_t)(t + 2) * kstep;
;             const char* a3 = a2 + kstepA; const char* b3 = b2 + kstep;
;     ...
;             PG8_LDA(At, 1, 1); PG8_STAGE(PG8_SB(1, 0), b3, voffB); PG8_STAGE(PG8_SB(1, 1), b3 + hstepB, voffB); PG8_STAGE(PG8_SA(1, 0), a3, voffA);
;             PG8_WAIT_V(8); PG8_WAIT_L(0); PG8_BAR; PG8_MMA(1, 0, At, B0); PG8_MMA(1, 1, At, B1); PG8_BAR; PG8_SCHED;
	s_add_i32 s73, s87, s14
	v_lshl_add_u64 v[230:231], v[208:209], 0, s[38:39]
	s_mov_b32 m0, s73
	ds_read_b128 v[160:163], v213 offset:49152
	ds_read_b128 v[164:167], v213 offset:50176
	ds_read_b128 v[168:171], v213 offset:51200
	ds_read_b128 v[172:175], v213 offset:52224
	ds_read_b128 v[176:179], v213 offset:53248
	ds_read_b128 v[180:183], v213 offset:54272
	ds_read_b128 v[220:223], v213 offset:55296
	ds_read_b128 v[224:227], v213 offset:56320
	global_load_lds_dwordx4 v[230:231], off
	v_lshl_add_u64 v[230:231], v[208:209], 0, s[40:41]
	s_add_i32 m0, s73, 0x2000
	s_add_i32 s73, s88, s14
	global_load_lds_dwordx4 v[230:231], off
	v_lshl_add_u64 v[230:231], v[208:209], 0, s[42:43]
	s_mov_b32 m0, s73
	v_lshl_add_u64 v[208:209], v[208:209], 0, s[44:45]
	global_load_lds_dwordx4 v[230:231], off
	s_add_i32 m0, s73, 0x2000
	s_nop 0
	global_load_lds_dwordx4 v[208:209], off
	v_lshl_add_u64 v[208:209], v[228:229], 0, s[38:39]
	s_mov_b32 m0, s74
	s_nop 0
	global_load_lds_dwordx4 v[208:209], off
	v_lshl_add_u64 v[208:209], v[228:229], 0, s[40:41]
	s_mov_b32 m0, s75
	s_nop 0
	global_load_lds_dwordx4 v[208:209], off
	s_waitcnt vmcnt(8)
	s_waitcnt lgkmcnt(0)
	s_barrier
	s_setprio 1
	s_waitcnt lgkmcnt(0)
	v_mfma_f32_16x16x32_bf16 v[60:63], v[128:131], v[160:163], v[60:63]
	v_mfma_f32_16x16x32_bf16 v[56:59], v[136:139], v[160:163], v[56:59]
	v_mfma_f32_16x16x32_bf16 v[44:47], v[128:131], v[168:171], v[44:47]
	v_mfma_f32_16x16x32_bf16 v[40:43], v[136:139], v[168:171], v[40:43]
	v_mfma_f32_16x16x32_bf16 v[28:31], v[128:131], v[176:179], v[28:31]
	v_mfma_f32_16x16x32_bf16 v[24:27], v[136:139], v[176:179], v[24:27]
	v_mfma_f32_16x16x32_bf16 v[12:15], v[128:131], v[220:223], v[12:15]
	v_mfma_f32_16x16x32_bf16 v[8:11], v[136:139], v[220:223], v[8:11]
	v_mfma_f32_16x16x32_bf16 v[60:63], v[132:135], v[164:167], v[60:63]
	v_mfma_f32_16x16x32_bf16 v[56:59], v[140:143], v[164:167], v[56:59]
	v_mfma_f32_16x16x32_bf16 v[44:47], v[132:135], v[172:175], v[44:47]
	v_mfma_f32_16x16x32_bf16 v[40:43], v[140:143], v[172:175], v[40:43]
	v_mfma_f32_16x16x32_bf16 v[28:31], v[132:135], v[180:183], v[28:31]
	v_mfma_f32_16x16x32_bf16 v[24:27], v[140:143], v[180:183], v[24:27]
	v_mfma_f32_16x16x32_bf16 v[12:15], v[132:135], v[224:227], v[12:15]
	v_mfma_f32_16x16x32_bf16 v[8:11], v[140:143], v[224:227], v[8:11]
	s_setprio 0
	s_setprio 1
	v_mfma_f32_16x16x32_bf16 v[52:55], v[144:147], v[160:163], v[52:55]
	v_mfma_f32_16x16x32_bf16 v[48:51], v[152:155], v[160:163], v[48:51]
	v_mfma_f32_16x16x32_bf16 v[36:39], v[144:147], v[168:171], v[36:39]
	v_mfma_f32_16x16x32_bf16 v[32:35], v[152:155], v[168:171], v[32:35]
	v_mfma_f32_16x16x32_bf16 v[20:23], v[144:147], v[176:179], v[20:23]
	v_mfma_f32_16x16x32_bf16 v[16:19], v[152:155], v[176:179], v[16:19]
	v_mfma_f32_16x16x32_bf16 v[4:7], v[144:147], v[220:223], v[4:7]
	v_mfma_f32_16x16x32_bf16 v[0:3], v[152:155], v[220:223], v[0:3]
	v_mfma_f32_16x16x32_bf16 v[52:55], v[148:151], v[164:167], v[52:55]
	v_mfma_f32_16x16x32_bf16 v[48:51], v[156:159], v[164:167], v[48:51]
	v_mfma_f32_16x16x32_bf16 v[36:39], v[148:151], v[172:175], v[36:39]
	v_mfma_f32_16x16x32_bf16 v[32:35], v[156:159], v[172:175], v[32:35]
	v_mfma_f32_16x16x32_bf16 v[20:23], v[148:151], v[180:183], v[20:23]
	v_mfma_f32_16x16x32_bf16 v[16:19], v[156:159], v[180:183], v[16:19]
	v_mfma_f32_16x16x32_bf16 v[4:7], v[148:151], v[224:227], v[4:7]
	v_mfma_f32_16x16x32_bf16 v[0:3], v[156:159], v[224:227], v[0:3]
	s_setprio 0
	s_barrier
	s_add_i32 s72, s72, 2
	s_add_u32 s68, s68, 0x10000
	s_addc_u32 s69, s69, 0
	s_add_u32 s70, s70, 0x10000
	s_addc_u32 s71, s71, 0
	s_cmp_gt_u32 s72, 13

; #define PG8_STAGE(bufoff, gbase, voff) do { _Pragma("unroll") for (int _i = 0; _i < 2; ++_i) \
;         __builtin_amdgcn_global_load_lds((const unsigned*)((const char*)(gbase) + (voff)[_i]), (PG8_LAS unsigned*)(lds + (bufoff) + ldsw + _i * 8192), 16, 0, 0); } while (0)
; #define PG8_LDA(dst, b, h) do { _Pragma("unroll") for (int m = 0; m < 4; ++m) _Pragma("unroll") for (int k = 0; k < 2; ++k) dst[m][k] = *(const PG8_LAS bf16x8*)(lds + PG8_SA(b, h) + aoff + m * 2048 + k * 1024); } while (0)
; #define PG8_LDB(dst, b, h) do { _Pragma("unroll") for (int n = 0; n < 2; ++n) _Pragma("unroll") for (int k = 0; k < 2; ++k) dst[n][k] = *(const PG8_LAS bf16x8*)(lds + PG8_SB(b, h) + boff + n * 2048 + k * 1024); } while (0)
; #define PG8_WAIT_V(n) asm volatile("s_waitcnt vmcnt(" #n ")" ::: "memory")
; #define PG8_BAR __builtin_amdgcn_s_barrier()
; template <class Epi, class Sched, bool ALIGN_EPI = false, bool SP2 = false>
; __device__ __forceinline__ void gemm_phase(PG8_LAS unsigned char* lds, const Gemm g, const Sched& S, const Epi& E) {
;     ...
;         const bool has_next = S.next(ui + 1, nxt);
;         const char* nA = has_next ? (const char*)g.A + (size_t)nxt.pm * tstepA : cA; const char* nB = has_next ? (const char*)g.Bt + (size_t)nxt.pn * tstepB : cB;
;         for (int t = 0; t < nt; t += 2) {
;             const bool last = (t == nt - 2);
;             const char* a1 = cA + (size_t)(t + 1) * kstepA;
;             const char* a2 = last ? nA : cA + (size_t)(t + 2) * kstepA; const char* b2 = last ? nB : cB + (size_t)(t + 2) * kstep;
;             const char* a3 = a2 + kstepA; const char* b3 = b2 + kstep;
;             if (last && has_next) S.a_ready(nxt);
;             if constexpr (SP2) {
;             PG8_LDB(B0, 0, 0); PG8_LDB(B1, 0, 1); PG8_SCHED; PG8_LDA(At, 0, 0); PG8_STAGE(PG8_SA(1, 1), a1 + hstepA, voffA);
;             PG8_WAIT_V(8); PG8_WAIT_L(0); PG8_BAR; PG8_MMA(0, 0, At, B0); PG8_MMA(0, 1, At, B1); PG8_BAR; PG8_SCHED;
;             PG8_LDA(At, 0, 1); PG8_STAGE(PG8_SB(0, 0), b2, voffB); PG8_STAGE(PG8_SB(0, 1), b2 + hstepB, voffB); PG8_STAGE(PG8_SA(0, 0), a2, voffA);
;     ...
; #pragma unroll
;         for (int a = 0; a < 2; ++a)
; #pragma unroll
;             for (int b = 0; b < 2; ++b)
; #pragma unroll
;                 for (int m = 0; m < 4; ++m)
; #pragma unroll
;                     for (int n = 0; n < 2; ++n) acc[a][b][m][n] = (f32x4){0.f, 0.f, 0.f, 0.f};
.LBB0_837:
	s_ashr_i32 s55, s54, 31
	s_lshl_b64 s[56:57], s[54:55], 19
	s_add_u32 s56, s12, s56
	s_addc_u32 s57, s13, s57
	s_and_b64 s[58:59], s[2:3], exec
	s_cselect_b32 s55, s57, s63
	s_cselect_b32 s80, s56, s62
	s_ashr_i32 s53, s52, 31
	s_lshl_b64 s[58:59], s[52:53], 19
	s_add_u32 s58, s33, s58
	s_addc_u32 s59, s83, s59
	s_and_b64 s[78:79], s[2:3], exec
	s_cselect_b32 s53, s59, s65
	s_cselect_b32 s81, s58, s64
	s_add_u32 s62, s62, 0x10000
	s_addc_u32 s63, s63, 0
	s_add_u32 s64, s64, 0x10000
	s_addc_u32 s65, s65, 0
	s_mov_b32 s82, -2
	ds_read_b128 v[148:151], v141
	ds_read_b128 v[152:155], v141 offset:1024
	ds_read_b128 v[156:159], v141 offset:2048
	ds_read_b128 v[160:163], v141 offset:3072
	ds_read_b128 v[164:167], v142
	ds_read_b128 v[168:171], v142 offset:1024
	ds_read_b128 v[172:175], v142 offset:2048
	ds_read_b128 v[176:179], v142 offset:3072
	s_cmp_eq_u32 s82, 12
	s_cselect_b32 s79, s55, s63
	s_cselect_b32 s78, s80, s62
	s_cselect_b32 s85, s53, s65
	s_cselect_b32 s84, s81, s64
	v_lshl_add_u64 v[216:217], s[62:63], 0, v[190:191]
	v_lshl_add_u64 v[220:221], v[216:217], 0, s[46:47]
	s_add_i32 m0, s18, 0xc000
	ds_read_b128 v[180:183], v143
	ds_read_b128 v[184:187], v143 offset:1024
	ds_read_b128 v[192:195], v143 offset:2048
	ds_read_b128 v[196:199], v143 offset:3072
	ds_read_b128 v[200:203], v143 offset:4096
	ds_read_b128 v[204:207], v143 offset:5120
	ds_read_b128 v[208:211], v143 offset:6144
	ds_read_b128 v[212:215], v143 offset:7168
	global_load_lds_dwordx4 v[220:221], off
	v_lshl_add_u64 v[216:217], v[216:217], 0, s[48:49]
	s_add_i32 m0, s18, 0xe000
	s_nop 0
	global_load_lds_dwordx4 v[216:217], off
	s_waitcnt vmcnt(8)
	s_waitcnt lgkmcnt(0)
	s_barrier
	s_setprio 1
	s_waitcnt lgkmcnt(0)
	v_mfma_f32_16x16x32_bf16 v[116:119], v[148:151], v[180:183], 0
	v_mfma_f32_16x16x32_bf16 v[112:115], v[156:159], v[180:183], 0
	v_mfma_f32_16x16x32_bf16 v[108:111], v[148:151], v[192:195], 0
	v_mfma_f32_16x16x32_bf16 v[100:103], v[156:159], v[192:195], 0
	v_mfma_f32_16x16x32_bf16 v[92:95], v[148:151], v[200:203], 0
	v_mfma_f32_16x16x32_bf16 v[84:87], v[156:159], v[200:203], 0
	v_mfma_f32_16x16x32_bf16 v[76:79], v[148:151], v[208:211], 0
	v_mfma_f32_16x16x32_bf16 v[68:71], v[156:159], v[208:211], 0
	v_mfma_f32_16x16x32_bf16 v[116:119], v[152:155], v[184:187], v[116:119]
	v_mfma_f32_16x16x32_bf16 v[112:115], v[160:163], v[184:187], v[112:115]
	v_mfma_f32_16x16x32_bf16 v[108:111], v[152:155], v[196:199], v[108:111]
	v_mfma_f32_16x16x32_bf16 v[100:103], v[160:163], v[196:199], v[100:103]
	v_mfma_f32_16x16x32_bf16 v[92:95], v[152:155], v[204:207], v[92:95]
	v_mfma_f32_16x16x32_bf16 v[84:87], v[160:163], v[204:207], v[84:87]
	v_mfma_f32_16x16x32_bf16 v[76:79], v[152:155], v[212:215], v[76:79]
	v_mfma_f32_16x16x32_bf16 v[68:71], v[160:163], v[212:215], v[68:71]
	s_setprio 0
	s_setprio 1
	v_mfma_f32_16x16x32_bf16 v[124:127], v[164:167], v[180:183], 0
	v_mfma_f32_16x16x32_bf16 v[120:123], v[172:175], v[180:183], 0
	v_mfma_f32_16x16x32_bf16 v[104:107], v[164:167], v[192:195], 0
	v_mfma_f32_16x16x32_bf16 v[96:99], v[172:175], v[192:195], 0
	v_mfma_f32_16x16x32_bf16 v[88:91], v[164:167], v[200:203], 0
	v_mfma_f32_16x16x32_bf16 v[80:83], v[172:175], v[200:203], 0
	v_mfma_f32_16x16x32_bf16 v[72:75], v[164:167], v[208:211], 0
	v_mfma_f32_16x16x32_bf16 v[64:67], v[172:175], v[208:211], 0
	v_mfma_f32_16x16x32_bf16 v[124:127], v[168:171], v[184:187], v[124:127]
	v_mfma_f32_16x16x32_bf16 v[120:123], v[176:179], v[184:187], v[120:123]
	v_mfma_f32_16x16x32_bf16 v[104:107], v[168:171], v[196:199], v[104:107]
	v_mfma_f32_16x16x32_bf16 v[96:99], v[176:179], v[196:199], v[96:99]
	v_mfma_f32_16x16x32_bf16 v[88:91], v[168:171], v[204:207], v[88:91]
	v_mfma_f32_16x16x32_bf16 v[80:83], v[176:179], v[204:207], v[80:83]
	v_mfma_f32_16x16x32_bf16 v[72:75], v[168:171], v[212:215], v[72:75]
	v_mfma_f32_16x16x32_bf16 v[64:67], v[176:179], v[212:215], v[64:67]
	s_setprio 0
	s_barrier
	v_lshl_add_u64 v[216:217], s[84:85], 0, v[190:191]
	s_add_i32 s84, s74, s14
	s_mov_b32 m0, s84
	ds_read_b128 v[180:183], v143 offset:16384
	ds_read_b128 v[184:187], v143 offset:17408
	ds_read_b128 v[192:195], v143 offset:18432
	ds_read_b128 v[196:199], v143 offset:19456
	ds_read_b128 v[200:203], v143 offset:20480
	ds_read_b128 v[204:207], v143 offset:21504
	ds_read_b128 v[208:211], v143 offset:22528
	ds_read_b128 v[212:215], v143 offset:23552
	global_load_lds_dwordx4 v[216:217], off
	v_lshl_add_u64 v[220:221], v[216:217], 0, s[6:7]
	s_add_i32 m0, s84, 0x2000
	s_add_i32 s84, s75, s14
	global_load_lds_dwordx4 v[220:221], off
	v_lshl_add_u64 v[220:221], v[216:217], 0, s[8:9]
	s_mov_b32 m0, s84
	s_nop 0
	global_load_lds_dwordx4 v[220:221], off
	v_lshl_add_u64 v[220:221], v[216:217], 0, s[10:11]
	s_add_i32 m0, s84, 0x2000
	s_nop 0
	global_load_lds_dwordx4 v[220:221], off
	v_lshl_add_u64 v[220:221], s[78:79], 0, v[190:191]
	s_mov_b32 m0, s18
	v_lshl_add_u64 v[222:223], v[220:221], 0, s[6:7]
	global_load_lds_dwordx4 v[220:221], off
	s_mov_b32 m0, s19
	s_nop 0
	global_load_lds_dwordx4 v[222:223], off
	s_waitcnt vmcnt(8)
	s_waitcnt lgkmcnt(0)
	s_barrier
; #define PG8_STAGE(bufoff, gbase, voff) do { _Pragma("unroll") for (int _i = 0; _i < 2; ++_i) \
;         __builtin_amdgcn_global_load_lds((const unsigned*)((const char*)(gbase) + (voff)[_i]), (PG8_LAS unsigned*)(lds + (bufoff) + ldsw + _i * 8192), 16, 0, 0); } while (0)
; #define PG8_LDA(dst, b, h) do { _Pragma("unroll") for (int m = 0; m < 4; ++m) _Pragma("unroll") for (int k = 0; k < 2; ++k) dst[m][k] = *(const PG8_LAS bf16x8*)(lds + PG8_SA(b, h) + aoff + m * 2048 + k * 1024); } while (0)
; #define PG8_LDB(dst, b, h) do { _Pragma("unroll") for (int n = 0; n < 2; ++n) _Pragma("unroll") for (int k = 0; k < 2; ++k) dst[n][k] = *(const PG8_LAS bf16x8*)(lds + PG8_SB(b, h) + boff + n * 2048 + k * 1024); } while (0)
; #define PG8_MMA(ai, bj, At, Bt) do { __builtin_amdgcn_s_setprio(1); _Pragma("unroll") for (int m = 0; m < 4; ++m) _Pragma("unroll") for (int n = 0; n < 2; ++n) _Pragma("unroll") for (int k = 0; k < 2; ++k) \
;         acc[ai][bj][m][n] = __builtin_amdgcn_mfma_f32_16x16x32_bf16(Bt[n][k], At[m][k], acc[ai][bj][m][n], 0, 0, 0); __builtin_amdgcn_s_setprio(0); } while (0)
; #define PG8_WAIT_V(n) asm volatile("s_waitcnt vmcnt(" #n ")" ::: "memory")
; #define PG8_WAIT_L(n) asm volatile("s_waitcnt lgkmcnt(" #n ")" ::: "memory")
; #define PG8_BAR __builtin_amdgcn_s_barrier()
; #define PG8_SCHED __builtin_amdgcn_sched_barrier(0)
; template <class Epi, class Sched, bool ALIGN_EPI = false, bool SP2 = false>
; __device__ __forceinline__ void gemm_phase(PG8_LAS unsigned char* lds, const Gemm g, const Sched& S, const Epi& E) {
;     ...
;             PG8_WAIT_V(8); PG8_WAIT_L(0); PG8_BAR; PG8_MMA(1, 0, At, B0); PG8_MMA(1, 1, At, B1); PG8_BAR; PG8_SCHED;
;             PG8_LDB(B0, 1, 0); PG8_LDB(B1, 1, 1); PG8_SCHED; PG8_LDA(At, 1, 0); PG8_STAGE(PG8_SA(0, 1), a2 + hstepA, voffA);
;             PG8_WAIT_V(8); PG8_WAIT_L(0); PG8_BAR; PG8_MMA(0, 0, At, B0); PG8_MMA(0, 1, At, B1); PG8_BAR; PG8_SCHED;
	s_setprio 1
	s_waitcnt lgkmcnt(0)
	v_mfma_f32_16x16x32_bf16 v[60:63], v[148:151], v[180:183], 0
	v_mfma_f32_16x16x32_bf16 v[52:55], v[156:159], v[180:183], 0
	v_mfma_f32_16x16x32_bf16 v[44:47], v[148:151], v[192:195], 0
	v_mfma_f32_16x16x32_bf16 v[36:39], v[156:159], v[192:195], 0
	v_mfma_f32_16x16x32_bf16 v[28:31], v[148:151], v[200:203], 0
	v_mfma_f32_16x16x32_bf16 v[20:23], v[156:159], v[200:203], 0
	v_mfma_f32_16x16x32_bf16 v[12:15], v[148:151], v[208:211], 0
	v_mfma_f32_16x16x32_bf16 v[4:7], v[156:159], v[208:211], 0
	v_mfma_f32_16x16x32_bf16 v[60:63], v[152:155], v[184:187], v[60:63]
	v_mfma_f32_16x16x32_bf16 v[52:55], v[160:163], v[184:187], v[52:55]
	v_mfma_f32_16x16x32_bf16 v[44:47], v[152:155], v[196:199], v[44:47]
	v_mfma_f32_16x16x32_bf16 v[36:39], v[160:163], v[196:199], v[36:39]
	v_mfma_f32_16x16x32_bf16 v[28:31], v[152:155], v[204:207], v[28:31]
	v_mfma_f32_16x16x32_bf16 v[20:23], v[160:163], v[204:207], v[20:23]
	v_mfma_f32_16x16x32_bf16 v[12:15], v[152:155], v[212:215], v[12:15]
	v_mfma_f32_16x16x32_bf16 v[4:7], v[160:163], v[212:215], v[4:7]
	s_setprio 0
	s_setprio 1
	v_mfma_f32_16x16x32_bf16 v[56:59], v[164:167], v[180:183], 0
	v_mfma_f32_16x16x32_bf16 v[48:51], v[172:175], v[180:183], 0
	v_mfma_f32_16x16x32_bf16 v[40:43], v[164:167], v[192:195], 0
	v_mfma_f32_16x16x32_bf16 v[32:35], v[172:175], v[192:195], 0
	v_mfma_f32_16x16x32_bf16 v[24:27], v[164:167], v[200:203], 0
	v_mfma_f32_16x16x32_bf16 v[16:19], v[172:175], v[200:203], 0
	v_mfma_f32_16x16x32_bf16 v[8:11], v[164:167], v[208:211], 0
	v_mfma_f32_16x16x32_bf16 v[0:3], v[172:175], v[208:211], 0
	v_mfma_f32_16x16x32_bf16 v[56:59], v[168:171], v[184:187], v[56:59]
	v_mfma_f32_16x16x32_bf16 v[48:51], v[176:179], v[184:187], v[48:51]
	v_mfma_f32_16x16x32_bf16 v[40:43], v[168:171], v[196:199], v[40:43]
	v_mfma_f32_16x16x32_bf16 v[32:35], v[176:179], v[196:199], v[32:35]
	v_mfma_f32_16x16x32_bf16 v[24:27], v[168:171], v[204:207], v[24:27]
	v_mfma_f32_16x16x32_bf16 v[16:19], v[176:179], v[204:207], v[16:19]
	v_mfma_f32_16x16x32_bf16 v[8:11], v[168:171], v[212:215], v[8:11]
	v_mfma_f32_16x16x32_bf16 v[0:3], v[176:179], v[212:215], v[0:3]
	s_setprio 0
	s_barrier
	ds_read_b128 v[148:151], v144
	ds_read_b128 v[152:155], v144 offset:1024
	ds_read_b128 v[156:159], v144 offset:2048
	ds_read_b128 v[160:163], v144 offset:3072
	ds_read_b128 v[164:167], v145
	ds_read_b128 v[168:171], v145 offset:1024
	ds_read_b128 v[172:175], v145 offset:2048
	ds_read_b128 v[176:179], v145 offset:3072
	s_mov_b32 m0, s66
	v_lshl_add_u64 v[222:223], v[220:221], 0, s[8:9]
	ds_read_b128 v[180:183], v143 offset:32768
	ds_read_b128 v[184:187], v143 offset:33792
	ds_read_b128 v[192:195], v143 offset:34816
	ds_read_b128 v[196:199], v143 offset:35840
	ds_read_b128 v[200:203], v143 offset:36864
	ds_read_b128 v[204:207], v143 offset:37888
	ds_read_b128 v[208:211], v143 offset:38912
	ds_read_b128 v[212:215], v143 offset:39936
	global_load_lds_dwordx4 v[222:223], off
	v_lshl_add_u64 v[222:223], v[220:221], 0, s[10:11]
	s_mov_b32 m0, s67
	s_nop 0
	global_load_lds_dwordx4 v[222:223], off
	s_waitcnt vmcnt(8)
	s_waitcnt lgkmcnt(0)
	s_barrier
	s_setprio 1
	s_waitcnt lgkmcnt(0)
	v_mfma_f32_16x16x32_bf16 v[116:119], v[148:151], v[180:183], v[116:119]
	v_mfma_f32_16x16x32_bf16 v[112:115], v[156:159], v[180:183], v[112:115]
	v_mfma_f32_16x16x32_bf16 v[108:111], v[148:151], v[192:195], v[108:111]
	v_mfma_f32_16x16x32_bf16 v[100:103], v[156:159], v[192:195], v[100:103]
	v_mfma_f32_16x16x32_bf16 v[92:95], v[148:151], v[200:203], v[92:95]
	v_mfma_f32_16x16x32_bf16 v[84:87], v[156:159], v[200:203], v[84:87]
	v_mfma_f32_16x16x32_bf16 v[76:79], v[148:151], v[208:211], v[76:79]
	v_mfma_f32_16x16x32_bf16 v[68:71], v[156:159], v[208:211], v[68:71]
	v_mfma_f32_16x16x32_bf16 v[116:119], v[152:155], v[184:187], v[116:119]
	v_mfma_f32_16x16x32_bf16 v[112:115], v[160:163], v[184:187], v[112:115]
	v_mfma_f32_16x16x32_bf16 v[108:111], v[152:155], v[196:199], v[108:111]
	v_mfma_f32_16x16x32_bf16 v[100:103], v[160:163], v[196:199], v[100:103]
	v_mfma_f32_16x16x32_bf16 v[92:95], v[152:155], v[204:207], v[92:95]
	v_mfma_f32_16x16x32_bf16 v[84:87], v[160:163], v[204:207], v[84:87]
	v_mfma_f32_16x16x32_bf16 v[76:79], v[152:155], v[212:215], v[76:79]
	v_mfma_f32_16x16x32_bf16 v[68:71], v[160:163], v[212:215], v[68:71]
	s_setprio 0
	s_setprio 1
	v_mfma_f32_16x16x32_bf16 v[124:127], v[164:167], v[180:183], v[124:127]
	v_mfma_f32_16x16x32_bf16 v[120:123], v[172:175], v[180:183], v[120:123]
	v_mfma_f32_16x16x32_bf16 v[104:107], v[164:167], v[192:195], v[104:107]
	v_mfma_f32_16x16x32_bf16 v[96:99], v[172:175], v[192:195], v[96:99]
	v_mfma_f32_16x16x32_bf16 v[88:91], v[164:167], v[200:203], v[88:91]
	v_mfma_f32_16x16x32_bf16 v[80:83], v[172:175], v[200:203], v[80:83]
	v_mfma_f32_16x16x32_bf16 v[72:75], v[164:167], v[208:211], v[72:75]
	v_mfma_f32_16x16x32_bf16 v[64:67], v[172:175], v[208:211], v[64:67]
	v_mfma_f32_16x16x32_bf16 v[124:127], v[168:171], v[184:187], v[124:127]
	v_mfma_f32_16x16x32_bf16 v[120:123], v[176:179], v[184:187], v[120:123]
	v_mfma_f32_16x16x32_bf16 v[104:107], v[168:171], v[196:199], v[104:107]
	v_mfma_f32_16x16x32_bf16 v[96:99], v[176:179], v[196:199], v[96:99]
	v_mfma_f32_16x16x32_bf16 v[88:91], v[168:171], v[204:207], v[88:91]
	v_mfma_f32_16x16x32_bf16 v[80:83], v[176:179], v[204:207], v[80:83]
	v_mfma_f32_16x16x32_bf16 v[72:75], v[168:171], v[212:215], v[72:75]
	v_mfma_f32_16x16x32_bf16 v[64:67], v[176:179], v[212:215], v[64:67]
	s_setprio 0
	s_barrier
; #define PG8_STAGE(bufoff, gbase, voff) do { _Pragma("unroll") for (int _i = 0; _i < 2; ++_i) \
;         __builtin_amdgcn_global_load_lds((const unsigned*)((const char*)(gbase) + (voff)[_i]), (PG8_LAS unsigned*)(lds + (bufoff) + ldsw + _i * 8192), 16, 0, 0); } while (0)
; #define PG8_LDA(dst, b, h) do { _Pragma("unroll") for (int m = 0; m < 4; ++m) _Pragma("unroll") for (int k = 0; k < 2; ++k) dst[m][k] = *(const PG8_LAS bf16x8*)(lds + PG8_SA(b, h) + aoff + m * 2048 + k * 1024); } while (0)
; #define PG8_MMA(ai, bj, At, Bt) do { __builtin_amdgcn_s_setprio(1); _Pragma("unroll") for (int m = 0; m < 4; ++m) _Pragma("unroll") for (int n = 0; n < 2; ++n) _Pragma("unroll") for (int k = 0; k < 2; ++k) \
;         acc[ai][bj][m][n] = __builtin_amdgcn_mfma_f32_16x16x32_bf16(Bt[n][k], At[m][k], acc[ai][bj][m][n], 0, 0, 0); __builtin_amdgcn_s_setprio(0); } while (0)
; #define PG8_WAIT_V(n) asm volatile("s_waitcnt vmcnt(" #n ")" ::: "memory")
; #define PG8_WAIT_L(n) asm volatile("s_waitcnt lgkmcnt(" #n ")" ::: "memory")
; #define PG8_BAR __builtin_amdgcn_s_barrier()
; #define PG8_SCHED __builtin_amdgcn_sched_barrier(0)
; template <class Epi, class Sched, bool ALIGN_EPI = false, bool SP2 = false>
; __device__ __forceinline__ void gemm_phase(PG8_LAS unsigned char* lds, const Gemm g, const Sched& S, const Epi& E) {
;     ...
;         for (int t = 0; t < nt; t += 2) {
;             const bool last = (t == nt - 2);
;             const char* a1 = cA + (size_t)(t + 1) * kstepA;
;             const char* a2 = last ? nA : cA + (size_t)(t + 2) * kstepA; const char* b2 = last ? nB : cB + (size_t)(t + 2) * kstep;
;             const char* a3 = a2 + kstepA; const char* b3 = b2 + kstep;
;     ...
;             PG8_LDA(At, 1, 1); PG8_STAGE(PG8_SB(1, 0), b3, voffB); PG8_STAGE(PG8_SB(1, 1), b3 + hstepB, voffB); PG8_STAGE(PG8_SA(1, 0), a3, voffA);
;             PG8_WAIT_V(8); PG8_WAIT_L(0); PG8_BAR; PG8_MMA(1, 0, At, B0); PG8_MMA(1, 1, At, B1); PG8_BAR; PG8_SCHED;
	s_add_i32 s78, s76, s14
	v_lshl_add_u64 v[222:223], v[216:217], 0, s[34:35]
	s_mov_b32 m0, s78
	ds_read_b128 v[180:183], v143 offset:49152
	ds_read_b128 v[184:187], v143 offset:50176
	ds_read_b128 v[192:195], v143 offset:51200
	ds_read_b128 v[196:199], v143 offset:52224
	ds_read_b128 v[200:203], v143 offset:53248
	ds_read_b128 v[204:207], v143 offset:54272
	ds_read_b128 v[208:211], v143 offset:55296
	ds_read_b128 v[212:215], v143 offset:56320
	global_load_lds_dwordx4 v[222:223], off
	v_lshl_add_u64 v[222:223], v[216:217], 0, s[36:37]
	s_add_i32 m0, s78, 0x2000
	s_add_i32 s78, s77, s14
	global_load_lds_dwordx4 v[222:223], off
	v_lshl_add_u64 v[222:223], v[216:217], 0, s[38:39]
	s_mov_b32 m0, s78
	v_lshl_add_u64 v[216:217], v[216:217], 0, s[40:41]
	global_load_lds_dwordx4 v[222:223], off
	s_add_i32 m0, s78, 0x2000
	s_nop 0
	global_load_lds_dwordx4 v[216:217], off
	v_lshl_add_u64 v[216:217], v[220:221], 0, s[34:35]
	s_mov_b32 m0, s68
	s_nop 0
	global_load_lds_dwordx4 v[216:217], off
	v_lshl_add_u64 v[216:217], v[220:221], 0, s[36:37]
	s_mov_b32 m0, s69
	s_nop 0
	global_load_lds_dwordx4 v[216:217], off
	s_waitcnt vmcnt(8)
	s_waitcnt lgkmcnt(0)
	s_barrier
	s_setprio 1
	s_waitcnt lgkmcnt(0)
	v_mfma_f32_16x16x32_bf16 v[60:63], v[148:151], v[180:183], v[60:63]
	v_mfma_f32_16x16x32_bf16 v[52:55], v[156:159], v[180:183], v[52:55]
	v_mfma_f32_16x16x32_bf16 v[44:47], v[148:151], v[192:195], v[44:47]
	v_mfma_f32_16x16x32_bf16 v[36:39], v[156:159], v[192:195], v[36:39]
	v_mfma_f32_16x16x32_bf16 v[28:31], v[148:151], v[200:203], v[28:31]
	v_mfma_f32_16x16x32_bf16 v[20:23], v[156:159], v[200:203], v[20:23]
	v_mfma_f32_16x16x32_bf16 v[12:15], v[148:151], v[208:211], v[12:15]
	v_mfma_f32_16x16x32_bf16 v[4:7], v[156:159], v[208:211], v[4:7]
	v_mfma_f32_16x16x32_bf16 v[60:63], v[152:155], v[184:187], v[60:63]
	v_mfma_f32_16x16x32_bf16 v[52:55], v[160:163], v[184:187], v[52:55]
	v_mfma_f32_16x16x32_bf16 v[44:47], v[152:155], v[196:199], v[44:47]
	v_mfma_f32_16x16x32_bf16 v[36:39], v[160:163], v[196:199], v[36:39]
	v_mfma_f32_16x16x32_bf16 v[28:31], v[152:155], v[204:207], v[28:31]
	v_mfma_f32_16x16x32_bf16 v[20:23], v[160:163], v[204:207], v[20:23]
	v_mfma_f32_16x16x32_bf16 v[12:15], v[152:155], v[212:215], v[12:15]
	v_mfma_f32_16x16x32_bf16 v[4:7], v[160:163], v[212:215], v[4:7]
	s_setprio 0
	s_setprio 1
	v_mfma_f32_16x16x32_bf16 v[56:59], v[164:167], v[180:183], v[56:59]
	v_mfma_f32_16x16x32_bf16 v[48:51], v[172:175], v[180:183], v[48:51]
	v_mfma_f32_16x16x32_bf16 v[40:43], v[164:167], v[192:195], v[40:43]
	v_mfma_f32_16x16x32_bf16 v[32:35], v[172:175], v[192:195], v[32:35]
	v_mfma_f32_16x16x32_bf16 v[24:27], v[164:167], v[200:203], v[24:27]
	v_mfma_f32_16x16x32_bf16 v[16:19], v[172:175], v[200:203], v[16:19]
	v_mfma_f32_16x16x32_bf16 v[8:11], v[164:167], v[208:211], v[8:11]
	v_mfma_f32_16x16x32_bf16 v[0:3], v[172:175], v[208:211], v[0:3]
	v_mfma_f32_16x16x32_bf16 v[56:59], v[168:171], v[184:187], v[56:59]
	v_mfma_f32_16x16x32_bf16 v[48:51], v[176:179], v[184:187], v[48:51]
	v_mfma_f32_16x16x32_bf16 v[40:43], v[168:171], v[196:199], v[40:43]
	v_mfma_f32_16x16x32_bf16 v[32:35], v[176:179], v[196:199], v[32:35]
	v_mfma_f32_16x16x32_bf16 v[24:27], v[168:171], v[204:207], v[24:27]
	v_mfma_f32_16x16x32_bf16 v[16:19], v[176:179], v[204:207], v[16:19]
	v_mfma_f32_16x16x32_bf16 v[8:11], v[168:171], v[212:215], v[8:11]
	v_mfma_f32_16x16x32_bf16 v[0:3], v[176:179], v[212:215], v[0:3]
	s_setprio 0
	s_barrier
	s_add_i32 s82, s82, 2
	s_add_u32 s62, s62, 0x10000
	s_addc_u32 s63, s63, 0
	s_add_u32 s64, s64, 0x10000
	s_addc_u32 s65, s65, 0
	s_cmp_gt_u32 s82, 13

; #define PG8_STAGE(bufoff, gbase, voff) do { _Pragma("unroll") for (int _i = 0; _i < 2; ++_i) \
;         __builtin_amdgcn_global_load_lds((const unsigned*)((const char*)(gbase) + (voff)[_i]), (PG8_LAS unsigned*)(lds + (bufoff) + ldsw + _i * 8192), 16, 0, 0); } while (0)
; #define PG8_LDA(dst, b, h) do { _Pragma("unroll") for (int m = 0; m < 4; ++m) _Pragma("unroll") for (int k = 0; k < 2; ++k) dst[m][k] = *(const PG8_LAS bf16x8*)(lds + PG8_SA(b, h) + aoff + m * 2048 + k * 1024); } while (0)
; #define PG8_LDB(dst, b, h) do { _Pragma("unroll") for (int n = 0; n < 2; ++n) _Pragma("unroll") for (int k = 0; k < 2; ++k) dst[n][k] = *(const PG8_LAS bf16x8*)(lds + PG8_SB(b, h) + boff + n * 2048 + k * 1024); } while (0)
; #define PG8_WAIT_V(n) asm volatile("s_waitcnt vmcnt(" #n ")" ::: "memory")
; #define PG8_BAR __builtin_amdgcn_s_barrier()
; template <class Epi, class Sched, bool ALIGN_EPI = false, bool SP2 = false>
; __device__ __forceinline__ void gemm_phase(PG8_LAS unsigned char* lds, const Gemm g, const Sched& S, const Epi& E) {
;     ...
;         const bool has_next = S.next(ui + 1, nxt);
;         const char* nA = has_next ? (const char*)g.A + (size_t)nxt.pm * tstepA : cA; const char* nB = has_next ? (const char*)g.Bt + (size_t)nxt.pn * tstepB : cB;
;         for (int t = 0; t < nt; t += 2) {
;             const bool last = (t == nt - 2);
;             const char* a1 = cA + (size_t)(t + 1) * kstepA;
;             const char* a2 = last ? nA : cA + (size_t)(t + 2) * kstepA; const char* b2 = last ? nB : cB + (size_t)(t + 2) * kstep;
;             const char* a3 = a2 + kstepA; const char* b3 = b2 + kstep;
;             if (last && has_next) S.a_ready(nxt);
;             if constexpr (SP2) {
;             PG8_LDB(B0, 0, 0); PG8_LDB(B1, 0, 1); PG8_SCHED; PG8_LDA(At, 0, 0); PG8_STAGE(PG8_SA(1, 1), a1 + hstepA, voffA);
;             PG8_WAIT_V(8); PG8_WAIT_L(0); PG8_BAR; PG8_MMA(0, 0, At, B0); PG8_MMA(0, 1, At, B1); PG8_BAR; PG8_SCHED;
;             PG8_LDA(At, 0, 1); PG8_STAGE(PG8_SB(0, 0), b2, voffB); PG8_STAGE(PG8_SB(0, 1), b2 + hstepB, voffB); PG8_STAGE(PG8_SA(0, 0), a2, voffA);
;     ...
; #pragma unroll
;         for (int a = 0; a < 2; ++a)
; #pragma unroll
;             for (int b = 0; b < 2; ++b)
; #pragma unroll
;                 for (int m = 0; m < 4; ++m)
; #pragma unroll
;                     for (int n = 0; n < 2; ++n) acc[a][b][m][n] = (f32x4){0.f, 0.f, 0.f, 0.f};
.LBB0_923:
	s_add_u32 s6, s6, 0x10000
	s_addc_u32 s7, s7, 0
	s_add_u32 s64, s64, 0x10000
	s_addc_u32 s65, s65, 0
	s_mov_b32 s66, -2
	s_waitcnt lgkmcnt(0)
	ds_read_b128 v[84:87], v221
	ds_read_b128 v[92:95], v221 offset:1024
	ds_read_b128 v[104:107], v221 offset:2048
	ds_read_b128 v[116:119], v221 offset:3072
	ds_read_b128 v[128:131], v222
	ds_read_b128 v[140:143], v222 offset:1024
	ds_read_b128 v[152:155], v222 offset:2048
	ds_read_b128 v[156:159], v222 offset:3072
	s_cmp_eq_u32 s66, 40
	s_cselect_b32 s69, s1, s7
	s_cselect_b32 s68, s0, s6
	s_cselect_b32 s71, s63, s65
	s_cselect_b32 s70, s62, s64
	v_lshl_add_u64 v[216:217], s[6:7], 0, v[190:191]
	v_lshl_add_u64 v[228:229], v[216:217], 0, s[58:59]
	s_add_i32 m0, s15, 0xc000
	ds_read_b128 v[160:163], v223
	ds_read_b128 v[164:167], v223 offset:1024
	ds_read_b128 v[168:171], v223 offset:2048
	ds_read_b128 v[172:175], v223 offset:3072
	ds_read_b128 v[176:179], v223 offset:4096
	ds_read_b128 v[180:183], v223 offset:5120
	ds_read_b128 v[184:187], v223 offset:6144
	ds_read_b128 v[212:215], v223 offset:7168
	global_load_lds_dwordx4 v[228:229], off
	v_lshl_add_u64 v[216:217], v[216:217], 0, s[60:61]
	s_add_i32 m0, s15, 0xe000
	s_nop 0
	global_load_lds_dwordx4 v[216:217], off
	s_waitcnt vmcnt(8)
	s_waitcnt lgkmcnt(0)
	s_barrier
	s_setprio 1
	s_waitcnt lgkmcnt(0)
	v_mfma_f32_16x16x32_bf16 v[148:151], v[84:87], v[160:163], 0
	v_mfma_f32_16x16x32_bf16 v[144:147], v[104:107], v[160:163], 0
	v_mfma_f32_16x16x32_bf16 v[124:127], v[84:87], v[168:171], 0
	v_mfma_f32_16x16x32_bf16 v[120:123], v[104:107], v[168:171], 0
	v_mfma_f32_16x16x32_bf16 v[100:103], v[84:87], v[176:179], 0
	v_mfma_f32_16x16x32_bf16 v[96:99], v[104:107], v[176:179], 0
	v_mfma_f32_16x16x32_bf16 v[76:79], v[84:87], v[184:187], 0
	v_mfma_f32_16x16x32_bf16 v[72:75], v[104:107], v[184:187], 0
	v_mfma_f32_16x16x32_bf16 v[148:151], v[92:95], v[164:167], v[148:151]
	v_mfma_f32_16x16x32_bf16 v[144:147], v[116:119], v[164:167], v[144:147]
	v_mfma_f32_16x16x32_bf16 v[124:127], v[92:95], v[172:175], v[124:127]
	v_mfma_f32_16x16x32_bf16 v[120:123], v[116:119], v[172:175], v[120:123]
	v_mfma_f32_16x16x32_bf16 v[100:103], v[92:95], v[180:183], v[100:103]
	v_mfma_f32_16x16x32_bf16 v[96:99], v[116:119], v[180:183], v[96:99]
	v_mfma_f32_16x16x32_bf16 v[76:79], v[92:95], v[212:215], v[76:79]
	v_mfma_f32_16x16x32_bf16 v[72:75], v[116:119], v[212:215], v[72:75]
	s_setprio 0
	s_setprio 1
	v_mfma_f32_16x16x32_bf16 v[136:139], v[128:131], v[160:163], 0
	v_mfma_f32_16x16x32_bf16 v[132:135], v[152:155], v[160:163], 0
	v_mfma_f32_16x16x32_bf16 v[112:115], v[128:131], v[168:171], 0
	v_mfma_f32_16x16x32_bf16 v[108:111], v[152:155], v[168:171], 0
	v_mfma_f32_16x16x32_bf16 v[88:91], v[128:131], v[176:179], 0
	v_mfma_f32_16x16x32_bf16 v[80:83], v[152:155], v[176:179], 0
	v_mfma_f32_16x16x32_bf16 v[68:71], v[128:131], v[184:187], 0
	v_mfma_f32_16x16x32_bf16 v[64:67], v[152:155], v[184:187], 0
	v_mfma_f32_16x16x32_bf16 v[136:139], v[140:143], v[164:167], v[136:139]
	v_mfma_f32_16x16x32_bf16 v[132:135], v[156:159], v[164:167], v[132:135]
	v_mfma_f32_16x16x32_bf16 v[112:115], v[140:143], v[172:175], v[112:115]
	v_mfma_f32_16x16x32_bf16 v[108:111], v[156:159], v[172:175], v[108:111]
	v_mfma_f32_16x16x32_bf16 v[88:91], v[140:143], v[180:183], v[88:91]
	v_mfma_f32_16x16x32_bf16 v[80:83], v[156:159], v[180:183], v[80:83]
	v_mfma_f32_16x16x32_bf16 v[68:71], v[140:143], v[212:215], v[68:71]
	v_mfma_f32_16x16x32_bf16 v[64:67], v[156:159], v[212:215], v[64:67]
	s_setprio 0
	s_barrier
	s_add_i32 s33, s81, s14
	v_lshl_add_u64 v[216:217], s[70:71], 0, v[190:191]
	s_mov_b32 m0, s33
	ds_read_b128 v[160:163], v223 offset:16384
	ds_read_b128 v[164:167], v223 offset:17408
	ds_read_b128 v[168:171], v223 offset:18432
	ds_read_b128 v[172:175], v223 offset:19456
	ds_read_b128 v[176:179], v223 offset:20480
	ds_read_b128 v[180:183], v223 offset:21504
	ds_read_b128 v[184:187], v223 offset:22528
	ds_read_b128 v[212:215], v223 offset:23552
	global_load_lds_dwordx4 v[216:217], off
	v_lshl_add_u64 v[228:229], v[216:217], 0, s[8:9]
	s_add_i32 m0, s33, 0x2000
	s_add_i32 s33, s82, s14
	global_load_lds_dwordx4 v[228:229], off
	v_lshl_add_u64 v[228:229], v[216:217], 0, s[10:11]
	s_mov_b32 m0, s33
	s_nop 0
	global_load_lds_dwordx4 v[228:229], off
	v_lshl_add_u64 v[228:229], v[216:217], 0, s[40:41]
	s_add_i32 m0, s33, 0x2000
	s_nop 0
	global_load_lds_dwordx4 v[228:229], off
	v_lshl_add_u64 v[228:229], s[68:69], 0, v[190:191]
	s_mov_b32 m0, s15
	v_lshl_add_u64 v[230:231], v[228:229], 0, s[8:9]
	global_load_lds_dwordx4 v[228:229], off
	s_mov_b32 m0, s17
	s_nop 0
	global_load_lds_dwordx4 v[230:231], off
	s_waitcnt vmcnt(8)
	s_waitcnt lgkmcnt(0)
	s_barrier
; #define PG8_STAGE(bufoff, gbase, voff) do { _Pragma("unroll") for (int _i = 0; _i < 2; ++_i) \
;         __builtin_amdgcn_global_load_lds((const unsigned*)((const char*)(gbase) + (voff)[_i]), (PG8_LAS unsigned*)(lds + (bufoff) + ldsw + _i * 8192), 16, 0, 0); } while (0)
; #define PG8_LDA(dst, b, h) do { _Pragma("unroll") for (int m = 0; m < 4; ++m) _Pragma("unroll") for (int k = 0; k < 2; ++k) dst[m][k] = *(const PG8_LAS bf16x8*)(lds + PG8_SA(b, h) + aoff + m * 2048 + k * 1024); } while (0)
; #define PG8_LDB(dst, b, h) do { _Pragma("unroll") for (int n = 0; n < 2; ++n) _Pragma("unroll") for (int k = 0; k < 2; ++k) dst[n][k] = *(const PG8_LAS bf16x8*)(lds + PG8_SB(b, h) + boff + n * 2048 + k * 1024); } while (0)
; #define PG8_MMA(ai, bj, At, Bt) do { __builtin_amdgcn_s_setprio(1); _Pragma("unroll") for (int m = 0; m < 4; ++m) _Pragma("unroll") for (int n = 0; n < 2; ++n) _Pragma("unroll") for (int k = 0; k < 2; ++k) \
;         acc[ai][bj][m][n] = __builtin_amdgcn_mfma_f32_16x16x32_bf16(Bt[n][k], At[m][k], acc[ai][bj][m][n], 0, 0, 0); __builtin_amdgcn_s_setprio(0); } while (0)
; #define PG8_WAIT_V(n) asm volatile("s_waitcnt vmcnt(" #n ")" ::: "memory")
; #define PG8_WAIT_L(n) asm volatile("s_waitcnt lgkmcnt(" #n ")" ::: "memory")
; #define PG8_BAR __builtin_amdgcn_s_barrier()
; #define PG8_SCHED __builtin_amdgcn_sched_barrier(0)
; template <class Epi, class Sched, bool ALIGN_EPI = false, bool SP2 = false>
; __device__ __forceinline__ void gemm_phase(PG8_LAS unsigned char* lds, const Gemm g, const Sched& S, const Epi& E) {
;     ...
;             PG8_WAIT_V(8); PG8_WAIT_L(0); PG8_BAR; PG8_MMA(1, 0, At, B0); PG8_MMA(1, 1, At, B1); PG8_BAR; PG8_SCHED;
;             PG8_LDB(B0, 1, 0); PG8_LDB(B1, 1, 1); PG8_SCHED; PG8_LDA(At, 1, 0); PG8_STAGE(PG8_SA(0, 1), a2 + hstepA, voffA);
;             PG8_WAIT_V(8); PG8_WAIT_L(0); PG8_BAR; PG8_MMA(0, 0, At, B0); PG8_MMA(0, 1, At, B1); PG8_BAR; PG8_SCHED;
	s_setprio 1
	s_waitcnt lgkmcnt(0)
	v_mfma_f32_16x16x32_bf16 v[60:63], v[84:87], v[160:163], 0
	v_mfma_f32_16x16x32_bf16 v[56:59], v[104:107], v[160:163], 0
	v_mfma_f32_16x16x32_bf16 v[44:47], v[84:87], v[168:171], 0
	v_mfma_f32_16x16x32_bf16 v[40:43], v[104:107], v[168:171], 0
	v_mfma_f32_16x16x32_bf16 v[28:31], v[84:87], v[176:179], 0
	v_mfma_f32_16x16x32_bf16 v[24:27], v[104:107], v[176:179], 0
	v_mfma_f32_16x16x32_bf16 v[12:15], v[84:87], v[184:187], 0
	v_mfma_f32_16x16x32_bf16 v[8:11], v[104:107], v[184:187], 0
	v_mfma_f32_16x16x32_bf16 v[60:63], v[92:95], v[164:167], v[60:63]
	v_mfma_f32_16x16x32_bf16 v[56:59], v[116:119], v[164:167], v[56:59]
	v_mfma_f32_16x16x32_bf16 v[44:47], v[92:95], v[172:175], v[44:47]
	v_mfma_f32_16x16x32_bf16 v[40:43], v[116:119], v[172:175], v[40:43]
	v_mfma_f32_16x16x32_bf16 v[28:31], v[92:95], v[180:183], v[28:31]
	v_mfma_f32_16x16x32_bf16 v[24:27], v[116:119], v[180:183], v[24:27]
	v_mfma_f32_16x16x32_bf16 v[12:15], v[92:95], v[212:215], v[12:15]
	v_mfma_f32_16x16x32_bf16 v[8:11], v[116:119], v[212:215], v[8:11]
	s_setprio 0
	s_setprio 1
	v_mfma_f32_16x16x32_bf16 v[52:55], v[128:131], v[160:163], 0
	v_mfma_f32_16x16x32_bf16 v[48:51], v[152:155], v[160:163], 0
	v_mfma_f32_16x16x32_bf16 v[36:39], v[128:131], v[168:171], 0
	v_mfma_f32_16x16x32_bf16 v[32:35], v[152:155], v[168:171], 0
	v_mfma_f32_16x16x32_bf16 v[20:23], v[128:131], v[176:179], 0
	v_mfma_f32_16x16x32_bf16 v[16:19], v[152:155], v[176:179], 0
	v_mfma_f32_16x16x32_bf16 v[4:7], v[128:131], v[184:187], 0
	v_mfma_f32_16x16x32_bf16 v[0:3], v[152:155], v[184:187], 0
	v_mfma_f32_16x16x32_bf16 v[52:55], v[140:143], v[164:167], v[52:55]
	v_mfma_f32_16x16x32_bf16 v[48:51], v[156:159], v[164:167], v[48:51]
	v_mfma_f32_16x16x32_bf16 v[36:39], v[140:143], v[172:175], v[36:39]
	v_mfma_f32_16x16x32_bf16 v[32:35], v[156:159], v[172:175], v[32:35]
	v_mfma_f32_16x16x32_bf16 v[20:23], v[140:143], v[180:183], v[20:23]
	v_mfma_f32_16x16x32_bf16 v[16:19], v[156:159], v[180:183], v[16:19]
	v_mfma_f32_16x16x32_bf16 v[4:7], v[140:143], v[212:215], v[4:7]
	v_mfma_f32_16x16x32_bf16 v[0:3], v[156:159], v[212:215], v[0:3]
	s_setprio 0
	s_barrier
	ds_read_b128 v[84:87], v224
	ds_read_b128 v[92:95], v224 offset:1024
	ds_read_b128 v[104:107], v224 offset:2048
	ds_read_b128 v[116:119], v224 offset:3072
	ds_read_b128 v[128:131], v225
	ds_read_b128 v[140:143], v225 offset:1024
	ds_read_b128 v[152:155], v225 offset:2048
	ds_read_b128 v[156:159], v225 offset:3072
	s_mov_b32 m0, s18
	v_lshl_add_u64 v[230:231], v[228:229], 0, s[10:11]
	ds_read_b128 v[160:163], v223 offset:32768
	ds_read_b128 v[164:167], v223 offset:33792
	ds_read_b128 v[168:171], v223 offset:34816
	ds_read_b128 v[172:175], v223 offset:35840
	ds_read_b128 v[176:179], v223 offset:36864
	ds_read_b128 v[180:183], v223 offset:37888
	ds_read_b128 v[184:187], v223 offset:38912
	ds_read_b128 v[212:215], v223 offset:39936
	global_load_lds_dwordx4 v[230:231], off
	v_lshl_add_u64 v[230:231], v[228:229], 0, s[40:41]
	s_mov_b32 m0, s19
	s_nop 0
	global_load_lds_dwordx4 v[230:231], off
	s_waitcnt vmcnt(8)
	s_waitcnt lgkmcnt(0)
	s_barrier
	s_setprio 1
	s_waitcnt lgkmcnt(0)
	v_mfma_f32_16x16x32_bf16 v[148:151], v[84:87], v[160:163], v[148:151]
	v_mfma_f32_16x16x32_bf16 v[144:147], v[104:107], v[160:163], v[144:147]
	v_mfma_f32_16x16x32_bf16 v[124:127], v[84:87], v[168:171], v[124:127]
	v_mfma_f32_16x16x32_bf16 v[120:123], v[104:107], v[168:171], v[120:123]
	v_mfma_f32_16x16x32_bf16 v[100:103], v[84:87], v[176:179], v[100:103]
	v_mfma_f32_16x16x32_bf16 v[96:99], v[104:107], v[176:179], v[96:99]
	v_mfma_f32_16x16x32_bf16 v[76:79], v[84:87], v[184:187], v[76:79]
	v_mfma_f32_16x16x32_bf16 v[72:75], v[104:107], v[184:187], v[72:75]
	v_mfma_f32_16x16x32_bf16 v[148:151], v[92:95], v[164:167], v[148:151]
	v_mfma_f32_16x16x32_bf16 v[144:147], v[116:119], v[164:167], v[144:147]
	v_mfma_f32_16x16x32_bf16 v[124:127], v[92:95], v[172:175], v[124:127]
	v_mfma_f32_16x16x32_bf16 v[120:123], v[116:119], v[172:175], v[120:123]
	v_mfma_f32_16x16x32_bf16 v[100:103], v[92:95], v[180:183], v[100:103]
	v_mfma_f32_16x16x32_bf16 v[96:99], v[116:119], v[180:183], v[96:99]
	v_mfma_f32_16x16x32_bf16 v[76:79], v[92:95], v[212:215], v[76:79]
	v_mfma_f32_16x16x32_bf16 v[72:75], v[116:119], v[212:215], v[72:75]
	s_setprio 0
	s_setprio 1
	v_mfma_f32_16x16x32_bf16 v[136:139], v[128:131], v[160:163], v[136:139]
	v_mfma_f32_16x16x32_bf16 v[132:135], v[152:155], v[160:163], v[132:135]
	v_mfma_f32_16x16x32_bf16 v[112:115], v[128:131], v[168:171], v[112:115]
	v_mfma_f32_16x16x32_bf16 v[108:111], v[152:155], v[168:171], v[108:111]
	v_mfma_f32_16x16x32_bf16 v[88:91], v[128:131], v[176:179], v[88:91]
	v_mfma_f32_16x16x32_bf16 v[80:83], v[152:155], v[176:179], v[80:83]
	v_mfma_f32_16x16x32_bf16 v[68:71], v[128:131], v[184:187], v[68:71]
	v_mfma_f32_16x16x32_bf16 v[64:67], v[152:155], v[184:187], v[64:67]
	v_mfma_f32_16x16x32_bf16 v[136:139], v[140:143], v[164:167], v[136:139]
	v_mfma_f32_16x16x32_bf16 v[132:135], v[156:159], v[164:167], v[132:135]
	v_mfma_f32_16x16x32_bf16 v[112:115], v[140:143], v[172:175], v[112:115]
	v_mfma_f32_16x16x32_bf16 v[108:111], v[156:159], v[172:175], v[108:111]
	v_mfma_f32_16x16x32_bf16 v[88:91], v[140:143], v[180:183], v[88:91]
	v_mfma_f32_16x16x32_bf16 v[80:83], v[156:159], v[180:183], v[80:83]
	v_mfma_f32_16x16x32_bf16 v[68:71], v[140:143], v[212:215], v[68:71]
	v_mfma_f32_16x16x32_bf16 v[64:67], v[156:159], v[212:215], v[64:67]
	s_setprio 0
	s_barrier
; #define PG8_STAGE(bufoff, gbase, voff) do { _Pragma("unroll") for (int _i = 0; _i < 2; ++_i) \
;         __builtin_amdgcn_global_load_lds((const unsigned*)((const char*)(gbase) + (voff)[_i]), (PG8_LAS unsigned*)(lds + (bufoff) + ldsw + _i * 8192), 16, 0, 0); } while (0)
; #define PG8_LDA(dst, b, h) do { _Pragma("unroll") for (int m = 0; m < 4; ++m) _Pragma("unroll") for (int k = 0; k < 2; ++k) dst[m][k] = *(const PG8_LAS bf16x8*)(lds + PG8_SA(b, h) + aoff + m * 2048 + k * 1024); } while (0)
; #define PG8_MMA(ai, bj, At, Bt) do { __builtin_amdgcn_s_setprio(1); _Pragma("unroll") for (int m = 0; m < 4; ++m) _Pragma("unroll") for (int n = 0; n < 2; ++n) _Pragma("unroll") for (int k = 0; k < 2; ++k) \
;         acc[ai][bj][m][n] = __builtin_amdgcn_mfma_f32_16x16x32_bf16(Bt[n][k], At[m][k], acc[ai][bj][m][n], 0, 0, 0); __builtin_amdgcn_s_setprio(0); } while (0)
; #define PG8_WAIT_V(n) asm volatile("s_waitcnt vmcnt(" #n ")" ::: "memory")
; #define PG8_WAIT_L(n) asm volatile("s_waitcnt lgkmcnt(" #n ")" ::: "memory")
; #define PG8_BAR __builtin_amdgcn_s_barrier()
; #define PG8_SCHED __builtin_amdgcn_sched_barrier(0)
; template <class Epi, class Sched, bool ALIGN_EPI = false, bool SP2 = false>
; __device__ __forceinline__ void gemm_phase(PG8_LAS unsigned char* lds, const Gemm g, const Sched& S, const Epi& E) {
;     ...
;         for (int t = 0; t < nt; t += 2) {
;             const bool last = (t == nt - 2);
;             const char* a1 = cA + (size_t)(t + 1) * kstepA;
;             const char* a2 = last ? nA : cA + (size_t)(t + 2) * kstepA; const char* b2 = last ? nB : cB + (size_t)(t + 2) * kstep;
;             const char* a3 = a2 + kstepA; const char* b3 = b2 + kstep;
;     ...
;             PG8_LDA(At, 1, 1); PG8_STAGE(PG8_SB(1, 0), b3, voffB); PG8_STAGE(PG8_SB(1, 1), b3 + hstepB, voffB); PG8_STAGE(PG8_SA(1, 0), a3, voffA);
;             PG8_WAIT_V(8); PG8_WAIT_L(0); PG8_BAR; PG8_MMA(1, 0, At, B0); PG8_MMA(1, 1, At, B1); PG8_BAR; PG8_SCHED;
	s_add_i32 s33, s83, s14
	v_lshl_add_u64 v[230:231], v[216:217], 0, s[42:43]
	s_mov_b32 m0, s33
	ds_read_b128 v[160:163], v223 offset:49152
	ds_read_b128 v[164:167], v223 offset:50176
	ds_read_b128 v[168:171], v223 offset:51200
	ds_read_b128 v[172:175], v223 offset:52224
	ds_read_b128 v[176:179], v223 offset:53248
	ds_read_b128 v[180:183], v223 offset:54272
	ds_read_b128 v[184:187], v223 offset:55296
	ds_read_b128 v[212:215], v223 offset:56320
	global_load_lds_dwordx4 v[230:231], off
	v_lshl_add_u64 v[230:231], v[216:217], 0, s[44:45]
	s_add_i32 m0, s33, 0x2000
	s_add_i32 s33, s84, s14
	global_load_lds_dwordx4 v[230:231], off
	v_lshl_add_u64 v[230:231], v[216:217], 0, s[46:47]
	s_mov_b32 m0, s33
	v_lshl_add_u64 v[216:217], v[216:217], 0, s[48:49]
	global_load_lds_dwordx4 v[230:231], off
	s_add_i32 m0, s33, 0x2000
	s_nop 0
	global_load_lds_dwordx4 v[216:217], off
	v_lshl_add_u64 v[216:217], v[228:229], 0, s[42:43]
	s_mov_b32 m0, s74
	s_nop 0
	global_load_lds_dwordx4 v[216:217], off
	v_lshl_add_u64 v[216:217], v[228:229], 0, s[44:45]
	s_mov_b32 m0, s75
	s_nop 0
	global_load_lds_dwordx4 v[216:217], off
	s_waitcnt vmcnt(8)
	s_waitcnt lgkmcnt(0)
	s_barrier
	s_setprio 1
	s_waitcnt lgkmcnt(0)
	v_mfma_f32_16x16x32_bf16 v[60:63], v[84:87], v[160:163], v[60:63]
	v_mfma_f32_16x16x32_bf16 v[56:59], v[104:107], v[160:163], v[56:59]
	v_mfma_f32_16x16x32_bf16 v[44:47], v[84:87], v[168:171], v[44:47]
	v_mfma_f32_16x16x32_bf16 v[40:43], v[104:107], v[168:171], v[40:43]
	v_mfma_f32_16x16x32_bf16 v[28:31], v[84:87], v[176:179], v[28:31]
	v_mfma_f32_16x16x32_bf16 v[24:27], v[104:107], v[176:179], v[24:27]
	v_mfma_f32_16x16x32_bf16 v[12:15], v[84:87], v[184:187], v[12:15]
	v_mfma_f32_16x16x32_bf16 v[8:11], v[104:107], v[184:187], v[8:11]
	v_mfma_f32_16x16x32_bf16 v[60:63], v[92:95], v[164:167], v[60:63]
	v_mfma_f32_16x16x32_bf16 v[56:59], v[116:119], v[164:167], v[56:59]
	v_mfma_f32_16x16x32_bf16 v[44:47], v[92:95], v[172:175], v[44:47]
	v_mfma_f32_16x16x32_bf16 v[40:43], v[116:119], v[172:175], v[40:43]
	v_mfma_f32_16x16x32_bf16 v[28:31], v[92:95], v[180:183], v[28:31]
	v_mfma_f32_16x16x32_bf16 v[24:27], v[116:119], v[180:183], v[24:27]
	v_mfma_f32_16x16x32_bf16 v[12:15], v[92:95], v[212:215], v[12:15]
	v_mfma_f32_16x16x32_bf16 v[8:11], v[116:119], v[212:215], v[8:11]
	s_setprio 0
	s_setprio 1
	v_mfma_f32_16x16x32_bf16 v[52:55], v[128:131], v[160:163], v[52:55]
	v_mfma_f32_16x16x32_bf16 v[48:51], v[152:155], v[160:163], v[48:51]
	v_mfma_f32_16x16x32_bf16 v[36:39], v[128:131], v[168:171], v[36:39]
	v_mfma_f32_16x16x32_bf16 v[32:35], v[152:155], v[168:171], v[32:35]
	v_mfma_f32_16x16x32_bf16 v[20:23], v[128:131], v[176:179], v[20:23]
	v_mfma_f32_16x16x32_bf16 v[16:19], v[152:155], v[176:179], v[16:19]
	v_mfma_f32_16x16x32_bf16 v[4:7], v[128:131], v[184:187], v[4:7]
	v_mfma_f32_16x16x32_bf16 v[0:3], v[152:155], v[184:187], v[0:3]
	v_mfma_f32_16x16x32_bf16 v[52:55], v[140:143], v[164:167], v[52:55]
	v_mfma_f32_16x16x32_bf16 v[48:51], v[156:159], v[164:167], v[48:51]
	v_mfma_f32_16x16x32_bf16 v[36:39], v[140:143], v[172:175], v[36:39]
	v_mfma_f32_16x16x32_bf16 v[32:35], v[156:159], v[172:175], v[32:35]
	v_mfma_f32_16x16x32_bf16 v[20:23], v[140:143], v[180:183], v[20:23]
	v_mfma_f32_16x16x32_bf16 v[16:19], v[156:159], v[180:183], v[16:19]
	v_mfma_f32_16x16x32_bf16 v[4:7], v[140:143], v[212:215], v[4:7]
	v_mfma_f32_16x16x32_bf16 v[0:3], v[156:159], v[212:215], v[0:3]
	s_setprio 0
	s_barrier
	s_add_i32 s66, s66, 2
	s_add_u32 s6, s6, 0x10000
	s_addc_u32 s7, s7, 0
	s_add_u32 s64, s64, 0x10000
	s_addc_u32 s65, s65, 0
	s_cmp_gt_u32 s66, 41

; #define PG8_STAGE(bufoff, gbase, voff) do { _Pragma("unroll") for (int _i = 0; _i < 2; ++_i) \
;         __builtin_amdgcn_global_load_lds((const unsigned*)((const char*)(gbase) + (voff)[_i]), (PG8_LAS unsigned*)(lds + (bufoff) + ldsw + _i * 8192), 16, 0, 0); } while (0)
; #define PG8_LDA(dst, b, h) do { _Pragma("unroll") for (int m = 0; m < 4; ++m) _Pragma("unroll") for (int k = 0; k < 2; ++k) dst[m][k] = *(const PG8_LAS bf16x8*)(lds + PG8_SA(b, h) + aoff + m * 2048 + k * 1024); } while (0)
; #define PG8_LDB(dst, b, h) do { _Pragma("unroll") for (int n = 0; n < 2; ++n) _Pragma("unroll") for (int k = 0; k < 2; ++k) dst[n][k] = *(const PG8_LAS bf16x8*)(lds + PG8_SB(b, h) + boff + n * 2048 + k * 1024); } while (0)
; #define PG8_WAIT_V(n) asm volatile("s_waitcnt vmcnt(" #n ")" ::: "memory")
; #define PG8_BAR __builtin_amdgcn_s_barrier()
; template <class Epi, class Sched, bool ALIGN_EPI = false, bool SP2 = false>
; __device__ __forceinline__ void gemm_phase(PG8_LAS unsigned char* lds, const Gemm g, const Sched& S, const Epi& E) {
;     ...
;         const bool has_next = S.next(ui + 1, nxt);
;         const char* nA = has_next ? (const char*)g.A + (size_t)nxt.pm * tstepA : cA; const char* nB = has_next ? (const char*)g.Bt + (size_t)nxt.pn * tstepB : cB;
;         for (int t = 0; t < nt; t += 2) {
;             const bool last = (t == nt - 2);
;             const char* a1 = cA + (size_t)(t + 1) * kstepA;
;             const char* a2 = last ? nA : cA + (size_t)(t + 2) * kstepA; const char* b2 = last ? nB : cB + (size_t)(t + 2) * kstep;
;             const char* a3 = a2 + kstepA; const char* b3 = b2 + kstep;
;             if (last && has_next) S.a_ready(nxt);
;             if constexpr (SP2) {
;             PG8_LDB(B0, 0, 0); PG8_LDB(B1, 0, 1); PG8_SCHED; PG8_LDA(At, 0, 0); PG8_STAGE(PG8_SA(1, 1), a1 + hstepA, voffA);
;             PG8_WAIT_V(8); PG8_WAIT_L(0); PG8_BAR; PG8_MMA(0, 0, At, B0); PG8_MMA(0, 1, At, B1); PG8_BAR; PG8_SCHED;
;             PG8_LDA(At, 0, 1); PG8_STAGE(PG8_SB(0, 0), b2, voffB); PG8_STAGE(PG8_SB(0, 1), b2 + hstepB, voffB); PG8_STAGE(PG8_SA(0, 0), a2, voffA);
;     ...
; #pragma unroll
;         for (int a = 0; a < 2; ++a)
; #pragma unroll
;             for (int b = 0; b < 2; ++b)
; #pragma unroll
;                 for (int m = 0; m < 4; ++m)
; #pragma unroll
;                     for (int n = 0; n < 2; ++n) acc[a][b][m][n] = (f32x4){0.f, 0.f, 0.f, 0.f};
.LBB0_1003:
	s_add_u32 s70, s70, 0x10000
	s_addc_u32 s71, s71, 0
	s_add_u32 s69, s72, 0x10000
	s_addc_u32 s72, s73, 0
	s_mov_b32 s73, -2
	ds_read_b128 v[128:131], v220
	ds_read_b128 v[132:135], v220 offset:1024
	ds_read_b128 v[136:139], v220 offset:2048
	ds_read_b128 v[140:143], v220 offset:3072
	ds_read_b128 v[144:147], v221
	ds_read_b128 v[148:151], v221 offset:1024
	ds_read_b128 v[152:155], v221 offset:2048
	ds_read_b128 v[156:159], v221 offset:3072
	s_cmp_eq_u32 s73, 40
	s_cselect_b32 s75, s1, s71
	s_cselect_b32 s74, s0, s70
	s_cselect_b32 s77, s67, s72
	s_cselect_b32 s76, s66, s69
	v_lshl_add_u64 v[238:239], s[70:71], 0, v[190:191]
	v_lshl_add_u64 v[240:241], v[238:239], 0, s[62:63]
	s_add_i32 m0, s15, 0xc000
	ds_read_b128 v[160:163], v222
	ds_read_b128 v[164:167], v222 offset:1024
	ds_read_b128 v[168:171], v222 offset:2048
	ds_read_b128 v[172:175], v222 offset:3072
	ds_read_b128 v[176:179], v222 offset:4096
	ds_read_b128 v[180:183], v222 offset:5120
	ds_read_b128 v[230:233], v222 offset:6144
	ds_read_b128 v[234:237], v222 offset:7168
	global_load_lds_dwordx4 v[240:241], off
	v_lshl_add_u64 v[238:239], v[238:239], 0, s[64:65]
	s_add_i32 m0, s15, 0xe000
	s_nop 0
	global_load_lds_dwordx4 v[238:239], off
	s_waitcnt vmcnt(8)
	s_waitcnt lgkmcnt(0)
	s_barrier
	s_setprio 1
	s_waitcnt lgkmcnt(0)
	v_mfma_f32_16x16x32_bf16 v[124:127], v[128:131], v[160:163], 0
	v_mfma_f32_16x16x32_bf16 v[120:123], v[136:139], v[160:163], 0
	v_mfma_f32_16x16x32_bf16 v[108:111], v[128:131], v[168:171], 0
	v_mfma_f32_16x16x32_bf16 v[104:107], v[136:139], v[168:171], 0
	v_mfma_f32_16x16x32_bf16 v[92:95], v[128:131], v[176:179], 0
	v_mfma_f32_16x16x32_bf16 v[88:91], v[136:139], v[176:179], 0
	v_mfma_f32_16x16x32_bf16 v[76:79], v[128:131], v[230:233], 0
	v_mfma_f32_16x16x32_bf16 v[72:75], v[136:139], v[230:233], 0
	v_mfma_f32_16x16x32_bf16 v[124:127], v[132:135], v[164:167], v[124:127]
	v_mfma_f32_16x16x32_bf16 v[120:123], v[140:143], v[164:167], v[120:123]
	v_mfma_f32_16x16x32_bf16 v[108:111], v[132:135], v[172:175], v[108:111]
	v_mfma_f32_16x16x32_bf16 v[104:107], v[140:143], v[172:175], v[104:107]
	v_mfma_f32_16x16x32_bf16 v[92:95], v[132:135], v[180:183], v[92:95]
	v_mfma_f32_16x16x32_bf16 v[88:91], v[140:143], v[180:183], v[88:91]
	v_mfma_f32_16x16x32_bf16 v[76:79], v[132:135], v[234:237], v[76:79]
	v_mfma_f32_16x16x32_bf16 v[72:75], v[140:143], v[234:237], v[72:75]
	s_setprio 0
	s_setprio 1
	v_mfma_f32_16x16x32_bf16 v[116:119], v[144:147], v[160:163], 0
	v_mfma_f32_16x16x32_bf16 v[112:115], v[152:155], v[160:163], 0
	v_mfma_f32_16x16x32_bf16 v[100:103], v[144:147], v[168:171], 0
	v_mfma_f32_16x16x32_bf16 v[96:99], v[152:155], v[168:171], 0
	v_mfma_f32_16x16x32_bf16 v[84:87], v[144:147], v[176:179], 0
	v_mfma_f32_16x16x32_bf16 v[80:83], v[152:155], v[176:179], 0
	v_mfma_f32_16x16x32_bf16 v[68:71], v[144:147], v[230:233], 0
	v_mfma_f32_16x16x32_bf16 v[64:67], v[152:155], v[230:233], 0
	v_mfma_f32_16x16x32_bf16 v[116:119], v[148:151], v[164:167], v[116:119]
	v_mfma_f32_16x16x32_bf16 v[112:115], v[156:159], v[164:167], v[112:115]
	v_mfma_f32_16x16x32_bf16 v[100:103], v[148:151], v[172:175], v[100:103]
	v_mfma_f32_16x16x32_bf16 v[96:99], v[156:159], v[172:175], v[96:99]
	v_mfma_f32_16x16x32_bf16 v[84:87], v[148:151], v[180:183], v[84:87]
	v_mfma_f32_16x16x32_bf16 v[80:83], v[156:159], v[180:183], v[80:83]
	v_mfma_f32_16x16x32_bf16 v[68:71], v[148:151], v[234:237], v[68:71]
	v_mfma_f32_16x16x32_bf16 v[64:67], v[156:159], v[234:237], v[64:67]
	s_setprio 0
	s_barrier
	s_add_i32 s33, s86, s14
	v_lshl_add_u64 v[238:239], s[76:77], 0, v[190:191]
	s_mov_b32 m0, s33
	ds_read_b128 v[160:163], v222 offset:16384
	ds_read_b128 v[164:167], v222 offset:17408
	ds_read_b128 v[168:171], v222 offset:18432
	ds_read_b128 v[172:175], v222 offset:19456
	ds_read_b128 v[176:179], v222 offset:20480
	ds_read_b128 v[180:183], v222 offset:21504
	ds_read_b128 v[230:233], v222 offset:22528
	ds_read_b128 v[234:237], v222 offset:23552
	global_load_lds_dwordx4 v[238:239], off
	v_lshl_add_u64 v[240:241], v[238:239], 0, s[40:41]
	s_add_i32 m0, s33, 0x2000
	s_add_i32 s33, s87, s14
	global_load_lds_dwordx4 v[240:241], off
	v_lshl_add_u64 v[240:241], v[238:239], 0, s[42:43]
	s_mov_b32 m0, s33
	s_nop 0
	global_load_lds_dwordx4 v[240:241], off
	v_lshl_add_u64 v[240:241], v[238:239], 0, s[44:45]
	s_add_i32 m0, s33, 0x2000
	s_nop 0
	global_load_lds_dwordx4 v[240:241], off
	v_lshl_add_u64 v[240:241], s[74:75], 0, v[190:191]
	s_mov_b32 m0, s15
	v_lshl_add_u64 v[242:243], v[240:241], 0, s[40:41]
	global_load_lds_dwordx4 v[240:241], off
	s_mov_b32 m0, s17
	s_nop 0
	global_load_lds_dwordx4 v[242:243], off
	s_waitcnt vmcnt(8)
	s_waitcnt lgkmcnt(0)
	s_barrier
; #define PG8_STAGE(bufoff, gbase, voff) do { _Pragma("unroll") for (int _i = 0; _i < 2; ++_i) \
;         __builtin_amdgcn_global_load_lds((const unsigned*)((const char*)(gbase) + (voff)[_i]), (PG8_LAS unsigned*)(lds + (bufoff) + ldsw + _i * 8192), 16, 0, 0); } while (0)
; #define PG8_LDA(dst, b, h) do { _Pragma("unroll") for (int m = 0; m < 4; ++m) _Pragma("unroll") for (int k = 0; k < 2; ++k) dst[m][k] = *(const PG8_LAS bf16x8*)(lds + PG8_SA(b, h) + aoff + m * 2048 + k * 1024); } while (0)
; #define PG8_LDB(dst, b, h) do { _Pragma("unroll") for (int n = 0; n < 2; ++n) _Pragma("unroll") for (int k = 0; k < 2; ++k) dst[n][k] = *(const PG8_LAS bf16x8*)(lds + PG8_SB(b, h) + boff + n * 2048 + k * 1024); } while (0)
; #define PG8_MMA(ai, bj, At, Bt) do { __builtin_amdgcn_s_setprio(1); _Pragma("unroll") for (int m = 0; m < 4; ++m) _Pragma("unroll") for (int n = 0; n < 2; ++n) _Pragma("unroll") for (int k = 0; k < 2; ++k) \
;         acc[ai][bj][m][n] = __builtin_amdgcn_mfma_f32_16x16x32_bf16(Bt[n][k], At[m][k], acc[ai][bj][m][n], 0, 0, 0); __builtin_amdgcn_s_setprio(0); } while (0)
; #define PG8_WAIT_V(n) asm volatile("s_waitcnt vmcnt(" #n ")" ::: "memory")
; #define PG8_WAIT_L(n) asm volatile("s_waitcnt lgkmcnt(" #n ")" ::: "memory")
; #define PG8_BAR __builtin_amdgcn_s_barrier()
; #define PG8_SCHED __builtin_amdgcn_sched_barrier(0)
; template <class Epi, class Sched, bool ALIGN_EPI = false, bool SP2 = false>
; __device__ __forceinline__ void gemm_phase(PG8_LAS unsigned char* lds, const Gemm g, const Sched& S, const Epi& E) {
;     ...
;             PG8_WAIT_V(8); PG8_WAIT_L(0); PG8_BAR; PG8_MMA(1, 0, At, B0); PG8_MMA(1, 1, At, B1); PG8_BAR; PG8_SCHED;
;             PG8_LDB(B0, 1, 0); PG8_LDB(B1, 1, 1); PG8_SCHED; PG8_LDA(At, 1, 0); PG8_STAGE(PG8_SA(0, 1), a2 + hstepA, voffA);
;             PG8_WAIT_V(8); PG8_WAIT_L(0); PG8_BAR; PG8_MMA(0, 0, At, B0); PG8_MMA(0, 1, At, B1); PG8_BAR; PG8_SCHED;
	s_setprio 1
	s_waitcnt lgkmcnt(0)
	v_mfma_f32_16x16x32_bf16 v[60:63], v[128:131], v[160:163], 0
	v_mfma_f32_16x16x32_bf16 v[56:59], v[136:139], v[160:163], 0
	v_mfma_f32_16x16x32_bf16 v[44:47], v[128:131], v[168:171], 0
	v_mfma_f32_16x16x32_bf16 v[40:43], v[136:139], v[168:171], 0
	v_mfma_f32_16x16x32_bf16 v[28:31], v[128:131], v[176:179], 0
	v_mfma_f32_16x16x32_bf16 v[24:27], v[136:139], v[176:179], 0
	v_mfma_f32_16x16x32_bf16 v[12:15], v[128:131], v[230:233], 0
	v_mfma_f32_16x16x32_bf16 v[8:11], v[136:139], v[230:233], 0
	v_mfma_f32_16x16x32_bf16 v[60:63], v[132:135], v[164:167], v[60:63]
	v_mfma_f32_16x16x32_bf16 v[56:59], v[140:143], v[164:167], v[56:59]
	v_mfma_f32_16x16x32_bf16 v[44:47], v[132:135], v[172:175], v[44:47]
	v_mfma_f32_16x16x32_bf16 v[40:43], v[140:143], v[172:175], v[40:43]
	v_mfma_f32_16x16x32_bf16 v[28:31], v[132:135], v[180:183], v[28:31]
	v_mfma_f32_16x16x32_bf16 v[24:27], v[140:143], v[180:183], v[24:27]
	v_mfma_f32_16x16x32_bf16 v[12:15], v[132:135], v[234:237], v[12:15]
	v_mfma_f32_16x16x32_bf16 v[8:11], v[140:143], v[234:237], v[8:11]
	s_setprio 0
	s_setprio 1
	v_mfma_f32_16x16x32_bf16 v[52:55], v[144:147], v[160:163], 0
	v_mfma_f32_16x16x32_bf16 v[48:51], v[152:155], v[160:163], 0
	v_mfma_f32_16x16x32_bf16 v[36:39], v[144:147], v[168:171], 0
	v_mfma_f32_16x16x32_bf16 v[32:35], v[152:155], v[168:171], 0
	v_mfma_f32_16x16x32_bf16 v[20:23], v[144:147], v[176:179], 0
	v_mfma_f32_16x16x32_bf16 v[16:19], v[152:155], v[176:179], 0
	v_mfma_f32_16x16x32_bf16 v[4:7], v[144:147], v[230:233], 0
	v_mfma_f32_16x16x32_bf16 v[0:3], v[152:155], v[230:233], 0
	v_mfma_f32_16x16x32_bf16 v[52:55], v[148:151], v[164:167], v[52:55]
	v_mfma_f32_16x16x32_bf16 v[48:51], v[156:159], v[164:167], v[48:51]
	v_mfma_f32_16x16x32_bf16 v[36:39], v[148:151], v[172:175], v[36:39]
	v_mfma_f32_16x16x32_bf16 v[32:35], v[156:159], v[172:175], v[32:35]
	v_mfma_f32_16x16x32_bf16 v[20:23], v[148:151], v[180:183], v[20:23]
	v_mfma_f32_16x16x32_bf16 v[16:19], v[156:159], v[180:183], v[16:19]
	v_mfma_f32_16x16x32_bf16 v[4:7], v[148:151], v[234:237], v[4:7]
	v_mfma_f32_16x16x32_bf16 v[0:3], v[156:159], v[234:237], v[0:3]
	s_setprio 0
	s_barrier
	ds_read_b128 v[128:131], v223
	ds_read_b128 v[132:135], v223 offset:1024
	ds_read_b128 v[136:139], v223 offset:2048
	ds_read_b128 v[140:143], v223 offset:3072
	ds_read_b128 v[144:147], v224
	ds_read_b128 v[148:151], v224 offset:1024
	ds_read_b128 v[152:155], v224 offset:2048
	ds_read_b128 v[156:159], v224 offset:3072
	s_mov_b32 m0, s18
	v_lshl_add_u64 v[242:243], v[240:241], 0, s[42:43]
	ds_read_b128 v[160:163], v222 offset:32768
	ds_read_b128 v[164:167], v222 offset:33792
	ds_read_b128 v[168:171], v222 offset:34816
	ds_read_b128 v[172:175], v222 offset:35840
	ds_read_b128 v[176:179], v222 offset:36864
	ds_read_b128 v[180:183], v222 offset:37888
	ds_read_b128 v[230:233], v222 offset:38912
	ds_read_b128 v[234:237], v222 offset:39936
	global_load_lds_dwordx4 v[242:243], off
	v_lshl_add_u64 v[242:243], v[240:241], 0, s[44:45]
	s_mov_b32 m0, s19
	s_nop 0
	global_load_lds_dwordx4 v[242:243], off
	s_waitcnt vmcnt(8)
	s_waitcnt lgkmcnt(0)
	s_barrier
	s_setprio 1
	s_waitcnt lgkmcnt(0)
	v_mfma_f32_16x16x32_bf16 v[124:127], v[128:131], v[160:163], v[124:127]
	v_mfma_f32_16x16x32_bf16 v[120:123], v[136:139], v[160:163], v[120:123]
	v_mfma_f32_16x16x32_bf16 v[108:111], v[128:131], v[168:171], v[108:111]
	v_mfma_f32_16x16x32_bf16 v[104:107], v[136:139], v[168:171], v[104:107]
	v_mfma_f32_16x16x32_bf16 v[92:95], v[128:131], v[176:179], v[92:95]
	v_mfma_f32_16x16x32_bf16 v[88:91], v[136:139], v[176:179], v[88:91]
	v_mfma_f32_16x16x32_bf16 v[76:79], v[128:131], v[230:233], v[76:79]
	v_mfma_f32_16x16x32_bf16 v[72:75], v[136:139], v[230:233], v[72:75]
	v_mfma_f32_16x16x32_bf16 v[124:127], v[132:135], v[164:167], v[124:127]
	v_mfma_f32_16x16x32_bf16 v[120:123], v[140:143], v[164:167], v[120:123]
	v_mfma_f32_16x16x32_bf16 v[108:111], v[132:135], v[172:175], v[108:111]
	v_mfma_f32_16x16x32_bf16 v[104:107], v[140:143], v[172:175], v[104:107]
	v_mfma_f32_16x16x32_bf16 v[92:95], v[132:135], v[180:183], v[92:95]
	v_mfma_f32_16x16x32_bf16 v[88:91], v[140:143], v[180:183], v[88:91]
	v_mfma_f32_16x16x32_bf16 v[76:79], v[132:135], v[234:237], v[76:79]
	v_mfma_f32_16x16x32_bf16 v[72:75], v[140:143], v[234:237], v[72:75]
	s_setprio 0
	s_setprio 1
	v_mfma_f32_16x16x32_bf16 v[116:119], v[144:147], v[160:163], v[116:119]
	v_mfma_f32_16x16x32_bf16 v[112:115], v[152:155], v[160:163], v[112:115]
	v_mfma_f32_16x16x32_bf16 v[100:103], v[144:147], v[168:171], v[100:103]
	v_mfma_f32_16x16x32_bf16 v[96:99], v[152:155], v[168:171], v[96:99]
	v_mfma_f32_16x16x32_bf16 v[84:87], v[144:147], v[176:179], v[84:87]
	v_mfma_f32_16x16x32_bf16 v[80:83], v[152:155], v[176:179], v[80:83]
	v_mfma_f32_16x16x32_bf16 v[68:71], v[144:147], v[230:233], v[68:71]
	v_mfma_f32_16x16x32_bf16 v[64:67], v[152:155], v[230:233], v[64:67]
	v_mfma_f32_16x16x32_bf16 v[116:119], v[148:151], v[164:167], v[116:119]
	v_mfma_f32_16x16x32_bf16 v[112:115], v[156:159], v[164:167], v[112:115]
	v_mfma_f32_16x16x32_bf16 v[100:103], v[148:151], v[172:175], v[100:103]
	v_mfma_f32_16x16x32_bf16 v[96:99], v[156:159], v[172:175], v[96:99]
	v_mfma_f32_16x16x32_bf16 v[84:87], v[148:151], v[180:183], v[84:87]
	v_mfma_f32_16x16x32_bf16 v[80:83], v[156:159], v[180:183], v[80:83]
	v_mfma_f32_16x16x32_bf16 v[68:71], v[148:151], v[234:237], v[68:71]
	v_mfma_f32_16x16x32_bf16 v[64:67], v[156:159], v[234:237], v[64:67]
	s_setprio 0
	s_barrier
; #define PG8_STAGE(bufoff, gbase, voff) do { _Pragma("unroll") for (int _i = 0; _i < 2; ++_i) \
;         __builtin_amdgcn_global_load_lds((const unsigned*)((const char*)(gbase) + (voff)[_i]), (PG8_LAS unsigned*)(lds + (bufoff) + ldsw + _i * 8192), 16, 0, 0); } while (0)
; #define PG8_LDA(dst, b, h) do { _Pragma("unroll") for (int m = 0; m < 4; ++m) _Pragma("unroll") for (int k = 0; k < 2; ++k) dst[m][k] = *(const PG8_LAS bf16x8*)(lds + PG8_SA(b, h) + aoff + m * 2048 + k * 1024); } while (0)
; #define PG8_MMA(ai, bj, At, Bt) do { __builtin_amdgcn_s_setprio(1); _Pragma("unroll") for (int m = 0; m < 4; ++m) _Pragma("unroll") for (int n = 0; n < 2; ++n) _Pragma("unroll") for (int k = 0; k < 2; ++k) \
;         acc[ai][bj][m][n] = __builtin_amdgcn_mfma_f32_16x16x32_bf16(Bt[n][k], At[m][k], acc[ai][bj][m][n], 0, 0, 0); __builtin_amdgcn_s_setprio(0); } while (0)
; #define PG8_WAIT_V(n) asm volatile("s_waitcnt vmcnt(" #n ")" ::: "memory")
; #define PG8_WAIT_L(n) asm volatile("s_waitcnt lgkmcnt(" #n ")" ::: "memory")
; #define PG8_BAR __builtin_amdgcn_s_barrier()
; #define PG8_SCHED __builtin_amdgcn_sched_barrier(0)
; template <class Epi, class Sched, bool ALIGN_EPI = false, bool SP2 = false>
; __device__ __forceinline__ void gemm_phase(PG8_LAS unsigned char* lds, const Gemm g, const Sched& S, const Epi& E) {
;     ...
;         for (int t = 0; t < nt; t += 2) {
;             const bool last = (t == nt - 2);
;             const char* a1 = cA + (size_t)(t + 1) * kstepA;
;             const char* a2 = last ? nA : cA + (size_t)(t + 2) * kstepA; const char* b2 = last ? nB : cB + (size_t)(t + 2) * kstep;
;             const char* a3 = a2 + kstepA; const char* b3 = b2 + kstep;
;     ...
;             PG8_LDA(At, 1, 1); PG8_STAGE(PG8_SB(1, 0), b3, voffB); PG8_STAGE(PG8_SB(1, 1), b3 + hstepB, voffB); PG8_STAGE(PG8_SA(1, 0), a3, voffA);
;             PG8_WAIT_V(8); PG8_WAIT_L(0); PG8_BAR; PG8_MMA(1, 0, At, B0); PG8_MMA(1, 1, At, B1); PG8_BAR; PG8_SCHED;
	s_add_i32 s33, s88, s14
	v_lshl_add_u64 v[242:243], v[238:239], 0, s[46:47]
	s_mov_b32 m0, s33
	ds_read_b128 v[160:163], v222 offset:49152
	ds_read_b128 v[164:167], v222 offset:50176
	ds_read_b128 v[168:171], v222 offset:51200
	ds_read_b128 v[172:175], v222 offset:52224
	ds_read_b128 v[176:179], v222 offset:53248
	ds_read_b128 v[180:183], v222 offset:54272
	ds_read_b128 v[230:233], v222 offset:55296
	ds_read_b128 v[234:237], v222 offset:56320
	global_load_lds_dwordx4 v[242:243], off
	v_lshl_add_u64 v[242:243], v[238:239], 0, s[48:49]
	s_add_i32 m0, s33, 0x2000
	s_add_i32 s33, s89, s14
	global_load_lds_dwordx4 v[242:243], off
	v_lshl_add_u64 v[242:243], v[238:239], 0, s[52:53]
	s_mov_b32 m0, s33
	v_lshl_add_u64 v[238:239], v[238:239], 0, s[54:55]
	global_load_lds_dwordx4 v[242:243], off
	s_add_i32 m0, s33, 0x2000
	s_nop 0
	global_load_lds_dwordx4 v[238:239], off
	v_lshl_add_u64 v[238:239], v[240:241], 0, s[46:47]
	s_mov_b32 m0, s80
	s_nop 0
	global_load_lds_dwordx4 v[238:239], off
	v_lshl_add_u64 v[238:239], v[240:241], 0, s[48:49]
	s_mov_b32 m0, s81
	s_nop 0
	global_load_lds_dwordx4 v[238:239], off
	s_waitcnt vmcnt(8)
	s_waitcnt lgkmcnt(0)
	s_barrier
	s_setprio 1
	s_waitcnt lgkmcnt(0)
	v_mfma_f32_16x16x32_bf16 v[60:63], v[128:131], v[160:163], v[60:63]
	v_mfma_f32_16x16x32_bf16 v[56:59], v[136:139], v[160:163], v[56:59]
	v_mfma_f32_16x16x32_bf16 v[44:47], v[128:131], v[168:171], v[44:47]
	v_mfma_f32_16x16x32_bf16 v[40:43], v[136:139], v[168:171], v[40:43]
	v_mfma_f32_16x16x32_bf16 v[28:31], v[128:131], v[176:179], v[28:31]
	v_mfma_f32_16x16x32_bf16 v[24:27], v[136:139], v[176:179], v[24:27]
	v_mfma_f32_16x16x32_bf16 v[12:15], v[128:131], v[230:233], v[12:15]
	v_mfma_f32_16x16x32_bf16 v[8:11], v[136:139], v[230:233], v[8:11]
	v_mfma_f32_16x16x32_bf16 v[60:63], v[132:135], v[164:167], v[60:63]
	v_mfma_f32_16x16x32_bf16 v[56:59], v[140:143], v[164:167], v[56:59]
	v_mfma_f32_16x16x32_bf16 v[44:47], v[132:135], v[172:175], v[44:47]
	v_mfma_f32_16x16x32_bf16 v[40:43], v[140:143], v[172:175], v[40:43]
	v_mfma_f32_16x16x32_bf16 v[28:31], v[132:135], v[180:183], v[28:31]
	v_mfma_f32_16x16x32_bf16 v[24:27], v[140:143], v[180:183], v[24:27]
	v_mfma_f32_16x16x32_bf16 v[12:15], v[132:135], v[234:237], v[12:15]
	v_mfma_f32_16x16x32_bf16 v[8:11], v[140:143], v[234:237], v[8:11]
	s_setprio 0
	s_setprio 1
	v_mfma_f32_16x16x32_bf16 v[52:55], v[144:147], v[160:163], v[52:55]
	v_mfma_f32_16x16x32_bf16 v[48:51], v[152:155], v[160:163], v[48:51]
	v_mfma_f32_16x16x32_bf16 v[36:39], v[144:147], v[168:171], v[36:39]
	v_mfma_f32_16x16x32_bf16 v[32:35], v[152:155], v[168:171], v[32:35]
	v_mfma_f32_16x16x32_bf16 v[20:23], v[144:147], v[176:179], v[20:23]
	v_mfma_f32_16x16x32_bf16 v[16:19], v[152:155], v[176:179], v[16:19]
	v_mfma_f32_16x16x32_bf16 v[4:7], v[144:147], v[230:233], v[4:7]
	v_mfma_f32_16x16x32_bf16 v[0:3], v[152:155], v[230:233], v[0:3]
	v_mfma_f32_16x16x32_bf16 v[52:55], v[148:151], v[164:167], v[52:55]
	v_mfma_f32_16x16x32_bf16 v[48:51], v[156:159], v[164:167], v[48:51]
	v_mfma_f32_16x16x32_bf16 v[36:39], v[148:151], v[172:175], v[36:39]
	v_mfma_f32_16x16x32_bf16 v[32:35], v[156:159], v[172:175], v[32:35]
	v_mfma_f32_16x16x32_bf16 v[20:23], v[148:151], v[180:183], v[20:23]
	v_mfma_f32_16x16x32_bf16 v[16:19], v[156:159], v[180:183], v[16:19]
	v_mfma_f32_16x16x32_bf16 v[4:7], v[148:151], v[234:237], v[4:7]
	v_mfma_f32_16x16x32_bf16 v[0:3], v[156:159], v[234:237], v[0:3]
	s_setprio 0
	s_barrier
	s_add_i32 s73, s73, 2
	s_add_u32 s70, s70, 0x10000
	s_addc_u32 s71, s71, 0
	s_add_u32 s69, s69, 0x10000
	s_addc_u32 s72, s72, 0
	s_cmp_gt_u32 s73, 41
